# packed f32 VALU ops (v_pk_fma/mul/add_f32) in GLA-sample, SWA-sample and GLA recurrence split into two scalar f32 ops each (bit-identical)
# speedup vs baseline: 1.0079x; 1.0079x over previous
; __device__ __forceinline__ float bf2f(unsigned h) { return __uint_as_float(h << 16); }
; __device__ __forceinline__ void gla_sample_unit(const Args& a, unsigned char* lds, int unit, int tid) {
;     ...
;     if (tid < 256) { const int kcol = tid; float la[4];
; #pragma unroll
;         for (int t = 0; t < 4; ++t) la[t] = a.b_a[h * 256 + kcol];
; #pragma unroll
;         for (int r = 0; r < 16; ++r) { const float w = a.w_a2[r * 1024 + h * 256 + kcol];
; #pragma unroll
;             for (int t = 0; t < 4; ++t) la[t] += bf2f(Z[(row0 + t) * DINP + ZAG + r]) * w; }
.LBB0_386:
	s_andn2_saveexec_b64 s[22:23], s[0:1]
	s_cbranch_execz .LBB0_388
	s_mul_i32 s0, s21, 0x5e00
	s_mul_hi_u32 s1, s20, 0x5e00
	v_readlane_b32 s48, v249, 5
	s_add_i32 s1, s1, s0
	s_mul_i32 s0, s20, 0x5e00
	v_lshl_or_b32 v0, s72, 10, v133
	v_mov_b32_e32 v1, v97
	v_readlane_b32 s49, v249, 6
	s_add_u32 s26, s74, s0
	s_addc_u32 s27, s75, s1
	v_lshl_add_u64 v[16:17], s[78:79], 0, v[0:1]
	s_mul_i32 s1, s24, 0x5e00
	s_mul_hi_i32 s0, s24, 0x5e00
	global_load_dword v18, v0, s[48:49]
	global_load_dword v22, v0, s[78:79]
	s_nop 0
	global_load_dwordx4 v[0:3], v213, s[26:27] offset:3072
	s_add_u32 s24, s74, s1
	s_addc_u32 s25, s75, s0
	s_movk_i32 s0, 0x4000
	s_lshl_b32 s14, s72, 9
	v_readlane_b32 s50, v249, 7
	v_readlane_b32 s51, v249, 8
	v_readlane_b32 s52, v249, 9
	v_readlane_b32 s53, v249, 10
	v_readlane_b32 s54, v249, 11
	v_readlane_b32 s55, v249, 12
	v_readlane_b32 s56, v249, 13
	v_readlane_b32 s57, v249, 14
	v_readlane_b32 s58, v249, 15
	v_readlane_b32 s59, v249, 16
	v_readlane_b32 s60, v249, 17
	v_readlane_b32 s61, v249, 18
	v_readlane_b32 s62, v249, 19
	v_readlane_b32 s63, v249, 20
	s_waitcnt vmcnt(0)
	v_lshlrev_b32_e32 v4, 16, v0
	v_fma_f32 v19, v22, v4, v18
	global_load_dwordx4 v[4:7], v214, s[24:25] offset:2560
	v_and_b32_e32 v0, 0xffff0000, v0
	s_waitcnt vmcnt(0)
	v_lshlrev_b32_e32 v8, 16, v4
	v_fma_f32 v20, v22, v8, v18
	global_load_dwordx4 v[8:11], v215, s[24:25] offset:2048
	s_waitcnt vmcnt(0)
	v_lshlrev_b32_e32 v12, 16, v8
	v_fma_f32 v21, v22, v12, v18
	global_load_dwordx4 v[12:15], v216, s[24:25] offset:1536
	s_waitcnt vmcnt(0)
	v_lshlrev_b32_e32 v23, 16, v12
	v_fmac_f32_e32 v18, v22, v23
	v_add_co_u32_e32 v22, vcc, s19, v16
	s_nop 1
	v_addc_co_u32_e32 v23, vcc, 0, v17, vcc
	global_load_dword v24, v[22:23], off offset:-4096
	s_waitcnt vmcnt(0)
	v_fmac_f32_e32 v19, v24, v0
	v_and_b32_e32 v0, 0xffff0000, v4
	v_fmac_f32_e32 v20, v24, v0
	v_and_b32_e32 v0, 0xffff0000, v8
	v_fmac_f32_e32 v21, v24, v0
	v_and_b32_e32 v0, 0xffff0000, v12
	v_fmac_f32_e32 v18, v24, v0
	global_load_dword v0, v[22:23], off
	v_lshlrev_b32_e32 v4, 16, v1
	v_add_co_u32_e32 v22, vcc, s0, v16
	v_and_b32_e32 v1, 0xffff0000, v1
	s_nop 0
	v_addc_co_u32_e32 v23, vcc, 0, v17, vcc
	s_movk_i32 s0, 0x6000
	s_waitcnt vmcnt(0)
	v_fmac_f32_e32 v19, v0, v4
	v_lshlrev_b32_e32 v4, 16, v5
	v_fmac_f32_e32 v20, v0, v4
	v_lshlrev_b32_e32 v4, 16, v9
	v_fmac_f32_e32 v21, v0, v4
	v_lshlrev_b32_e32 v4, 16, v13
	v_fmac_f32_e32 v18, v0, v4
	global_load_dword v0, v[22:23], off offset:-4096
	s_waitcnt vmcnt(0)
	v_fmac_f32_e32 v19, v0, v1
	v_and_b32_e32 v1, 0xffff0000, v5
	v_fmac_f32_e32 v20, v0, v1
	v_and_b32_e32 v1, 0xffff0000, v9
	v_fmac_f32_e32 v21, v0, v1
	v_and_b32_e32 v1, 0xffff0000, v13
	v_fmac_f32_e32 v18, v0, v1
	global_load_dword v0, v[22:23], off
	v_lshlrev_b32_e32 v1, 16, v2
	v_and_b32_e32 v2, 0xffff0000, v2
	s_waitcnt vmcnt(0)
	v_fmac_f32_e32 v19, v0, v1
	v_lshlrev_b32_e32 v1, 16, v6
	v_fmac_f32_e32 v20, v0, v1
	v_lshlrev_b32_e32 v1, 16, v10
	v_fmac_f32_e32 v21, v0, v1
	v_lshlrev_b32_e32 v1, 16, v14
	v_fmac_f32_e32 v18, v0, v1
	v_add_co_u32_e32 v0, vcc, s0, v16
	s_mov_b32 s0, 0x8000
	s_nop 0
	v_addc_co_u32_e32 v1, vcc, 0, v17, vcc
	global_load_dword v4, v[0:1], off offset:-4096
	s_waitcnt vmcnt(0)
	v_fmac_f32_e32 v19, v4, v2
	global_load_dword v0, v[0:1], off
	v_and_b32_e32 v2, 0xffff0000, v6
	v_lshlrev_b32_e32 v1, 16, v3
	v_fmac_f32_e32 v20, v4, v2
	v_and_b32_e32 v2, 0xffff0000, v10
	v_fmac_f32_e32 v21, v4, v2
	v_and_b32_e32 v2, 0xffff0000, v14
	v_fmac_f32_e32 v18, v4, v2
	v_and_b32_e32 v3, 0xffff0000, v3
	s_waitcnt vmcnt(0)
	v_fmac_f32_e32 v19, v0, v1
	v_lshlrev_b32_e32 v1, 16, v7
	v_fmac_f32_e32 v20, v0, v1
	v_lshlrev_b32_e32 v1, 16, v11
	v_fmac_f32_e32 v21, v0, v1
	v_lshlrev_b32_e32 v1, 16, v15
	v_fmac_f32_e32 v18, v0, v1
	v_add_co_u32_e32 v0, vcc, s0, v16
	s_mov_b32 s0, 0xa000
	s_nop 0
	v_addc_co_u32_e32 v1, vcc, 0, v17, vcc
	global_load_dword v2, v[0:1], off offset:-4096
	s_waitcnt vmcnt(0)
	v_fmac_f32_e32 v19, v2, v3
	v_and_b32_e32 v3, 0xffff0000, v7
	v_fmac_f32_e32 v20, v2, v3
	v_and_b32_e32 v3, 0xffff0000, v11
	v_fmac_f32_e32 v21, v2, v3
	v_and_b32_e32 v3, 0xffff0000, v15
	global_load_dword v22, v[0:1], off
	global_load_dwordx4 v[12:15], v213, s[26:27] offset:3088
	global_load_dwordx4 v[8:11], v214, s[24:25] offset:2576
	global_load_dwordx4 v[4:7], v215, s[24:25] offset:2064
	v_fmac_f32_e32 v18, v2, v3
	s_waitcnt vmcnt(2)
	v_lshlrev_b32_e32 v0, 16, v12
	v_fmac_f32_e32 v19, v22, v0
	s_waitcnt vmcnt(1)
	v_lshlrev_b32_e32 v0, 16, v8
	v_fmac_f32_e32 v20, v22, v0
	s_waitcnt vmcnt(0)
	v_lshlrev_b32_e32 v0, 16, v4
	v_fmac_f32_e32 v21, v22, v0
	global_load_dwordx4 v[0:3], v216, s[24:25] offset:1552
	v_and_b32_e32 v12, 0xffff0000, v12
	v_and_b32_e32 v8, 0xffff0000, v8
	v_and_b32_e32 v4, 0xffff0000, v4
	v_bfi_b32 v27, v217, 0, v13
	v_lshlrev_b32_e32 v26, 16, v13
	s_waitcnt vmcnt(0)
	v_lshlrev_b32_e32 v23, 16, v0
	v_fmac_f32_e32 v18, v22, v23
	v_add_co_u32_e32 v22, vcc, s0, v16
	v_and_b32_e32 v0, 0xffff0000, v0
	s_nop 0
	v_addc_co_u32_e32 v23, vcc, 0, v17, vcc
	global_load_dword v24, v[22:23], off offset:-4096
	s_mov_b32 s0, 0xc000
	global_load_dword v22, v[22:23], off
	s_waitcnt vmcnt(1)
	v_fmac_f32_e32 v19, v24, v12
	v_fmac_f32_e32 v20, v24, v8
	v_fmac_f32_e32 v21, v24, v4
	v_fmac_f32_e32 v18, v24, v0
	v_add_co_u32_e32 v24, vcc, s0, v16
	s_mov_b32 s0, 0xe000
	s_nop 0
	v_addc_co_u32_e32 v25, vcc, 0, v17, vcc
	global_load_dword v23, v[24:25], off offset:-4096
	s_waitcnt vmcnt(0)
; __device__ __forceinline__ float bf2f(unsigned h) { return __uint_as_float(h << 16); }
; __device__ __forceinline__ float logsig16(float g) { return (fminf(g, 0.f) - __logf(1.f + __expf(-fabsf(g)))) * 0.0625f; }
; __device__ __forceinline__ void gla_sample_unit(const Args& a, unsigned char* lds, int unit, int tid) {
;     ...
;         for (int r = 0; r < 16; ++r) { const float w = a.w_a2[r * 1024 + h * 256 + kcol];
; #pragma unroll
;             for (int t = 0; t < 4; ++t) la[t] += bf2f(Z[(row0 + t) * DINP + ZAG + r]) * w; }
;         float bb[4]; float c = 0.f;
; #pragma unroll
;         for (int t = 0; t < 4; ++t) { c += logsig16(la[t]); bb[t] = c; }
;         f32x4 qv, kd, ki;
; #pragma unroll
;         for (int t = 0; t < 4; ++t) { const float q = bf2f(Z[(row0 + t) * DINP + ZQG + h * 256 + kcol]), k = bf2f(Z[(row0 + t) * DINP + ZKG + h * 256 + kcol]);
;             qv[t] = q * __expf(bb[t]) * 0.0625f; ki[t] = k * __expf(-bb[t]); kd[t] = k * __expf(c - bb[t]); }
	v_mul_f32_e32 v12, v22, v26
	v_mul_f32_e32 v13, v23, v27
	s_nop 0
	v_add_f32_e32 v0, v19, v12
	v_add_f32_e32 v19, v0, v13
	v_bfi_b32 v13, v217, 0, v9
	v_lshlrev_b32_e32 v12, 16, v9
	v_mul_f32_e32 v8, v22, v12
	v_mul_f32_e32 v9, v23, v13
	s_nop 0
	v_add_f32_e32 v0, v20, v8
	v_add_f32_e32 v12, v0, v9
	v_bfi_b32 v9, v217, 0, v5
	v_lshlrev_b32_e32 v8, 16, v5
	v_mul_f32_e32 v4, v22, v8
	v_mul_f32_e32 v5, v23, v9
	v_bfi_b32 v9, v217, 0, v14
	v_add_f32_e32 v0, v21, v4
	v_add_f32_e32 v13, v0, v5
	v_bfi_b32 v5, v217, 0, v1
	v_lshlrev_b32_e32 v4, 16, v1
	v_mul_f32_e32 v0, v22, v4
	v_mul_f32_e32 v1, v23, v5
	global_load_dword v4, v[24:25], off
	v_add_f32_e32 v0, v18, v0
	v_add_f32_e32 v18, v0, v1
	v_add_co_u32_e32 v0, vcc, s0, v16
	v_lshlrev_b32_e32 v8, 16, v14
	s_nop 0
	v_addc_co_u32_e32 v1, vcc, 0, v17, vcc
	global_load_dword v5, v[0:1], off offset:-4096
	s_mov_b32 s0, 0xf000
	global_load_dword v0, v[0:1], off
	s_waitcnt vmcnt(1)
	v_mul_f32_e32 v8, v4, v8
	v_mul_f32_e32 v9, v5, v9
	s_nop 0
	v_add_f32_e32 v8, v19, v8
	v_add_f32_e32 v14, v8, v9
	v_bfi_b32 v9, v217, 0, v10
	v_lshlrev_b32_e32 v8, 16, v10
	v_mul_f32_e32 v8, v4, v8
	v_mul_f32_e32 v9, v5, v9
	s_nop 0
	v_add_f32_e32 v8, v12, v8
	v_add_f32_e32 v10, v8, v9
	v_bfi_b32 v9, v217, 0, v6
	v_lshlrev_b32_e32 v8, 16, v6
	v_mul_f32_e32 v8, v4, v8
	v_mul_f32_e32 v9, v5, v9
	s_nop 0
	v_add_f32_e32 v6, v13, v8
	v_add_f32_e32 v6, v6, v9
	v_bfi_b32 v9, v217, 0, v2
	v_lshlrev_b32_e32 v8, 16, v2
	v_mul_f32_e32 v4, v4, v8
	v_mul_f32_e32 v5, v5, v9
	s_nop 0
	v_add_f32_e32 v2, v18, v4
	v_add_co_u32_e32 v4, vcc, s0, v16
	v_add_f32_e32 v2, v2, v5
	s_nop 0
	v_addc_co_u32_e32 v5, vcc, 0, v17, vcc
	global_load_dword v1, v[4:5], off
	v_bfi_b32 v5, v217, 0, v15
	v_lshlrev_b32_e32 v4, 16, v15
	s_waitcnt vmcnt(0)
	v_mul_f32_e32 v4, v0, v4
	v_mul_f32_e32 v5, v1, v5
	s_nop 0
	v_add_f32_e32 v4, v14, v4
	v_add_f32_e32 v8, v4, v5
	v_bfi_b32 v5, v217, 0, v11
	v_lshlrev_b32_e32 v4, 16, v11
	v_mul_f32_e32 v4, v0, v4
	v_mul_f32_e32 v5, v1, v5
	s_nop 0
	v_add_f32_e32 v4, v10, v4
	v_add_f32_e32 v9, v4, v5
	v_bfi_b32 v5, v217, 0, v7
	v_lshlrev_b32_e32 v4, 16, v7
	v_mul_f32_e32 v4, v0, v4
	v_mul_f32_e32 v5, v1, v5
	s_nop 0
	v_add_f32_e32 v4, v6, v4
	v_add_f32_e32 v6, v4, v5
	v_bfi_b32 v5, v217, 0, v3
	v_lshlrev_b32_e32 v4, 16, v3
	v_mul_f32_e32 v0, v0, v4
	v_mul_f32_e32 v1, v1, v5
	s_nop 0
	v_add_f32_e32 v0, v2, v0
	v_mul_f32_e64 v2, |v8|, s28
	v_exp_f32_e32 v2, v2
	v_add_f32_e32 v0, v0, v1
	v_min_f32_e32 v1, 0, v8
	v_add_f32_e32 v2, 1.0, v2
	v_cmp_gt_f32_e32 vcc, s29, v2
	s_nop 1
	v_cndmask_b32_e64 v3, 0, 32, vcc
	v_ldexp_f32 v2, v2, v3
	v_log_f32_e32 v2, v2
	s_nop 0
	v_mul_f32_e32 v3, 0x3f317217, v2
	v_fma_f32 v3, v2, s30, -v3
	v_fmac_f32_e32 v3, 0x3377d1cf, v2
	v_fmac_f32_e32 v3, 0x3f317217, v2
	v_cmp_lt_f32_e64 s[0:1], |v2|, s31
	s_nop 1
	v_cndmask_b32_e64 v2, v2, v3, s[0:1]
	v_cndmask_b32_e32 v3, 0, v221, vcc
	v_sub_f32_e32 v2, v2, v3
	v_sub_f32_e32 v1, v1, v2
	v_mul_f32_e64 v2, |v9|, s28
	v_exp_f32_e32 v2, v2
	v_fma_f32 v5, v1, s18, 0
	v_min_f32_e32 v1, 0, v9
	v_mul_f32_e32 v4, 0x3fb8aa3b, v5
	v_add_f32_e32 v2, 1.0, v2
	v_cmp_gt_f32_e32 vcc, s29, v2
	v_exp_f32_e32 v8, v4
	v_mul_f32_e32 v4, 0xbfb8aa3b, v5
	v_cndmask_b32_e64 v3, 0, 32, vcc
	v_ldexp_f32 v2, v2, v3
	v_log_f32_e32 v2, v2
	v_exp_f32_e32 v4, v4
	v_mul_f32_e32 v3, 0x3f317217, v2
	v_fma_f32 v3, v2, s30, -v3
	v_fmac_f32_e32 v3, 0x3377d1cf, v2
	v_fmac_f32_e32 v3, 0x3f317217, v2
	v_cmp_lt_f32_e64 s[0:1], |v2|, s31
	s_nop 1
	v_cndmask_b32_e64 v2, v2, v3, s[0:1]
	v_cndmask_b32_e32 v3, 0, v221, vcc
	v_sub_f32_e32 v2, v2, v3
	v_sub_f32_e32 v1, v1, v2
	v_mul_f32_e64 v2, |v6|, s28
	v_exp_f32_e32 v2, v2
	v_fmamk_f32 v7, v1, 0x3d800000, v5
	v_min_f32_e32 v1, 0, v6
	v_add_f32_e32 v2, 1.0, v2
	v_cmp_gt_f32_e32 vcc, s29, v2
	s_nop 1
	v_cndmask_b32_e64 v3, 0, 32, vcc
	v_ldexp_f32 v2, v2, v3
	v_log_f32_e32 v2, v2
	s_nop 0
	v_mul_f32_e32 v3, 0x3f317217, v2
	v_fma_f32 v3, v2, s30, -v3
	v_fmac_f32_e32 v3, 0x3377d1cf, v2
	v_fmac_f32_e32 v3, 0x3f317217, v2
	v_cmp_lt_f32_e64 s[0:1], |v2|, s31
	s_nop 1
	v_cndmask_b32_e64 v2, v2, v3, s[0:1]
	v_cndmask_b32_e32 v3, 0, v221, vcc
	v_sub_f32_e32 v2, v2, v3
	v_sub_f32_e32 v1, v1, v2
	v_fmamk_f32 v13, v1, 0x3d800000, v7
	v_min_f32_e32 v1, 0, v0
	v_mul_f32_e64 v0, |v0|, s28
	v_exp_f32_e32 v0, v0
	s_nop 0
	v_add_f32_e32 v0, 1.0, v0
	v_cmp_gt_f32_e32 vcc, s29, v0
	s_nop 1
	v_cndmask_b32_e64 v2, 0, 32, vcc
	v_ldexp_f32 v0, v0, v2
	v_log_f32_e32 v0, v0
	s_nop 0
	v_mul_f32_e32 v2, 0x3f317217, v0
	v_fma_f32 v2, v0, s30, -v2
	v_fmac_f32_e32 v2, 0x3377d1cf, v0
	v_fmac_f32_e32 v2, 0x3f317217, v0
	v_cmp_lt_f32_e64 s[0:1], |v0|, s31
	s_nop 1
	v_cndmask_b32_e64 v0, v0, v2, s[0:1]
	v_cndmask_b32_e32 v2, 0, v221, vcc
	s_add_u32 s0, s26, s14
	v_sub_f32_e32 v0, v0, v2
	s_addc_u32 s1, s27, 0
	v_sub_f32_e32 v0, v1, v0
	s_add_u32 s24, s24, s14
	v_fmamk_f32 v15, v0, 0x3d800000, v13
	v_lshlrev_b32_e32 v0, 1, v188
	v_mov_b32_e32 v1, v97
	s_addc_u32 s25, s25, 0
	v_lshl_add_u64 v[16:17], s[24:25], 0, v[0:1]
	s_mov_b32 s14, 0x17806000
	v_add_co_u32_e32 v10, vcc, s14, v16
	v_lshl_add_u64 v[2:3], s[0:1], 0, v[0:1]
	s_nop 0
	v_addc_co_u32_e32 v11, vcc, 0, v17, vcc
	global_load_ushort v1, v[10:11], off offset:2560
	s_nop 0
	global_load_ushort v0, v0, s[0:1] offset:3072
	v_sub_f32_e32 v5, v15, v5
	v_mul_f32_e32 v5, 0x3fb8aa3b, v5
	v_exp_f32_e32 v6, v5
	v_mul_f32_e32 v5, 0x3fb8aa3b, v7
	v_exp_f32_e32 v9, v5
	s_movk_i32 s0, 0x1000
	v_add_co_u32_e32 v2, vcc, s0, v2
	s_mov_b32 s0, 0x17807000
	s_nop 0
	v_addc_co_u32_e32 v3, vcc, 0, v3, vcc
	v_mul_f32_e32 v5, 0xbfb8aa3b, v7
	v_sub_f32_e32 v7, v15, v7
	v_mul_f32_e32 v7, 0x3fb8aa3b, v7
	v_exp_f32_e32 v5, v5
	v_exp_f32_e32 v7, v7
	s_waitcnt vmcnt(1)
; __device__ __forceinline__ float bf2f(unsigned h) { return __uint_as_float(h << 16); }
; __device__ __forceinline__ void gla_sample_unit(const Args& a, unsigned char* lds, int unit, int tid) {
;     ...
;         for (int t = 0; t < 4; ++t) { const float q = bf2f(Z[(row0 + t) * DINP + ZQG + h * 256 + kcol]), k = bf2f(Z[(row0 + t) * DINP + ZKG + h * 256 + kcol]);
;             qv[t] = q * __expf(bb[t]) * 0.0625f; ki[t] = k * __expf(-bb[t]); kd[t] = k * __expf(c - bb[t]); }
;         *(f32x4*)(Q4 + kcol * 4) = qv; *(f32x4*)(KD4 + kcol * 4) = kd; *(f32x4*)(KI4 + kcol * 4) = ki; DECS[kcol] = __expf(c);
	v_lshlrev_b32_e32 v1, 16, v1
	s_waitcnt vmcnt(0)
	v_lshlrev_b32_e32 v0, 16, v0
	v_mul_f32_e32 v0, v8, v0
	v_mul_f32_e32 v1, v9, v1
	global_load_ushort v8, v[2:3], off offset:1024
	v_add_co_u32_e32 v2, vcc, s0, v16
	s_mov_b32 s0, 0x1780c000
	s_nop 0
	v_addc_co_u32_e32 v3, vcc, 0, v17, vcc
	global_load_ushort v2, v[2:3], off offset:512
	v_mul_f32_e32 v0, s18, v0
	v_mul_f32_e32 v1, s18, v1
	s_waitcnt vmcnt(1)
	v_lshlrev_b32_e32 v10, 16, v8
	s_waitcnt vmcnt(0)
	v_lshlrev_b32_e32 v11, 16, v2
	v_mul_f32_e32 v2, 0x3fb8aa3b, v13
	v_exp_f32_e32 v8, v2
	v_mul_f32_e32 v2, 0xbfb8aa3b, v13
	v_exp_f32_e32 v12, v2
	v_sub_f32_e32 v2, v15, v13
	v_mul_f32_e32 v2, 0x3fb8aa3b, v2
	v_exp_f32_e32 v14, v2
	v_mul_f32_e32 v2, 0x3fb8aa3b, v15
	v_exp_f32_e32 v9, v2
	v_add_co_u32_e32 v2, vcc, s0, v16
	s_mov_b32 s0, 0x17812000
	s_nop 0
	v_addc_co_u32_e32 v3, vcc, 0, v17, vcc
	v_add_co_u32_e32 v18, vcc, s0, v16
	global_load_ushort v2, v[2:3], off offset:2048
	s_nop 0
	v_addc_co_u32_e32 v19, vcc, 0, v17, vcc
	global_load_ushort v3, v[18:19], off offset:1536
	s_mov_b32 s0, 0x1780d000
	v_add_co_u32_e32 v16, vcc, s0, v16
	s_waitcnt vmcnt(1)
	v_lshlrev_b32_e32 v2, 16, v2
	v_addc_co_u32_e32 v17, vcc, 0, v17, vcc
	s_waitcnt vmcnt(0)
	v_lshlrev_b32_e32 v3, 16, v3
	v_mul_f32_e32 v2, v8, v2
	v_mul_f32_e32 v3, v9, v3
	v_mul_f32_e32 v8, 0xbfb8aa3b, v15
	v_exp_f32_e32 v13, v8
	v_sub_f32_e32 v8, v15, v15
	v_mul_f32_e32 v8, 0x3fb8aa3b, v8
	v_exp_f32_e32 v15, v8
	global_load_ushort v8, v[16:17], off
	s_nop 0
	global_load_ushort v16, v[18:19], off offset:3584
	v_mul_f32_e32 v2, s18, v2
	v_mul_f32_e32 v3, s18, v3
	s_waitcnt vmcnt(1)
	v_lshlrev_b32_e32 v20, 16, v8
	s_waitcnt vmcnt(0)
	v_lshlrev_b32_e32 v21, 16, v16
	v_mul_f32_e32 v16, v4, v10
	v_mul_f32_e32 v17, v5, v11
	v_mul_f32_e32 v18, v12, v20
	v_mul_f32_e32 v19, v13, v21
	v_mul_f32_e32 v4, v6, v10
	v_mul_f32_e32 v5, v7, v11
	v_mul_f32_e32 v6, v14, v20
	v_mul_f32_e32 v7, v15, v21
	ds_write_b128 v135, v[0:3]
	ds_write_b128 v135, v[4:7] offset:4096
	ds_write_b128 v135, v[16:19] offset:8192
	ds_write_b32 v218, v9 offset:12288

; __device__ __forceinline__ void gla_sample_unit(const Args& a, unsigned char* lds, int unit, int tid) {
;     ...
;     f32x4 vr[4], o[4];
; #pragma unroll
;     for (int t = 0; t < 4; ++t) { vr[t] = *(const f32x4*)(VS + t * 512 + vc); o[t] = (f32x4){0.f, 0.f, 0.f, 0.f}; }
;     const float* S0 = a.s0 + (size_t)unit * 256 * 512; float* SN = a.out + OUT_SS + (size_t)unit * 256 * 512;
;     f32x4 sb[2][8];
; #pragma unroll
;     for (int i = 0; i < 8; ++i) sb[0][i] = *(const f32x4*)(S0 + (size_t)(i * 4 + kq) * 512 + vc);
; #pragma unroll
;     for (int g = 0; g < 8; ++g) {
;         if (g + 1 < 8) {
; #pragma unroll
;             for (int i = 0; i < 8; ++i) sb[(g + 1) & 1][i] = *(const f32x4*)(S0 + (size_t)(((g + 1) * 8 + i) * 4 + kq) * 512 + vc); }
; #pragma unroll
;         for (int i = 0; i < 8; ++i) { const int k = (g * 8 + i) * 4 + kq; const f32x4 s = sb[g & 1][i];
;             const f32x4 qv = *(const f32x4*)(Q4 + k * 4), kd = *(const f32x4*)(KD4 + k * 4); const float dec = DECS[k];
;             f32x4 sn = s * dec;
; #pragma unroll
;             for (int t = 0; t < 4; ++t) { sn += vr[t] * kd[t]; o[t] += s * qv[t]; }
;             *(f32x4*)(SN + (size_t)k * 512 + vc) = sn; } }
.LBB0_390:
	s_or_b64 exec, exec, s[0:1]
	v_lshl_add_u64 v[110:111], v[102:103], 0, v[100:101]
	v_add_co_u32_e32 v16, vcc, 0x2000, v110
	ds_read_b128 v[12:15], v140 offset:13440
	ds_read_b128 v[8:11], v140 offset:15488
	ds_read_b128 v[4:7], v140 offset:17536
	s_waitcnt lgkmcnt(3)
	ds_read_b128 v[0:3], v140 offset:19584
	v_addc_co_u32_e32 v17, vcc, 0, v111, vcc
	global_load_dwordx4 v[76:79], v[110:111], off nt
	global_load_dwordx4 v[64:67], v[16:17], off nt
	v_add_co_u32_e32 v16, vcc, 0x4000, v110
	v_add_u32_e32 v107, 0x3000, v141
	s_nop 0
	v_addc_co_u32_e32 v17, vcc, 0, v111, vcc
	v_add_co_u32_e32 v18, vcc, 0x6000, v110
	s_mov_b32 s0, 0xb600000
	s_nop 0
	v_addc_co_u32_e32 v19, vcc, 0, v111, vcc
	global_load_dwordx4 v[56:59], v[16:17], off nt
	global_load_dwordx4 v[48:51], v[18:19], off nt
	v_add_co_u32_e32 v16, vcc, 0x8000, v110
	s_nop 1
	v_addc_co_u32_e32 v17, vcc, 0, v111, vcc
	v_add_co_u32_e32 v18, vcc, 0xa000, v110
	s_nop 1
	v_addc_co_u32_e32 v19, vcc, 0, v111, vcc
	global_load_dwordx4 v[40:43], v[16:17], off nt
	global_load_dwordx4 v[32:35], v[18:19], off nt
	v_add_co_u32_e32 v16, vcc, 0xc000, v110
	s_nop 1
	v_addc_co_u32_e32 v17, vcc, 0, v111, vcc
	v_add_co_u32_e32 v18, vcc, 0xe000, v110
	s_nop 1
	v_addc_co_u32_e32 v19, vcc, 0, v111, vcc
	global_load_dwordx4 v[24:27], v[16:17], off nt
	s_nop 0
	global_load_dwordx4 v[16:19], v[18:19], off nt
	v_add_co_u32_e32 v20, vcc, 0x10000, v110
	s_nop 1
	v_addc_co_u32_e32 v21, vcc, 0, v111, vcc
	v_add_co_u32_e32 v22, vcc, 0x12000, v110
	s_nop 1
	v_addc_co_u32_e32 v23, vcc, 0, v111, vcc
	global_load_dwordx4 v[72:75], v[20:21], off nt
	global_load_dwordx4 v[68:71], v[22:23], off nt
	v_add_co_u32_e32 v20, vcc, 0x14000, v110
	s_nop 1
	v_addc_co_u32_e32 v21, vcc, 0, v111, vcc
	v_add_co_u32_e32 v22, vcc, 0x16000, v110
	s_nop 1
	v_addc_co_u32_e32 v23, vcc, 0, v111, vcc
	global_load_dwordx4 v[60:63], v[20:21], off nt
	global_load_dwordx4 v[52:55], v[22:23], off nt
	v_add_co_u32_e32 v20, vcc, 0x18000, v110
	s_nop 1
	v_addc_co_u32_e32 v21, vcc, 0, v111, vcc
	v_add_co_u32_e32 v22, vcc, 0x1a000, v110
	s_nop 1
	v_addc_co_u32_e32 v23, vcc, 0, v111, vcc
	global_load_dwordx4 v[44:47], v[20:21], off nt
	global_load_dwordx4 v[36:39], v[22:23], off nt
	ds_read2_b32 v[116:117], v107 offset1:4
	ds_read_b128 v[80:83], v138
	ds_read_b128 v[112:115], v138 offset:4096
	v_add_co_u32_e32 v20, vcc, 0x1c000, v110
	s_waitcnt vmcnt(13) lgkmcnt(2)
	v_mul_f32_e32 v108, v76, v116
	v_mul_f32_e32 v109, v77, v116
	v_mul_f32_e32 v118, v78, v116
	v_mul_f32_e32 v119, v79, v116
	s_waitcnt lgkmcnt(0)
	v_fmac_f32_e32 v108, v12, v112
	v_fmac_f32_e32 v109, v13, v112
	v_fmac_f32_e32 v118, v14, v112
	v_fmac_f32_e32 v119, v15, v112
	v_addc_co_u32_e32 v21, vcc, 0, v111, vcc
	v_fmac_f32_e32 v108, v8, v113
	v_fmac_f32_e32 v109, v9, v113
	v_fma_f32 v112, v10, v113, v118
	v_fma_f32 v113, v11, v113, v119
	v_add_co_u32_e32 v22, vcc, 0x1e000, v110
	v_fma_f32 v120, v78, v80, 0
	v_fma_f32 v121, v79, v80, 0
	v_fma_f32 v122, v76, v80, 0
	v_fma_f32 v123, v77, v80, 0
	v_fma_f32 v118, v78, v81, 0
	v_fma_f32 v119, v79, v81, 0
	v_fma_f32 v222, v76, v81, 0
	v_fma_f32 v223, v77, v81, 0
	v_fma_f32 v80, v6, v114, v112
	v_fma_f32 v81, v7, v114, v113
	v_fmac_f32_e32 v108, v4, v114
	v_fmac_f32_e32 v109, v5, v114
	v_fma_f32 v224, v78, v82, 0
	v_fma_f32 v225, v79, v82, 0
	v_fma_f32 v226, v76, v82, 0
	v_fma_f32 v227, v77, v82, 0
	v_mov_b32_e32 v82, v115
	v_addc_co_u32_e32 v23, vcc, 0, v111, vcc
	v_fma_f32 v112, v0, v82, v108
	v_fma_f32 v113, v1, v82, v109
	v_fma_f32 v114, v2, v82, v80
	v_fma_f32 v115, v3, v82, v81
	v_mov_b32_e32 v80, v83
	v_lshl_add_u64 v[108:109], v[104:105], 0, v[100:101]
	v_fma_f32 v228, v78, v80, 0
	v_fma_f32 v229, v79, v80, 0
	v_add_co_u32_e32 v78, vcc, s0, v108
	global_load_dwordx4 v[28:31], v[20:21], off nt
	s_nop 0
	global_load_dwordx4 v[20:23], v[22:23], off nt
	v_addc_co_u32_e32 v79, vcc, 0, v109, vcc
	global_store_dwordx4 v[78:79], v[112:115], off nt
	v_fma_f32 v76, v76, v80, 0
	v_fma_f32 v77, v77, v80, 0
	ds_read_b128 v[80:83], v142
	ds_read_b128 v[112:115], v142 offset:4096
	ds_read2_b32 v[230:231], v107 offset0:8 offset1:12
	ds_read2_b32 v[78:79], v107 offset0:16 offset1:20
	v_mov_b32_e32 v116, v117
	s_waitcnt vmcnt(15)
	v_mul_f32_e32 v232, v66, v116
	v_mul_f32_e32 v233, v67, v116
	v_mul_f32_e32 v117, v65, v116
	v_mul_f32_e32 v116, v64, v116
	s_waitcnt lgkmcnt(2)
	v_fmac_f32_e32 v232, v14, v112
	v_fmac_f32_e32 v233, v15, v112
	v_fmac_f32_e32 v116, v12, v112
	v_fmac_f32_e32 v117, v13, v112
	v_fmac_f32_e32 v232, v10, v113
	v_fmac_f32_e32 v233, v11, v113
	v_fmac_f32_e32 v120, v66, v80
	v_fmac_f32_e32 v121, v67, v80
	v_fmac_f32_e32 v122, v64, v80
	v_fmac_f32_e32 v123, v65, v80
	v_fma_f32 v112, v8, v113, v116
	v_fma_f32 v113, v9, v113, v117
	v_fma_f32 v116, v66, v81, v118
	v_fma_f32 v117, v67, v81, v119
	v_fma_f32 v118, v64, v81, v222
	v_fma_f32 v119, v65, v81, v223
	v_fma_f32 v80, v6, v114, v232
	v_fma_f32 v81, v7, v114, v233
	v_fma_f32 v222, v64, v82, v226
	v_fma_f32 v223, v65, v82, v227
	v_fmac_f32_e32 v224, v66, v82
	v_fmac_f32_e32 v225, v67, v82
	v_mov_b32_e32 v82, v115
	v_fmac_f32_e32 v112, v4, v114
	v_fmac_f32_e32 v113, v5, v114
	v_fma_f32 v114, v2, v82, v80
	v_fma_f32 v115, v3, v82, v81
	v_mov_b32_e32 v80, v83
	v_fmac_f32_e32 v112, v0, v82
	v_fmac_f32_e32 v113, v1, v82
	v_fmac_f32_e32 v76, v64, v80
	v_fmac_f32_e32 v77, v65, v80
	v_fma_f32 v226, v66, v80, v228
	v_fma_f32 v227, v67, v80, v229
	ds_read_b128 v[64:67], v143
	ds_read_b128 v[80:83], v143 offset:4096
	s_mov_b32 s0, 0xb602000
	v_add_co_u32_e32 v228, vcc, s0, v108
	s_waitcnt vmcnt(14) lgkmcnt(1)
; __device__ __forceinline__ void gla_sample_unit(const Args& a, unsigned char* lds, int unit, int tid) {
;     ...
;     for (int g = 0; g < 8; ++g) {
;         if (g + 1 < 8) {
; #pragma unroll
;             for (int i = 0; i < 8; ++i) sb[(g + 1) & 1][i] = *(const f32x4*)(S0 + (size_t)(((g + 1) * 8 + i) * 4 + kq) * 512 + vc); }
; #pragma unroll
;         for (int i = 0; i < 8; ++i) { const int k = (g * 8 + i) * 4 + kq; const f32x4 s = sb[g & 1][i];
;             const f32x4 qv = *(const f32x4*)(Q4 + k * 4), kd = *(const f32x4*)(KD4 + k * 4); const float dec = DECS[k];
;             f32x4 sn = s * dec;
; #pragma unroll
;             for (int t = 0; t < 4; ++t) { sn += vr[t] * kd[t]; o[t] += s * qv[t]; }
;             *(f32x4*)(SN + (size_t)k * 512 + vc) = sn; } }
	v_fmac_f32_e32 v120, v58, v64
	v_fmac_f32_e32 v121, v59, v64
	v_addc_co_u32_e32 v229, vcc, 0, v109, vcc
	global_store_dwordx4 v[228:229], v[112:115], off nt
	v_fmac_f32_e32 v122, v56, v64
	v_fmac_f32_e32 v123, v57, v64
	s_mov_b32 s0, 0xb604000
	v_mul_f32_e32 v112, v58, v230
	v_mul_f32_e32 v113, v59, v230
	v_mul_f32_e32 v114, v56, v230
	v_mul_f32_e32 v115, v57, v230
	s_waitcnt lgkmcnt(0)
	v_fmac_f32_e32 v112, v14, v80
	v_fmac_f32_e32 v113, v15, v80
	v_fmac_f32_e32 v114, v12, v80
	v_fmac_f32_e32 v115, v13, v80
	v_fmac_f32_e32 v112, v10, v81
	v_fmac_f32_e32 v113, v11, v81
	v_fma_f32 v80, v8, v81, v114
	v_fma_f32 v81, v9, v81, v115
	v_fma_f32 v114, v58, v65, v116
	v_fma_f32 v115, v59, v65, v117
	v_fma_f32 v116, v56, v65, v118
	v_fma_f32 v117, v57, v65, v119
	v_fma_f32 v64, v6, v82, v112
	v_fma_f32 v65, v7, v82, v113
	v_fma_f32 v112, v58, v66, v224
	v_fma_f32 v113, v59, v66, v225
	v_fma_f32 v118, v56, v66, v222
	v_fma_f32 v119, v57, v66, v223
	v_mov_b32_e32 v66, v83
	v_fmac_f32_e32 v80, v4, v82
	v_fmac_f32_e32 v81, v5, v82
	v_fma_f32 v82, v2, v66, v64
	v_fma_f32 v83, v3, v66, v65
	v_mov_b32_e32 v64, v67
	v_fmac_f32_e32 v80, v0, v66
	v_fmac_f32_e32 v81, v1, v66
	v_fma_f32 v222, v58, v64, v226
	v_fma_f32 v223, v59, v64, v227
	v_fmac_f32_e32 v76, v56, v64
	v_fmac_f32_e32 v77, v57, v64
	ds_read_b128 v[56:59], v144
	ds_read_b128 v[64:67], v144 offset:4096
	v_add_co_u32_e32 v224, vcc, s0, v108
	s_mov_b32 s0, 0xb606000
	s_nop 0
	v_addc_co_u32_e32 v225, vcc, 0, v109, vcc
	global_store_dwordx4 v[224:225], v[80:83], off nt
	s_waitcnt vmcnt(15) lgkmcnt(1)
	v_fmac_f32_e32 v120, v50, v56
	v_fmac_f32_e32 v121, v51, v56
	v_fmac_f32_e32 v122, v48, v56
	v_fmac_f32_e32 v123, v49, v56
	v_mov_b32_e32 v80, v231
	v_mul_f32_e32 v82, v50, v80
	v_mul_f32_e32 v83, v51, v80
	v_mul_f32_e32 v81, v49, v80
	v_mul_f32_e32 v80, v48, v80
	s_waitcnt lgkmcnt(0)
	v_fmac_f32_e32 v82, v14, v64
	v_fmac_f32_e32 v83, v15, v64
	v_fmac_f32_e32 v80, v12, v64
	v_fmac_f32_e32 v81, v13, v64
	v_fmac_f32_e32 v82, v10, v65
	v_fmac_f32_e32 v83, v11, v65
	v_fma_f32 v64, v8, v65, v80
	v_fma_f32 v65, v9, v65, v81
	v_fma_f32 v80, v50, v57, v114
	v_fma_f32 v81, v51, v57, v115
	v_fma_f32 v114, v48, v57, v116
	v_fma_f32 v115, v49, v57, v117
	v_fma_f32 v56, v6, v66, v82
	v_fma_f32 v57, v7, v66, v83
	v_fma_f32 v82, v50, v58, v112
	v_fma_f32 v83, v51, v58, v113
	v_fma_f32 v112, v48, v58, v118
	v_fma_f32 v113, v49, v58, v119
	v_mov_b32_e32 v58, v67
	v_fmac_f32_e32 v64, v4, v66
	v_fmac_f32_e32 v65, v5, v66
	v_fma_f32 v66, v2, v58, v56
	v_fma_f32 v67, v3, v58, v57
	v_mov_b32_e32 v56, v59
	v_fmac_f32_e32 v64, v0, v58
	v_fmac_f32_e32 v65, v1, v58
	v_fma_f32 v116, v50, v56, v222
	v_fma_f32 v117, v51, v56, v223
	v_fmac_f32_e32 v76, v48, v56
	v_fmac_f32_e32 v77, v49, v56
	ds_read_b128 v[48:51], v145
	ds_read_b128 v[56:59], v145 offset:4096
	v_add_co_u32_e32 v118, vcc, s0, v108
	s_mov_b32 s0, 0xb608000
	s_nop 0
	v_addc_co_u32_e32 v119, vcc, 0, v109, vcc
	global_store_dwordx4 v[118:119], v[64:67], off nt
	s_waitcnt vmcnt(15) lgkmcnt(1)
	v_fma_f32 v118, v42, v48, v120
	v_fma_f32 v119, v43, v48, v121
	v_fma_f32 v120, v40, v48, v122
	v_fma_f32 v121, v41, v48, v123
	v_mul_f32_e32 v64, v42, v78
	v_mul_f32_e32 v65, v43, v78
	v_mul_f32_e32 v66, v40, v78
	v_mul_f32_e32 v67, v41, v78
	s_waitcnt lgkmcnt(0)
	v_fmac_f32_e32 v64, v14, v56
	v_fmac_f32_e32 v65, v15, v56
	v_fmac_f32_e32 v66, v12, v56
	v_fmac_f32_e32 v67, v13, v56
	v_fmac_f32_e32 v64, v10, v57
	v_fmac_f32_e32 v65, v11, v57
	v_fma_f32 v56, v8, v57, v66
	v_fma_f32 v57, v9, v57, v67
	v_fma_f32 v66, v42, v49, v80
	v_fma_f32 v67, v43, v49, v81
	v_fma_f32 v80, v40, v49, v114
	v_fma_f32 v81, v41, v49, v115
	v_fma_f32 v48, v6, v58, v64
	v_fma_f32 v49, v7, v58, v65
	v_fma_f32 v64, v42, v50, v82
	v_fma_f32 v65, v43, v50, v83
	v_fma_f32 v82, v40, v50, v112
	v_fma_f32 v83, v41, v50, v113
	v_mov_b32_e32 v50, v59
	v_fmac_f32_e32 v56, v4, v58
	v_fmac_f32_e32 v57, v5, v58
	v_fma_f32 v58, v2, v50, v48
	v_fma_f32 v59, v3, v50, v49
	v_mov_b32_e32 v48, v51
	v_fma_f32 v114, v40, v48, v76
	v_fma_f32 v115, v41, v48, v77
	v_add_co_u32_e32 v40, vcc, s0, v108
	v_fmac_f32_e32 v56, v0, v50
	v_fmac_f32_e32 v57, v1, v50
	s_nop 0
	v_addc_co_u32_e32 v41, vcc, 0, v109, vcc
	global_store_dwordx4 v[40:41], v[56:59], off nt
	v_fma_f32 v112, v42, v48, v116
	v_fma_f32 v113, v43, v48, v117
	ds_read_b128 v[40:43], v146
	ds_read_b128 v[48:51], v146 offset:4096
	ds_read2_b32 v[56:57], v107 offset0:24 offset1:28
	ds_read2_b32 v[76:77], v107 offset0:32 offset1:36
	v_mov_b32_e32 v58, v79
	s_waitcnt vmcnt(15)
	v_mul_f32_e32 v78, v34, v58
	v_mul_f32_e32 v79, v35, v58
	v_mul_f32_e32 v59, v33, v58
	v_mul_f32_e32 v58, v32, v58
	s_waitcnt lgkmcnt(2)
	v_fmac_f32_e32 v78, v14, v48
	v_fmac_f32_e32 v79, v15, v48
	v_fmac_f32_e32 v58, v12, v48
	v_fmac_f32_e32 v59, v13, v48
	v_fmac_f32_e32 v78, v10, v49
	v_fmac_f32_e32 v79, v11, v49
	v_fma_f32 v116, v34, v40, v118
	v_fma_f32 v117, v35, v40, v119
	v_fma_f32 v118, v32, v40, v120
	v_fma_f32 v119, v33, v40, v121
	v_fma_f32 v48, v8, v49, v58
	v_fma_f32 v49, v9, v49, v59
	v_fma_f32 v58, v34, v41, v66
	v_fma_f32 v59, v35, v41, v67
	v_fma_f32 v66, v32, v41, v80
	v_fma_f32 v67, v33, v41, v81
	v_fma_f32 v40, v6, v50, v78
	v_fma_f32 v41, v7, v50, v79
	v_fmac_f32_e32 v64, v34, v42
	v_fmac_f32_e32 v65, v35, v42
	v_fma_f32 v78, v32, v42, v82
	v_fma_f32 v79, v33, v42, v83
	v_mov_b32_e32 v42, v51
	v_fmac_f32_e32 v48, v4, v50
	v_fmac_f32_e32 v49, v5, v50
	v_fma_f32 v50, v2, v42, v40
	v_fma_f32 v51, v3, v42, v41
	v_mov_b32_e32 v40, v43
	v_fmac_f32_e32 v48, v0, v42
	v_fmac_f32_e32 v49, v1, v42
	v_fma_f32 v80, v34, v40, v112
	v_fma_f32 v81, v35, v40, v113
	v_fma_f32 v82, v32, v40, v114
	v_fma_f32 v83, v33, v40, v115
	ds_read_b128 v[32:35], v147
	ds_read_b128 v[40:43], v147 offset:4096
	s_mov_b32 s0, 0xb60a000
	v_add_co_u32_e32 v112, vcc, s0, v108
	s_waitcnt vmcnt(14) lgkmcnt(1)
; __device__ __forceinline__ void gla_sample_unit(const Args& a, unsigned char* lds, int unit, int tid) {
;     ...
;     for (int g = 0; g < 8; ++g) {
;         if (g + 1 < 8) {
; #pragma unroll
;             for (int i = 0; i < 8; ++i) sb[(g + 1) & 1][i] = *(const f32x4*)(S0 + (size_t)(((g + 1) * 8 + i) * 4 + kq) * 512 + vc); }
; #pragma unroll
;         for (int i = 0; i < 8; ++i) { const int k = (g * 8 + i) * 4 + kq; const f32x4 s = sb[g & 1][i];
;             const f32x4 qv = *(const f32x4*)(Q4 + k * 4), kd = *(const f32x4*)(KD4 + k * 4); const float dec = DECS[k];
;             f32x4 sn = s * dec;
; #pragma unroll
;             for (int t = 0; t < 4; ++t) { sn += vr[t] * kd[t]; o[t] += s * qv[t]; }
;             *(f32x4*)(SN + (size_t)k * 512 + vc) = sn; } }
	v_fma_f32 v114, v24, v32, v118
	v_fma_f32 v115, v25, v32, v119
	v_addc_co_u32_e32 v113, vcc, 0, v109, vcc
	global_store_dwordx4 v[112:113], v[48:51], off nt
	v_fma_f32 v112, v26, v32, v116
	v_fma_f32 v113, v27, v32, v117
	s_mov_b32 s0, 0xb60c000
	v_mul_f32_e32 v48, v26, v56
	v_mul_f32_e32 v49, v27, v56
	v_mul_f32_e32 v50, v24, v56
	v_mul_f32_e32 v51, v25, v56
	s_waitcnt lgkmcnt(0)
	v_fmac_f32_e32 v48, v14, v40
	v_fmac_f32_e32 v49, v15, v40
	v_fmac_f32_e32 v50, v12, v40
	v_fmac_f32_e32 v51, v13, v40
	v_fmac_f32_e32 v48, v10, v41
	v_fmac_f32_e32 v49, v11, v41
	v_fma_f32 v40, v8, v41, v50
	v_fma_f32 v41, v9, v41, v51
	v_fma_f32 v50, v26, v33, v58
	v_fma_f32 v51, v27, v33, v59
	v_fma_f32 v58, v24, v33, v66
	v_fma_f32 v59, v25, v33, v67
	v_fma_f32 v32, v6, v42, v48
	v_fma_f32 v33, v7, v42, v49
	v_fma_f32 v48, v26, v34, v64
	v_fma_f32 v49, v27, v34, v65
	v_fma_f32 v64, v24, v34, v78
	v_fma_f32 v65, v25, v34, v79
	v_mov_b32_e32 v34, v43
	v_fmac_f32_e32 v40, v4, v42
	v_fmac_f32_e32 v41, v5, v42
	v_fma_f32 v42, v2, v34, v32
	v_fma_f32 v43, v3, v34, v33
	v_mov_b32_e32 v32, v35
	v_fmac_f32_e32 v40, v0, v34
	v_fmac_f32_e32 v41, v1, v34
	v_fma_f32 v66, v26, v32, v80
	v_fma_f32 v67, v27, v32, v81
	v_fma_f32 v78, v24, v32, v82
	v_fma_f32 v79, v25, v32, v83
	ds_read_b128 v[24:27], v149
	ds_read_b128 v[32:35], v149 offset:4096
	v_add_co_u32_e32 v80, vcc, s0, v108
	s_mov_b32 s0, 0xb60e000
	s_nop 0
	v_addc_co_u32_e32 v81, vcc, 0, v109, vcc
	global_store_dwordx4 v[80:81], v[40:43], off nt
	s_waitcnt vmcnt(15) lgkmcnt(1)
	v_fma_f32 v120, v18, v24, v112
	v_fma_f32 v121, v19, v24, v113
	v_fma_f32 v122, v16, v24, v114
	v_fma_f32 v123, v17, v24, v115
	v_mov_b32_e32 v40, v57
	v_mul_f32_e32 v42, v18, v40
	v_mul_f32_e32 v43, v19, v40
	v_mul_f32_e32 v41, v17, v40
	v_mul_f32_e32 v40, v16, v40
	s_waitcnt lgkmcnt(0)
	v_fmac_f32_e32 v42, v14, v32
	v_fmac_f32_e32 v43, v15, v32
	v_fmac_f32_e32 v40, v12, v32
	v_fmac_f32_e32 v41, v13, v32
	v_fmac_f32_e32 v42, v10, v33
	v_fmac_f32_e32 v43, v11, v33
	v_fma_f32 v32, v8, v33, v40
	v_fma_f32 v33, v9, v33, v41
	v_fma_f32 v222, v18, v25, v50
	v_fma_f32 v223, v19, v25, v51
	v_fma_f32 v224, v16, v25, v58
	v_fma_f32 v225, v17, v25, v59
	v_fma_f32 v24, v6, v34, v42
	v_fma_f32 v25, v7, v34, v43
	v_fma_f32 v226, v18, v26, v48
	v_fma_f32 v227, v19, v26, v49
	v_fma_f32 v228, v16, v26, v64
	v_fma_f32 v229, v17, v26, v65
	v_mov_b32_e32 v26, v35
	v_fmac_f32_e32 v32, v4, v34
	v_fmac_f32_e32 v33, v5, v34
	v_fma_f32 v34, v2, v26, v24
	v_fma_f32 v35, v3, v26, v25
	v_mov_b32_e32 v24, v27
	v_fmac_f32_e32 v78, v16, v24
	v_fmac_f32_e32 v79, v17, v24
	v_add_co_u32_e32 v16, vcc, s0, v108
	v_fmac_f32_e32 v32, v0, v26
	v_fmac_f32_e32 v33, v1, v26
	s_nop 0
	v_addc_co_u32_e32 v17, vcc, 0, v109, vcc
	s_mov_b32 s0, 0x20000
	global_store_dwordx4 v[16:17], v[32:35], off nt
	v_add_co_u32_e32 v16, vcc, s0, v110
	s_mov_b32 s0, 0x22000
	s_nop 0
	v_addc_co_u32_e32 v17, vcc, 0, v111, vcc
	v_fma_f32 v230, v18, v24, v66
	v_fma_f32 v231, v19, v24, v67
	v_add_co_u32_e32 v18, vcc, s0, v110
	s_mov_b32 s0, 0x24000
	s_nop 0
	v_addc_co_u32_e32 v19, vcc, 0, v111, vcc
	global_load_dwordx4 v[80:83], v[16:17], off nt
	global_load_dwordx4 v[64:67], v[18:19], off nt
	v_add_co_u32_e32 v16, vcc, s0, v110
	s_mov_b32 s0, 0x26000
	s_nop 0
	v_addc_co_u32_e32 v17, vcc, 0, v111, vcc
	v_add_co_u32_e32 v18, vcc, s0, v110
	s_mov_b32 s0, 0x28000
	s_nop 0
	v_addc_co_u32_e32 v19, vcc, 0, v111, vcc
	global_load_dwordx4 v[56:59], v[16:17], off nt
	global_load_dwordx4 v[48:51], v[18:19], off nt
	v_add_co_u32_e32 v16, vcc, s0, v110
	s_mov_b32 s0, 0x2a000
	s_nop 0
	v_addc_co_u32_e32 v17, vcc, 0, v111, vcc
	v_add_co_u32_e32 v18, vcc, s0, v110
	s_mov_b32 s0, 0x2c000
	s_nop 0
	v_addc_co_u32_e32 v19, vcc, 0, v111, vcc
	global_load_dwordx4 v[40:43], v[16:17], off nt
	global_load_dwordx4 v[32:35], v[18:19], off nt
	ds_read_b128 v[112:115], v150
	ds_read_b128 v[116:119], v150 offset:4096
	s_waitcnt vmcnt(21)
	v_mul_f32_e32 v232, v74, v76
	v_mul_f32_e32 v233, v75, v76
	v_mul_f32_e32 v234, v72, v76
	v_mul_f32_e32 v235, v73, v76
	v_add_co_u32_e32 v16, vcc, s0, v110
	s_waitcnt lgkmcnt(0)
	v_fmac_f32_e32 v232, v14, v116
	v_fmac_f32_e32 v233, v15, v116
	v_fmac_f32_e32 v234, v12, v116
	v_fmac_f32_e32 v235, v13, v116
	v_addc_co_u32_e32 v17, vcc, 0, v111, vcc
	s_mov_b32 s0, 0x2e000
	v_fmac_f32_e32 v232, v10, v117
	v_fmac_f32_e32 v233, v11, v117
	v_fma_f32 v116, v8, v117, v234
	v_fma_f32 v117, v9, v117, v235
	v_add_co_u32_e32 v18, vcc, s0, v110
	v_fmac_f32_e32 v120, v74, v112
	v_fmac_f32_e32 v121, v75, v112
	v_fmac_f32_e32 v122, v72, v112
	v_fmac_f32_e32 v123, v73, v112
	v_fmac_f32_e32 v222, v74, v113
	v_fmac_f32_e32 v223, v75, v113
	v_fmac_f32_e32 v224, v72, v113
	v_fmac_f32_e32 v225, v73, v113
	v_fma_f32 v112, v6, v118, v232
	v_fma_f32 v113, v7, v118, v233
	v_fmac_f32_e32 v116, v4, v118
	v_fmac_f32_e32 v117, v5, v118
	v_mov_b32_e32 v76, v119
	v_addc_co_u32_e32 v19, vcc, 0, v111, vcc
	v_fma_f32 v118, v2, v76, v112
	v_fma_f32 v119, v3, v76, v113
	v_fmac_f32_e32 v116, v0, v76
	v_fmac_f32_e32 v117, v1, v76
	v_mov_b32_e32 v76, v115
	global_load_dwordx4 v[24:27], v[16:17], off nt
	s_nop 0
	global_load_dwordx4 v[16:19], v[18:19], off nt
	v_fmac_f32_e32 v226, v74, v114
	v_fmac_f32_e32 v227, v75, v114
	v_fmac_f32_e32 v228, v72, v114
	v_fmac_f32_e32 v229, v73, v114
	v_fmac_f32_e32 v230, v74, v76
	v_fmac_f32_e32 v231, v75, v76
	v_fma_f32 v232, v72, v76, v78
	v_fma_f32 v233, v73, v76, v79
	ds_read_b128 v[72:75], v151
	ds_read_b128 v[112:115], v151 offset:4096
	s_mov_b32 s0, 0xb610000
	v_add_co_u32_e32 v78, vcc, s0, v108
	v_mov_b32_e32 v76, v77
	s_nop 0
	v_addc_co_u32_e32 v79, vcc, 0, v109, vcc
	global_store_dwordx4 v[78:79], v[116:119], off nt
	s_waitcnt vmcnt(23)
; __device__ __forceinline__ void gla_sample_unit(const Args& a, unsigned char* lds, int unit, int tid) {
;     ...
;     for (int g = 0; g < 8; ++g) {
;         if (g + 1 < 8) {
; #pragma unroll
;             for (int i = 0; i < 8; ++i) sb[(g + 1) & 1][i] = *(const f32x4*)(S0 + (size_t)(((g + 1) * 8 + i) * 4 + kq) * 512 + vc); }
; #pragma unroll
;         for (int i = 0; i < 8; ++i) { const int k = (g * 8 + i) * 4 + kq; const f32x4 s = sb[g & 1][i];
;             const f32x4 qv = *(const f32x4*)(Q4 + k * 4), kd = *(const f32x4*)(KD4 + k * 4); const float dec = DECS[k];
;             f32x4 sn = s * dec;
; #pragma unroll
;             for (int t = 0; t < 4; ++t) { sn += vr[t] * kd[t]; o[t] += s * qv[t]; }
;             *(f32x4*)(SN + (size_t)k * 512 + vc) = sn; } }
	v_mul_f32_e32 v78, v70, v76
	v_mul_f32_e32 v79, v71, v76
	v_mul_f32_e32 v77, v69, v76
	v_mul_f32_e32 v76, v68, v76
	s_waitcnt lgkmcnt(0)
	v_fmac_f32_e32 v78, v14, v112
	v_fmac_f32_e32 v79, v15, v112
	v_fmac_f32_e32 v76, v12, v112
	v_fmac_f32_e32 v77, v13, v112
	v_fmac_f32_e32 v78, v10, v113
	v_fmac_f32_e32 v79, v11, v113
	v_fma_f32 v116, v70, v72, v120
	v_fma_f32 v117, v71, v72, v121
	v_fma_f32 v118, v68, v72, v122
	v_fma_f32 v119, v69, v72, v123
	v_fmac_f32_e32 v76, v8, v113
	v_fmac_f32_e32 v77, v9, v113
	v_fma_f32 v112, v70, v73, v222
	v_fma_f32 v113, v71, v73, v223
	v_fma_f32 v120, v68, v73, v224
	v_fma_f32 v121, v69, v73, v225
	v_fma_f32 v72, v6, v114, v78
	v_fma_f32 v73, v7, v114, v79
	v_fma_f32 v122, v70, v74, v226
	v_fma_f32 v123, v71, v74, v227
	v_fma_f32 v222, v68, v74, v228
	v_fma_f32 v223, v69, v74, v229
	v_mov_b32_e32 v74, v115
	v_fmac_f32_e32 v76, v4, v114
	v_fmac_f32_e32 v77, v5, v114
	v_fma_f32 v78, v2, v74, v72
	v_fma_f32 v79, v3, v74, v73
	v_mov_b32_e32 v72, v75
	v_fmac_f32_e32 v76, v0, v74
	v_fmac_f32_e32 v77, v1, v74
	v_fma_f32 v114, v70, v72, v230
	v_fma_f32 v115, v71, v72, v231
	v_fma_f32 v224, v68, v72, v232
	v_fma_f32 v225, v69, v72, v233
	ds_read_b128 v[68:71], v152
	ds_read_b128 v[72:75], v152 offset:4096
	ds_read2_b32 v[226:227], v107 offset0:40 offset1:44
	s_mov_b32 s0, 0xb612000
	v_add_co_u32_e32 v228, vcc, s0, v108
	s_waitcnt vmcnt(22) lgkmcnt(2)
	v_fmac_f32_e32 v116, v62, v68
	v_fmac_f32_e32 v117, v63, v68
	v_addc_co_u32_e32 v229, vcc, 0, v109, vcc
	global_store_dwordx4 v[228:229], v[76:79], off nt
	v_fmac_f32_e32 v118, v60, v68
	v_fmac_f32_e32 v119, v61, v68
	s_mov_b32 s0, 0xb614000
	s_waitcnt lgkmcnt(0)
	v_mul_f32_e32 v76, v62, v226
	v_mul_f32_e32 v77, v63, v226
	v_mul_f32_e32 v78, v60, v226
	v_mul_f32_e32 v79, v61, v226
	v_fmac_f32_e32 v76, v14, v72
	v_fmac_f32_e32 v77, v15, v72
	v_fmac_f32_e32 v78, v12, v72
	v_fmac_f32_e32 v79, v13, v72
	v_fmac_f32_e32 v76, v10, v73
	v_fmac_f32_e32 v77, v11, v73
	v_fma_f32 v72, v8, v73, v78
	v_fma_f32 v73, v9, v73, v79
	v_fma_f32 v78, v62, v69, v112
	v_fma_f32 v79, v63, v69, v113
	v_fma_f32 v112, v60, v69, v120
	v_fma_f32 v113, v61, v69, v121
	v_fma_f32 v68, v6, v74, v76
	v_fma_f32 v69, v7, v74, v77
	v_fma_f32 v76, v62, v70, v122
	v_fma_f32 v77, v63, v70, v123
	v_fma_f32 v120, v60, v70, v222
	v_fma_f32 v121, v61, v70, v223
	v_mov_b32_e32 v70, v75
	v_fmac_f32_e32 v72, v4, v74
	v_fmac_f32_e32 v73, v5, v74
	v_fma_f32 v74, v2, v70, v68
	v_fma_f32 v75, v3, v70, v69
	v_mov_b32_e32 v68, v71
	v_fmac_f32_e32 v72, v0, v70
	v_fmac_f32_e32 v73, v1, v70
	v_fmac_f32_e32 v114, v62, v68
	v_fmac_f32_e32 v115, v63, v68
	v_fma_f32 v122, v60, v68, v224
	v_fma_f32 v123, v61, v68, v225
	ds_read_b128 v[60:63], v153
	ds_read_b128 v[68:71], v153 offset:4096
	v_add_co_u32_e32 v222, vcc, s0, v108
	s_mov_b32 s0, 0xb616000
	s_nop 0
	v_addc_co_u32_e32 v223, vcc, 0, v109, vcc
	global_store_dwordx4 v[222:223], v[72:75], off nt
	s_waitcnt vmcnt(23) lgkmcnt(1)
	v_fmac_f32_e32 v116, v54, v60
	v_fmac_f32_e32 v117, v55, v60
	v_fmac_f32_e32 v118, v52, v60
	v_fmac_f32_e32 v119, v53, v60
	v_mov_b32_e32 v72, v227
	v_mul_f32_e32 v74, v54, v72
	v_mul_f32_e32 v75, v55, v72
	v_mul_f32_e32 v73, v53, v72
	v_mul_f32_e32 v72, v52, v72
	s_waitcnt lgkmcnt(0)
	v_fmac_f32_e32 v74, v14, v68
	v_fmac_f32_e32 v75, v15, v68
	v_fmac_f32_e32 v72, v12, v68
	v_fmac_f32_e32 v73, v13, v68
	v_fmac_f32_e32 v74, v10, v69
	v_fmac_f32_e32 v75, v11, v69
	v_fma_f32 v68, v8, v69, v72
	v_fma_f32 v69, v9, v69, v73
	v_fma_f32 v72, v54, v61, v78
	v_fma_f32 v73, v55, v61, v79
	v_fma_f32 v78, v52, v61, v112
	v_fma_f32 v79, v53, v61, v113
	v_fma_f32 v60, v6, v70, v74
	v_fma_f32 v61, v7, v70, v75
	v_fma_f32 v74, v54, v62, v76
	v_fma_f32 v75, v55, v62, v77
	v_fma_f32 v76, v52, v62, v120
	v_fma_f32 v77, v53, v62, v121
	v_mov_b32_e32 v62, v71
	v_fmac_f32_e32 v68, v4, v70
	v_fmac_f32_e32 v69, v5, v70
	v_fma_f32 v70, v2, v62, v60
	v_fma_f32 v71, v3, v62, v61
	v_mov_b32_e32 v60, v63
	v_fmac_f32_e32 v68, v0, v62
	v_fmac_f32_e32 v69, v1, v62
	v_fma_f32 v112, v54, v60, v114
	v_fma_f32 v113, v55, v60, v115
	v_fma_f32 v114, v52, v60, v122
	v_fma_f32 v115, v53, v60, v123
	ds_read_b128 v[52:55], v154
	ds_read_b128 v[60:63], v154 offset:4096
	ds_read2_b32 v[120:121], v107 offset0:48 offset1:52
	v_add_co_u32_e32 v122, vcc, s0, v108
	s_waitcnt vmcnt(22) lgkmcnt(2)
	v_fmac_f32_e32 v116, v46, v52
	v_fmac_f32_e32 v117, v47, v52
	v_addc_co_u32_e32 v123, vcc, 0, v109, vcc
	global_store_dwordx4 v[122:123], v[68:71], off nt
	v_fmac_f32_e32 v118, v44, v52
	v_fmac_f32_e32 v119, v45, v52
	s_mov_b32 s0, 0xb618000
	s_waitcnt lgkmcnt(0)
	v_mul_f32_e32 v68, v46, v120
	v_mul_f32_e32 v69, v47, v120
	v_mul_f32_e32 v70, v44, v120
	v_mul_f32_e32 v71, v45, v120
	v_fmac_f32_e32 v68, v14, v60
	v_fmac_f32_e32 v69, v15, v60
	v_fmac_f32_e32 v70, v12, v60
	v_fmac_f32_e32 v71, v13, v60
	v_fmac_f32_e32 v68, v10, v61
	v_fmac_f32_e32 v69, v11, v61
	v_fma_f32 v60, v8, v61, v70
	v_fma_f32 v61, v9, v61, v71
	v_fma_f32 v70, v46, v53, v72
	v_fma_f32 v71, v47, v53, v73
	v_fma_f32 v72, v44, v53, v78
	v_fma_f32 v73, v45, v53, v79
	v_fma_f32 v52, v6, v62, v68
	v_fma_f32 v53, v7, v62, v69
	v_fma_f32 v68, v46, v54, v74
	v_fma_f32 v69, v47, v54, v75
	v_fma_f32 v74, v44, v54, v76
	v_fma_f32 v75, v45, v54, v77
	v_mov_b32_e32 v54, v63
	v_fmac_f32_e32 v60, v4, v62
	v_fmac_f32_e32 v61, v5, v62
	v_fma_f32 v62, v2, v54, v52
	v_fma_f32 v63, v3, v54, v53
	v_mov_b32_e32 v52, v55
	v_fmac_f32_e32 v60, v0, v54
	v_fmac_f32_e32 v61, v1, v54
	v_fma_f32 v76, v46, v52, v112
	v_fma_f32 v77, v47, v52, v113
	v_fma_f32 v78, v44, v52, v114
	v_fma_f32 v79, v45, v52, v115
	ds_read_b128 v[44:47], v155
	ds_read_b128 v[52:55], v155 offset:4096
	v_add_co_u32_e32 v112, vcc, s0, v108
	s_mov_b32 s0, 0xb61a000
	s_nop 0
	v_addc_co_u32_e32 v113, vcc, 0, v109, vcc
	global_store_dwordx4 v[112:113], v[60:63], off nt
	s_waitcnt vmcnt(23) lgkmcnt(1)
; __device__ __forceinline__ void gla_sample_unit(const Args& a, unsigned char* lds, int unit, int tid) {
;     ...
;     for (int g = 0; g < 8; ++g) {
;         if (g + 1 < 8) {
; #pragma unroll
;             for (int i = 0; i < 8; ++i) sb[(g + 1) & 1][i] = *(const f32x4*)(S0 + (size_t)(((g + 1) * 8 + i) * 4 + kq) * 512 + vc); }
; #pragma unroll
;         for (int i = 0; i < 8; ++i) { const int k = (g * 8 + i) * 4 + kq; const f32x4 s = sb[g & 1][i];
;             const f32x4 qv = *(const f32x4*)(Q4 + k * 4), kd = *(const f32x4*)(KD4 + k * 4); const float dec = DECS[k];
;             f32x4 sn = s * dec;
; #pragma unroll
;             for (int t = 0; t < 4; ++t) { sn += vr[t] * kd[t]; o[t] += s * qv[t]; }
;             *(f32x4*)(SN + (size_t)k * 512 + vc) = sn; } }
	v_fma_f32 v112, v38, v44, v116
	v_fma_f32 v113, v39, v44, v117
	v_fma_f32 v114, v36, v44, v118
	v_fma_f32 v115, v37, v44, v119
	v_mov_b32_e32 v60, v121
	v_mul_f32_e32 v62, v38, v60
	v_mul_f32_e32 v63, v39, v60
	v_mul_f32_e32 v61, v37, v60
	v_mul_f32_e32 v60, v36, v60
	s_waitcnt lgkmcnt(0)
	v_fmac_f32_e32 v62, v14, v52
	v_fmac_f32_e32 v63, v15, v52
	v_fmac_f32_e32 v60, v12, v52
	v_fmac_f32_e32 v61, v13, v52
	v_fmac_f32_e32 v62, v10, v53
	v_fmac_f32_e32 v63, v11, v53
	v_fma_f32 v52, v8, v53, v60
	v_fma_f32 v53, v9, v53, v61
	v_fma_f32 v60, v38, v45, v70
	v_fma_f32 v61, v39, v45, v71
	v_fma_f32 v70, v36, v45, v72
	v_fma_f32 v71, v37, v45, v73
	v_fma_f32 v44, v6, v54, v62
	v_fma_f32 v45, v7, v54, v63
	v_fma_f32 v62, v38, v46, v68
	v_fma_f32 v63, v39, v46, v69
	v_fma_f32 v68, v36, v46, v74
	v_fma_f32 v69, v37, v46, v75
	v_mov_b32_e32 v46, v55
	v_fmac_f32_e32 v52, v4, v54
	v_fmac_f32_e32 v53, v5, v54
	v_fma_f32 v54, v2, v46, v44
	v_fma_f32 v55, v3, v46, v45
	v_mov_b32_e32 v44, v47
	v_fmac_f32_e32 v52, v0, v46
	v_fmac_f32_e32 v53, v1, v46
	v_fma_f32 v72, v38, v44, v76
	v_fma_f32 v73, v39, v44, v77
	v_fma_f32 v74, v36, v44, v78
	v_fma_f32 v75, v37, v44, v79
	ds_read_b128 v[36:39], v156
	ds_read_b128 v[44:47], v156 offset:4096
	ds_read2_b32 v[76:77], v107 offset0:56 offset1:60
	v_add_co_u32_e32 v78, vcc, s0, v108
	s_mov_b32 s0, 0xb61c000
	s_nop 0
	v_addc_co_u32_e32 v79, vcc, 0, v109, vcc
	global_store_dwordx4 v[78:79], v[52:55], off nt
	s_waitcnt vmcnt(23) lgkmcnt(2)
	v_fma_f32 v78, v30, v36, v112
	v_fma_f32 v79, v31, v36, v113
	v_fma_f32 v112, v28, v36, v114
	v_fma_f32 v113, v29, v36, v115
	s_waitcnt lgkmcnt(0)
	v_mul_f32_e32 v52, v30, v76
	v_mul_f32_e32 v53, v31, v76
	v_mul_f32_e32 v54, v28, v76
	v_mul_f32_e32 v55, v29, v76
	v_fmac_f32_e32 v52, v14, v44
	v_fmac_f32_e32 v53, v15, v44
	v_fmac_f32_e32 v54, v12, v44
	v_fmac_f32_e32 v55, v13, v44
	v_fmac_f32_e32 v52, v10, v45
	v_fmac_f32_e32 v53, v11, v45
	v_fma_f32 v44, v8, v45, v54
	v_fma_f32 v45, v9, v45, v55
	v_fma_f32 v54, v30, v37, v60
	v_fma_f32 v55, v31, v37, v61
	v_fma_f32 v60, v28, v37, v70
	v_fma_f32 v61, v29, v37, v71
	v_fma_f32 v36, v6, v46, v52
	v_fma_f32 v37, v7, v46, v53
	v_fma_f32 v52, v30, v38, v62
	v_fma_f32 v53, v31, v38, v63
	v_fma_f32 v62, v28, v38, v68
	v_fma_f32 v63, v29, v38, v69
	v_mov_b32_e32 v38, v47
	v_fmac_f32_e32 v44, v4, v46
	v_fmac_f32_e32 v45, v5, v46
	v_fma_f32 v46, v2, v38, v36
	v_fma_f32 v47, v3, v38, v37
	v_mov_b32_e32 v36, v39
	v_fmac_f32_e32 v44, v0, v38
	v_fmac_f32_e32 v45, v1, v38
	v_fma_f32 v68, v30, v36, v72
	v_fma_f32 v69, v31, v36, v73
	v_fma_f32 v70, v28, v36, v74
	v_fma_f32 v71, v29, v36, v75
	ds_read_b128 v[28:31], v157
	ds_read_b128 v[36:39], v157 offset:4096
	v_add_co_u32_e32 v72, vcc, s0, v108
	s_mov_b32 s0, 0xb61e000
	s_nop 0
	v_addc_co_u32_e32 v73, vcc, 0, v109, vcc
	global_store_dwordx4 v[72:73], v[44:47], off nt
	s_waitcnt vmcnt(23) lgkmcnt(1)
	v_fma_f32 v116, v22, v28, v78
	v_fma_f32 v117, v23, v28, v79
	v_fma_f32 v118, v20, v28, v112
	v_fma_f32 v119, v21, v28, v113
	v_mov_b32_e32 v44, v77
	v_mul_f32_e32 v46, v22, v44
	v_mul_f32_e32 v47, v23, v44
	v_mul_f32_e32 v45, v21, v44
	v_mul_f32_e32 v44, v20, v44
	s_waitcnt lgkmcnt(0)
	v_fmac_f32_e32 v46, v14, v36
	v_fmac_f32_e32 v47, v15, v36
	v_fmac_f32_e32 v44, v12, v36
	v_fmac_f32_e32 v45, v13, v36
	v_fmac_f32_e32 v46, v10, v37
	v_fmac_f32_e32 v47, v11, v37
	v_fma_f32 v36, v8, v37, v44
	v_fma_f32 v37, v9, v37, v45
	v_fma_f32 v120, v22, v29, v54
	v_fma_f32 v121, v23, v29, v55
	v_fma_f32 v122, v20, v29, v60
	v_fma_f32 v123, v21, v29, v61
	v_fma_f32 v28, v6, v38, v46
	v_fma_f32 v29, v7, v38, v47
	v_fma_f32 v222, v22, v30, v52
	v_fma_f32 v223, v23, v30, v53
	v_fma_f32 v224, v20, v30, v62
	v_fma_f32 v225, v21, v30, v63
	v_mov_b32_e32 v30, v39
	v_fmac_f32_e32 v36, v4, v38
	v_fmac_f32_e32 v37, v5, v38
	v_fma_f32 v38, v2, v30, v28
	v_fma_f32 v39, v3, v30, v29
	v_mov_b32_e32 v28, v31
	v_fma_f32 v228, v20, v28, v70
	v_fma_f32 v229, v21, v28, v71
	v_add_co_u32_e32 v20, vcc, s0, v108
	v_fmac_f32_e32 v36, v0, v30
	v_fmac_f32_e32 v37, v1, v30
	s_nop 0
	v_addc_co_u32_e32 v21, vcc, 0, v109, vcc
	s_mov_b32 s0, 0x30000
	global_store_dwordx4 v[20:21], v[36:39], off nt
	v_add_co_u32_e32 v20, vcc, s0, v110
	s_mov_b32 s0, 0x32000
	s_nop 0
	v_addc_co_u32_e32 v21, vcc, 0, v111, vcc
	v_fma_f32 v226, v22, v28, v68
	v_fma_f32 v227, v23, v28, v69
	v_add_co_u32_e32 v22, vcc, s0, v110
	s_mov_b32 s0, 0x34000
	s_nop 0
	v_addc_co_u32_e32 v23, vcc, 0, v111, vcc
	global_load_dwordx4 v[76:79], v[20:21], off nt
	global_load_dwordx4 v[68:71], v[22:23], off nt
	v_add_co_u32_e32 v20, vcc, s0, v110
	s_mov_b32 s0, 0x36000
	s_nop 0
	v_addc_co_u32_e32 v21, vcc, 0, v111, vcc
	v_add_co_u32_e32 v22, vcc, s0, v110
	s_mov_b32 s0, 0x38000
	s_nop 0
	v_addc_co_u32_e32 v23, vcc, 0, v111, vcc
	global_load_dwordx4 v[60:63], v[20:21], off nt
	global_load_dwordx4 v[52:55], v[22:23], off nt
	v_add_co_u32_e32 v20, vcc, s0, v110
	s_mov_b32 s0, 0x3a000
	s_nop 0
	v_addc_co_u32_e32 v21, vcc, 0, v111, vcc
	v_add_co_u32_e32 v22, vcc, s0, v110
	s_mov_b32 s0, 0x3c000
	s_nop 0
	v_addc_co_u32_e32 v23, vcc, 0, v111, vcc
	global_load_dwordx4 v[44:47], v[20:21], off nt
	global_load_dwordx4 v[36:39], v[22:23], off nt
	ds_read2_b32 v[230:231], v107 offset0:64 offset1:68
	ds_read_b128 v[72:75], v158
	ds_read_b128 v[112:115], v158 offset:4096
	v_add_co_u32_e32 v20, vcc, s0, v110
	s_waitcnt vmcnt(21) lgkmcnt(2)
	v_mul_f32_e32 v232, v82, v230
	v_mul_f32_e32 v233, v83, v230
	v_mul_f32_e32 v234, v80, v230
	v_mul_f32_e32 v235, v81, v230
	s_waitcnt lgkmcnt(0)
; __device__ __forceinline__ void gla_sample_unit(const Args& a, unsigned char* lds, int unit, int tid) {
;     ...
;     for (int g = 0; g < 8; ++g) {
;         if (g + 1 < 8) {
; #pragma unroll
;             for (int i = 0; i < 8; ++i) sb[(g + 1) & 1][i] = *(const f32x4*)(S0 + (size_t)(((g + 1) * 8 + i) * 4 + kq) * 512 + vc); }
; #pragma unroll
;         for (int i = 0; i < 8; ++i) { const int k = (g * 8 + i) * 4 + kq; const f32x4 s = sb[g & 1][i];
;             const f32x4 qv = *(const f32x4*)(Q4 + k * 4), kd = *(const f32x4*)(KD4 + k * 4); const float dec = DECS[k];
;             f32x4 sn = s * dec;
; #pragma unroll
;             for (int t = 0; t < 4; ++t) { sn += vr[t] * kd[t]; o[t] += s * qv[t]; }
;             *(f32x4*)(SN + (size_t)k * 512 + vc) = sn; } }
	v_fmac_f32_e32 v232, v14, v112
	v_fmac_f32_e32 v233, v15, v112
	v_addc_co_u32_e32 v21, vcc, 0, v111, vcc
	s_mov_b32 s0, 0x3e000
	v_fmac_f32_e32 v234, v12, v112
	v_fmac_f32_e32 v235, v13, v112
	v_fmac_f32_e32 v232, v10, v113
	v_fmac_f32_e32 v233, v11, v113
	v_add_co_u32_e32 v22, vcc, s0, v110
	v_fmac_f32_e32 v116, v82, v72
	v_fmac_f32_e32 v117, v83, v72
	v_fmac_f32_e32 v118, v80, v72
	v_fmac_f32_e32 v119, v81, v72
	v_fma_f32 v112, v8, v113, v234
	v_fma_f32 v113, v9, v113, v235
	v_fmac_f32_e32 v120, v82, v73
	v_fmac_f32_e32 v121, v83, v73
	v_fmac_f32_e32 v122, v80, v73
	v_fmac_f32_e32 v123, v81, v73
	v_fma_f32 v72, v6, v114, v232
	v_fma_f32 v73, v7, v114, v233
	v_fmac_f32_e32 v222, v82, v74
	v_fmac_f32_e32 v223, v83, v74
	v_fmac_f32_e32 v224, v80, v74
	v_fmac_f32_e32 v225, v81, v74
	v_mov_b32_e32 v74, v115
	v_addc_co_u32_e32 v23, vcc, 0, v111, vcc
	v_fmac_f32_e32 v112, v4, v114
	v_fmac_f32_e32 v113, v5, v114
	v_fma_f32 v114, v2, v74, v72
	v_fma_f32 v115, v3, v74, v73
	v_mov_b32_e32 v72, v75
	global_load_dwordx4 v[28:31], v[20:21], off nt
	s_nop 0
	global_load_dwordx4 v[20:23], v[22:23], off nt
	v_fmac_f32_e32 v112, v0, v74
	v_fmac_f32_e32 v113, v1, v74
	v_fmac_f32_e32 v226, v82, v72
	v_fmac_f32_e32 v227, v83, v72
	v_fmac_f32_e32 v228, v80, v72
	v_fmac_f32_e32 v229, v81, v72
	s_mov_b32 s0, 0xb620000
	ds_read_b128 v[72:75], v159
	ds_read_b128 v[80:83], v159 offset:4096
	v_add_co_u32_e32 v232, vcc, s0, v108
	s_mov_b32 s0, 0xb622000
	s_nop 0
	v_addc_co_u32_e32 v233, vcc, 0, v109, vcc
	global_store_dwordx4 v[232:233], v[112:115], off nt
	s_waitcnt vmcnt(23) lgkmcnt(1)
	v_fmac_f32_e32 v116, v66, v72
	v_fmac_f32_e32 v117, v67, v72
	v_fmac_f32_e32 v118, v64, v72
	v_fmac_f32_e32 v119, v65, v72
	v_mov_b32_e32 v112, v231
	v_mul_f32_e32 v114, v66, v112
	v_mul_f32_e32 v115, v67, v112
	v_mul_f32_e32 v113, v65, v112
	v_mul_f32_e32 v112, v64, v112
	s_waitcnt lgkmcnt(0)
	v_fmac_f32_e32 v114, v14, v80
	v_fmac_f32_e32 v115, v15, v80
	v_fmac_f32_e32 v112, v12, v80
	v_fmac_f32_e32 v113, v13, v80
	v_fmac_f32_e32 v114, v10, v81
	v_fmac_f32_e32 v115, v11, v81
	v_fma_f32 v80, v8, v81, v112
	v_fma_f32 v81, v9, v81, v113
	v_fma_f32 v112, v66, v73, v120
	v_fma_f32 v113, v67, v73, v121
	v_fma_f32 v120, v64, v73, v122
	v_fma_f32 v121, v65, v73, v123
	v_fma_f32 v72, v6, v82, v114
	v_fma_f32 v73, v7, v82, v115
	v_fma_f32 v114, v66, v74, v222
	v_fma_f32 v115, v67, v74, v223
	v_fma_f32 v122, v64, v74, v224
	v_fma_f32 v123, v65, v74, v225
	v_mov_b32_e32 v74, v83
	v_fmac_f32_e32 v80, v4, v82
	v_fmac_f32_e32 v81, v5, v82
	v_fma_f32 v82, v2, v74, v72
	v_fma_f32 v83, v3, v74, v73
	v_mov_b32_e32 v72, v75
	v_fmac_f32_e32 v80, v0, v74
	v_fmac_f32_e32 v81, v1, v74
	v_fma_f32 v222, v66, v72, v226
	v_fma_f32 v223, v67, v72, v227
	v_fma_f32 v224, v64, v72, v228
	v_fma_f32 v225, v65, v72, v229
	ds_read_b128 v[64:67], v160
	ds_read_b128 v[72:75], v160 offset:4096
	ds_read2_b32 v[226:227], v107 offset0:72 offset1:76
	v_add_co_u32_e32 v228, vcc, s0, v108
	s_waitcnt vmcnt(22) lgkmcnt(2)
	v_fmac_f32_e32 v116, v58, v64
	v_fmac_f32_e32 v117, v59, v64
	v_addc_co_u32_e32 v229, vcc, 0, v109, vcc
	global_store_dwordx4 v[228:229], v[80:83], off nt
	v_fmac_f32_e32 v118, v56, v64
	v_fmac_f32_e32 v119, v57, v64
	s_mov_b32 s0, 0xb624000
	s_waitcnt lgkmcnt(0)
	v_mul_f32_e32 v80, v58, v226
	v_mul_f32_e32 v81, v59, v226
	v_mul_f32_e32 v82, v56, v226
	v_mul_f32_e32 v83, v57, v226
	v_fmac_f32_e32 v80, v14, v72
	v_fmac_f32_e32 v81, v15, v72
	v_fmac_f32_e32 v82, v12, v72
	v_fmac_f32_e32 v83, v13, v72
	v_fmac_f32_e32 v80, v10, v73
	v_fmac_f32_e32 v81, v11, v73
	v_fma_f32 v72, v8, v73, v82
	v_fma_f32 v73, v9, v73, v83
	v_fma_f32 v82, v58, v65, v112
	v_fma_f32 v83, v59, v65, v113
	v_fma_f32 v112, v56, v65, v120
	v_fma_f32 v113, v57, v65, v121
	v_fma_f32 v64, v6, v74, v80
	v_fma_f32 v65, v7, v74, v81
	v_fma_f32 v80, v58, v66, v114
	v_fma_f32 v81, v59, v66, v115
	v_fma_f32 v114, v56, v66, v122
	v_fma_f32 v115, v57, v66, v123
	v_mov_b32_e32 v66, v75
	v_fmac_f32_e32 v72, v4, v74
	v_fmac_f32_e32 v73, v5, v74
	v_fma_f32 v74, v2, v66, v64
	v_fma_f32 v75, v3, v66, v65
	v_mov_b32_e32 v64, v67
	v_fmac_f32_e32 v72, v0, v66
	v_fmac_f32_e32 v73, v1, v66
	v_fma_f32 v120, v58, v64, v222
	v_fma_f32 v121, v59, v64, v223
	v_fma_f32 v122, v56, v64, v224
	v_fma_f32 v123, v57, v64, v225
	ds_read_b128 v[56:59], v161
	ds_read_b128 v[64:67], v161 offset:4096
	v_add_co_u32_e32 v222, vcc, s0, v108
	s_mov_b32 s0, 0xb626000
	s_nop 0
	v_addc_co_u32_e32 v223, vcc, 0, v109, vcc
	global_store_dwordx4 v[222:223], v[72:75], off nt
	s_waitcnt vmcnt(23) lgkmcnt(1)
	v_fmac_f32_e32 v116, v50, v56
	v_fmac_f32_e32 v117, v51, v56
	v_fmac_f32_e32 v118, v48, v56
	v_fmac_f32_e32 v119, v49, v56
	v_mov_b32_e32 v72, v227
	v_mul_f32_e32 v74, v50, v72
	v_mul_f32_e32 v75, v51, v72
	v_mul_f32_e32 v73, v49, v72
	v_mul_f32_e32 v72, v48, v72
	s_waitcnt lgkmcnt(0)
	v_fmac_f32_e32 v74, v14, v64
	v_fmac_f32_e32 v75, v15, v64
	v_fmac_f32_e32 v72, v12, v64
	v_fmac_f32_e32 v73, v13, v64
	v_fmac_f32_e32 v74, v10, v65
	v_fmac_f32_e32 v75, v11, v65
	v_fma_f32 v64, v8, v65, v72
	v_fma_f32 v65, v9, v65, v73
	v_fma_f32 v72, v50, v57, v82
	v_fma_f32 v73, v51, v57, v83
	v_fma_f32 v82, v48, v57, v112
	v_fma_f32 v83, v49, v57, v113
	v_fma_f32 v56, v6, v66, v74
	v_fma_f32 v57, v7, v66, v75
	v_fma_f32 v74, v50, v58, v80
	v_fma_f32 v75, v51, v58, v81
	v_fma_f32 v80, v48, v58, v114
	v_fma_f32 v81, v49, v58, v115
	v_mov_b32_e32 v58, v67
	v_fmac_f32_e32 v64, v4, v66
	v_fmac_f32_e32 v65, v5, v66
	v_fma_f32 v66, v2, v58, v56
	v_fma_f32 v67, v3, v58, v57
	v_mov_b32_e32 v56, v59
	v_fmac_f32_e32 v64, v0, v58
	v_fmac_f32_e32 v65, v1, v58
	v_fma_f32 v112, v50, v56, v120
	v_fma_f32 v113, v51, v56, v121
	v_fma_f32 v114, v48, v56, v122
	v_fma_f32 v115, v49, v56, v123
	ds_read_b128 v[48:51], v162
	ds_read_b128 v[56:59], v162 offset:4096
	ds_read2_b32 v[120:121], v107 offset0:80 offset1:84
	v_add_co_u32_e32 v122, vcc, s0, v108
	s_waitcnt vmcnt(22) lgkmcnt(2)
; __device__ __forceinline__ void gla_sample_unit(const Args& a, unsigned char* lds, int unit, int tid) {
;     ...
;     for (int g = 0; g < 8; ++g) {
;         if (g + 1 < 8) {
; #pragma unroll
;             for (int i = 0; i < 8; ++i) sb[(g + 1) & 1][i] = *(const f32x4*)(S0 + (size_t)(((g + 1) * 8 + i) * 4 + kq) * 512 + vc); }
; #pragma unroll
;         for (int i = 0; i < 8; ++i) { const int k = (g * 8 + i) * 4 + kq; const f32x4 s = sb[g & 1][i];
;             const f32x4 qv = *(const f32x4*)(Q4 + k * 4), kd = *(const f32x4*)(KD4 + k * 4); const float dec = DECS[k];
;             f32x4 sn = s * dec;
; #pragma unroll
;             for (int t = 0; t < 4; ++t) { sn += vr[t] * kd[t]; o[t] += s * qv[t]; }
;             *(f32x4*)(SN + (size_t)k * 512 + vc) = sn; } }
	v_fmac_f32_e32 v116, v42, v48
	v_fmac_f32_e32 v117, v43, v48
	v_addc_co_u32_e32 v123, vcc, 0, v109, vcc
	global_store_dwordx4 v[122:123], v[64:67], off nt
	v_fmac_f32_e32 v118, v40, v48
	v_fmac_f32_e32 v119, v41, v48
	s_mov_b32 s0, 0xb628000
	s_waitcnt lgkmcnt(0)
	v_mul_f32_e32 v64, v42, v120
	v_mul_f32_e32 v65, v43, v120
	v_mul_f32_e32 v66, v40, v120
	v_mul_f32_e32 v67, v41, v120
	v_fmac_f32_e32 v64, v14, v56
	v_fmac_f32_e32 v65, v15, v56
	v_fmac_f32_e32 v66, v12, v56
	v_fmac_f32_e32 v67, v13, v56
	v_fmac_f32_e32 v64, v10, v57
	v_fmac_f32_e32 v65, v11, v57
	v_fma_f32 v56, v8, v57, v66
	v_fma_f32 v57, v9, v57, v67
	v_fma_f32 v66, v42, v49, v72
	v_fma_f32 v67, v43, v49, v73
	v_fma_f32 v72, v40, v49, v82
	v_fma_f32 v73, v41, v49, v83
	v_fma_f32 v48, v6, v58, v64
	v_fma_f32 v49, v7, v58, v65
	v_fma_f32 v64, v42, v50, v74
	v_fma_f32 v65, v43, v50, v75
	v_fma_f32 v74, v40, v50, v80
	v_fma_f32 v75, v41, v50, v81
	v_mov_b32_e32 v50, v59
	v_fmac_f32_e32 v56, v4, v58
	v_fmac_f32_e32 v57, v5, v58
	v_fma_f32 v58, v2, v50, v48
	v_fma_f32 v59, v3, v50, v49
	v_mov_b32_e32 v48, v51
	v_fmac_f32_e32 v56, v0, v50
	v_fmac_f32_e32 v57, v1, v50
	v_fma_f32 v80, v42, v48, v112
	v_fma_f32 v81, v43, v48, v113
	v_fma_f32 v82, v40, v48, v114
	v_fma_f32 v83, v41, v48, v115
	ds_read_b128 v[40:43], v163
	ds_read_b128 v[48:51], v163 offset:4096
	v_add_co_u32_e32 v112, vcc, s0, v108
	s_mov_b32 s0, 0xb62a000
	s_nop 0
	v_addc_co_u32_e32 v113, vcc, 0, v109, vcc
	global_store_dwordx4 v[112:113], v[56:59], off nt
	s_waitcnt vmcnt(23) lgkmcnt(1)
	v_fma_f32 v112, v34, v40, v116
	v_fma_f32 v113, v35, v40, v117
	v_fma_f32 v114, v32, v40, v118
	v_fma_f32 v115, v33, v40, v119
	v_mov_b32_e32 v56, v121
	v_mul_f32_e32 v58, v34, v56
	v_mul_f32_e32 v59, v35, v56
	v_mul_f32_e32 v57, v33, v56
	v_mul_f32_e32 v56, v32, v56
	s_waitcnt lgkmcnt(0)
	v_fmac_f32_e32 v58, v14, v48
	v_fmac_f32_e32 v59, v15, v48
	v_fmac_f32_e32 v56, v12, v48
	v_fmac_f32_e32 v57, v13, v48
	v_fmac_f32_e32 v58, v10, v49
	v_fmac_f32_e32 v59, v11, v49
	v_fma_f32 v48, v8, v49, v56
	v_fma_f32 v49, v9, v49, v57
	v_fma_f32 v56, v34, v41, v66
	v_fma_f32 v57, v35, v41, v67
	v_fma_f32 v66, v32, v41, v72
	v_fma_f32 v67, v33, v41, v73
	v_fma_f32 v40, v6, v50, v58
	v_fma_f32 v41, v7, v50, v59
	v_fma_f32 v58, v34, v42, v64
	v_fma_f32 v59, v35, v42, v65
	v_fma_f32 v64, v32, v42, v74
	v_fma_f32 v65, v33, v42, v75
	v_mov_b32_e32 v42, v51
	v_fmac_f32_e32 v48, v4, v50
	v_fmac_f32_e32 v49, v5, v50
	v_fma_f32 v50, v2, v42, v40
	v_fma_f32 v51, v3, v42, v41
	v_mov_b32_e32 v40, v43
	v_fmac_f32_e32 v48, v0, v42
	v_fmac_f32_e32 v49, v1, v42
	v_fma_f32 v72, v34, v40, v80
	v_fma_f32 v73, v35, v40, v81
	v_fma_f32 v74, v32, v40, v82
	v_fma_f32 v75, v33, v40, v83
	ds_read_b128 v[32:35], v164
	ds_read_b128 v[40:43], v164 offset:4096
	ds_read2_b32 v[80:81], v107 offset0:88 offset1:92
	v_add_co_u32_e32 v82, vcc, s0, v108
	s_mov_b32 s0, 0xb62c000
	s_nop 0
	v_addc_co_u32_e32 v83, vcc, 0, v109, vcc
	global_store_dwordx4 v[82:83], v[48:51], off nt
	s_waitcnt vmcnt(23) lgkmcnt(2)
	v_fma_f32 v82, v26, v32, v112
	v_fma_f32 v83, v27, v32, v113
	v_fma_f32 v112, v24, v32, v114
	v_fma_f32 v113, v25, v32, v115
	s_waitcnt lgkmcnt(0)
	v_mul_f32_e32 v48, v26, v80
	v_mul_f32_e32 v49, v27, v80
	v_mul_f32_e32 v50, v24, v80
	v_mul_f32_e32 v51, v25, v80
	v_fmac_f32_e32 v48, v14, v40
	v_fmac_f32_e32 v49, v15, v40
	v_fmac_f32_e32 v50, v12, v40
	v_fmac_f32_e32 v51, v13, v40
	v_fmac_f32_e32 v48, v10, v41
	v_fmac_f32_e32 v49, v11, v41
	v_fma_f32 v40, v8, v41, v50
	v_fma_f32 v41, v9, v41, v51
	v_fma_f32 v50, v26, v33, v56
	v_fma_f32 v51, v27, v33, v57
	v_fma_f32 v56, v24, v33, v66
	v_fma_f32 v57, v25, v33, v67
	v_fma_f32 v32, v6, v42, v48
	v_fma_f32 v33, v7, v42, v49
	v_fma_f32 v48, v26, v34, v58
	v_fma_f32 v49, v27, v34, v59
	v_fma_f32 v58, v24, v34, v64
	v_fma_f32 v59, v25, v34, v65
	v_mov_b32_e32 v34, v43
	v_fmac_f32_e32 v40, v4, v42
	v_fmac_f32_e32 v41, v5, v42
	v_fma_f32 v42, v2, v34, v32
	v_fma_f32 v43, v3, v34, v33
	v_mov_b32_e32 v32, v35
	v_fmac_f32_e32 v40, v0, v34
	v_fmac_f32_e32 v41, v1, v34
	v_fma_f32 v64, v26, v32, v72
	v_fma_f32 v65, v27, v32, v73
	v_fma_f32 v66, v24, v32, v74
	v_fma_f32 v67, v25, v32, v75
	ds_read_b128 v[24:27], v165
	ds_read_b128 v[32:35], v165 offset:4096
	v_add_co_u32_e32 v72, vcc, s0, v108
	s_mov_b32 s0, 0xb62e000
	s_nop 0
	v_addc_co_u32_e32 v73, vcc, 0, v109, vcc
	global_store_dwordx4 v[72:73], v[40:43], off nt
	s_waitcnt vmcnt(23) lgkmcnt(1)
	v_fma_f32 v114, v16, v25, v56
	v_fma_f32 v115, v17, v25, v57
	v_fma_f32 v116, v18, v26, v48
	v_fma_f32 v117, v19, v26, v49
	v_mov_b32_e32 v40, v81
	v_mul_f32_e32 v42, v18, v40
	v_mul_f32_e32 v43, v19, v40
	v_mul_f32_e32 v41, v17, v40
	v_mul_f32_e32 v40, v16, v40
	s_waitcnt lgkmcnt(0)
; __device__ __forceinline__ void gla_sample_unit(const Args& a, unsigned char* lds, int unit, int tid) {
;     ...
;     for (int g = 0; g < 8; ++g) {
;         if (g + 1 < 8) {
; #pragma unroll
;             for (int i = 0; i < 8; ++i) sb[(g + 1) & 1][i] = *(const f32x4*)(S0 + (size_t)(((g + 1) * 8 + i) * 4 + kq) * 512 + vc); }
; #pragma unroll
;         for (int i = 0; i < 8; ++i) { const int k = (g * 8 + i) * 4 + kq; const f32x4 s = sb[g & 1][i];
;             const f32x4 qv = *(const f32x4*)(Q4 + k * 4), kd = *(const f32x4*)(KD4 + k * 4); const float dec = DECS[k];
;             f32x4 sn = s * dec;
; #pragma unroll
;             for (int t = 0; t < 4; ++t) { sn += vr[t] * kd[t]; o[t] += s * qv[t]; }
;             *(f32x4*)(SN + (size_t)k * 512 + vc) = sn; } }
	v_fmac_f32_e32 v42, v14, v32
	v_fmac_f32_e32 v43, v15, v32
	v_fmac_f32_e32 v40, v12, v32
	v_fmac_f32_e32 v41, v13, v32
	v_fmac_f32_e32 v42, v10, v33
	v_fmac_f32_e32 v43, v11, v33
	v_fma_f32 v80, v18, v24, v82
	v_fma_f32 v81, v19, v24, v83
	v_fma_f32 v82, v16, v24, v112
	v_fma_f32 v83, v17, v24, v113
	v_fma_f32 v32, v8, v33, v40
	v_fma_f32 v33, v9, v33, v41
	v_fma_f32 v112, v18, v25, v50
	v_fma_f32 v113, v19, v25, v51
	v_fma_f32 v24, v6, v34, v42
	v_fma_f32 v25, v7, v34, v43
	v_fma_f32 v118, v16, v26, v58
	v_fma_f32 v119, v17, v26, v59
	v_mov_b32_e32 v26, v35
	v_fmac_f32_e32 v32, v4, v34
	v_fmac_f32_e32 v33, v5, v34
	v_fma_f32 v34, v2, v26, v24
	v_fma_f32 v35, v3, v26, v25
	v_mov_b32_e32 v24, v27
	v_fma_f32 v122, v16, v24, v66
	v_fma_f32 v123, v17, v24, v67
	v_add_co_u32_e32 v16, vcc, s0, v108
	v_fmac_f32_e32 v32, v0, v26
	v_fmac_f32_e32 v33, v1, v26
	s_nop 0
	v_addc_co_u32_e32 v17, vcc, 0, v109, vcc
	s_mov_b32 s0, 0x40000
	global_store_dwordx4 v[16:17], v[32:35], off nt
	v_add_co_u32_e32 v16, vcc, s0, v110
	s_mov_b32 s0, 0x42000
	s_nop 0
	v_addc_co_u32_e32 v17, vcc, 0, v111, vcc
	v_fma_f32 v120, v18, v24, v64
	v_fma_f32 v121, v19, v24, v65
	v_add_co_u32_e32 v18, vcc, s0, v110
	s_mov_b32 s0, 0x44000
	s_nop 0
	v_addc_co_u32_e32 v19, vcc, 0, v111, vcc
	global_load_dwordx4 v[72:75], v[16:17], off nt
	global_load_dwordx4 v[64:67], v[18:19], off nt
	v_add_co_u32_e32 v16, vcc, s0, v110
	s_mov_b32 s0, 0x46000
	s_nop 0
	v_addc_co_u32_e32 v17, vcc, 0, v111, vcc
	v_add_co_u32_e32 v18, vcc, s0, v110
	s_mov_b32 s0, 0x48000
	s_nop 0
	v_addc_co_u32_e32 v19, vcc, 0, v111, vcc
	global_load_dwordx4 v[56:59], v[16:17], off nt
	global_load_dwordx4 v[48:51], v[18:19], off nt
	v_add_co_u32_e32 v16, vcc, s0, v110
	s_mov_b32 s0, 0x4a000
	s_nop 0
	v_addc_co_u32_e32 v17, vcc, 0, v111, vcc
	v_add_co_u32_e32 v18, vcc, s0, v110
	s_mov_b32 s0, 0x4c000
	s_nop 0
	v_addc_co_u32_e32 v19, vcc, 0, v111, vcc
	global_load_dwordx4 v[40:43], v[16:17], off nt
	global_load_dwordx4 v[32:35], v[18:19], off nt
	ds_read2_b32 v[230:231], v107 offset0:96 offset1:100
	ds_read_b128 v[222:225], v166
	ds_read_b128 v[226:229], v166 offset:4096
	v_add_co_u32_e32 v16, vcc, s0, v110
	s_waitcnt vmcnt(21) lgkmcnt(2)
	v_mul_f32_e32 v232, v78, v230
	v_mul_f32_e32 v233, v79, v230
	v_mul_f32_e32 v234, v76, v230
	v_mul_f32_e32 v235, v77, v230
	s_waitcnt lgkmcnt(0)
	v_fmac_f32_e32 v232, v14, v226
	v_fmac_f32_e32 v233, v15, v226
	v_fmac_f32_e32 v234, v12, v226
	v_fmac_f32_e32 v235, v13, v226
	v_addc_co_u32_e32 v17, vcc, 0, v111, vcc
	s_mov_b32 s0, 0x4e000
	v_fma_f32 v236, v78, v222, v80
	v_fma_f32 v237, v79, v222, v81
	v_fma_f32 v238, v76, v222, v82
	v_fma_f32 v239, v77, v222, v83
	v_fma_f32 v80, v10, v227, v232
	v_fma_f32 v81, v11, v227, v233
	v_fma_f32 v82, v8, v227, v234
	v_fma_f32 v83, v9, v227, v235
	v_add_co_u32_e32 v18, vcc, s0, v110
	v_fmac_f32_e32 v112, v78, v223
	v_fmac_f32_e32 v113, v79, v223
	v_fma_f32 v222, v76, v223, v114
	v_fma_f32 v223, v77, v223, v115
	v_fmac_f32_e32 v80, v6, v228
	v_fmac_f32_e32 v81, v7, v228
	v_fma_f32 v114, v4, v228, v82
	v_fma_f32 v115, v5, v228, v83
	v_fma_f32 v226, v78, v224, v116
	v_fma_f32 v227, v79, v224, v117
	v_mov_b32_e32 v116, v229
	v_addc_co_u32_e32 v19, vcc, 0, v111, vcc
	v_fma_f32 v82, v2, v116, v80
	v_fma_f32 v83, v3, v116, v81
	v_fma_f32 v80, v0, v116, v114
	v_fma_f32 v81, v1, v116, v115
	v_mov_b32_e32 v114, v225
	global_load_dwordx4 v[24:27], v[16:17], off nt
	s_nop 0
	global_load_dwordx4 v[16:19], v[18:19], off nt
	v_fma_f32 v232, v76, v224, v118
	v_fma_f32 v233, v77, v224, v119
	v_fma_f32 v224, v78, v114, v120
	v_fma_f32 v225, v79, v114, v121
	v_fmac_f32_e32 v122, v76, v114
	v_fmac_f32_e32 v123, v77, v114
	s_mov_b32 s0, 0xb630000
	ds_read_b128 v[114:117], v167
	ds_read_b128 v[118:121], v167 offset:4096
	v_add_co_u32_e32 v76, vcc, s0, v108
	s_mov_b32 s0, 0xb632000
	s_nop 0
	v_addc_co_u32_e32 v77, vcc, 0, v109, vcc
	global_store_dwordx4 v[76:77], v[80:83], off nt
	v_mov_b32_e32 v76, v231
	s_waitcnt vmcnt(23)
	v_mul_f32_e32 v78, v70, v76
	v_mul_f32_e32 v79, v71, v76
	v_mul_f32_e32 v77, v69, v76
	v_mul_f32_e32 v76, v68, v76
	s_waitcnt lgkmcnt(0)
	v_fma_f32 v80, v14, v118, v78
	v_fma_f32 v81, v15, v118, v79
	v_fma_f32 v82, v12, v118, v76
	v_fma_f32 v83, v13, v118, v77
	v_fma_f32 v228, v10, v119, v80
	v_fma_f32 v229, v11, v119, v81
	v_fma_f32 v118, v8, v119, v82
	v_fma_f32 v119, v9, v119, v83
	v_fma_f32 v76, v70, v114, v236
	v_fma_f32 v77, v71, v114, v237
	v_fma_f32 v78, v68, v114, v238
	v_fma_f32 v79, v69, v114, v239
	v_fma_f32 v80, v70, v115, v112
	v_fma_f32 v81, v71, v115, v113
	v_fma_f32 v82, v68, v115, v222
	v_fma_f32 v83, v69, v115, v223
	v_fma_f32 v222, v6, v120, v228
	v_fma_f32 v223, v7, v120, v229
	v_fmac_f32_e32 v118, v4, v120
	v_fmac_f32_e32 v119, v5, v120
	v_fma_f32 v112, v70, v116, v226
	v_fma_f32 v113, v71, v116, v227
	v_fma_f32 v114, v68, v116, v232
	v_fma_f32 v115, v69, v116, v233
	v_mov_b32_e32 v116, v121
	v_fma_f32 v120, v2, v116, v222
	v_fma_f32 v121, v3, v116, v223
	v_fmac_f32_e32 v118, v0, v116
	v_fmac_f32_e32 v119, v1, v116
	v_mov_b32_e32 v116, v117
	v_fma_f32 v70, v70, v116, v224
	v_fma_f32 v71, v71, v116, v225
	v_fma_f32 v68, v68, v116, v122
	v_fma_f32 v69, v69, v116, v123
	ds_read_b128 v[222:225], v168
	ds_read_b128 v[226:229], v168 offset:4096
	ds_read2_b32 v[116:117], v107 offset0:104 offset1:108
	v_add_co_u32_e32 v122, vcc, s0, v108
	s_waitcnt vmcnt(22) lgkmcnt(2)
	v_fma_f32 v230, v60, v222, v78
	v_fma_f32 v231, v61, v222, v79
	v_addc_co_u32_e32 v123, vcc, 0, v109, vcc
	global_store_dwordx4 v[122:123], v[118:121], off nt
	v_fma_f32 v122, v62, v222, v76
	v_fma_f32 v123, v63, v222, v77
	v_fmac_f32_e32 v80, v62, v223
	v_fmac_f32_e32 v81, v63, v223
	s_waitcnt lgkmcnt(0)
; __device__ __forceinline__ void gla_sample_unit(const Args& a, unsigned char* lds, int unit, int tid) {
;     ...
;     for (int g = 0; g < 8; ++g) {
;         if (g + 1 < 8) {
; #pragma unroll
;             for (int i = 0; i < 8; ++i) sb[(g + 1) & 1][i] = *(const f32x4*)(S0 + (size_t)(((g + 1) * 8 + i) * 4 + kq) * 512 + vc); }
; #pragma unroll
;         for (int i = 0; i < 8; ++i) { const int k = (g * 8 + i) * 4 + kq; const f32x4 s = sb[g & 1][i];
;             const f32x4 qv = *(const f32x4*)(Q4 + k * 4), kd = *(const f32x4*)(KD4 + k * 4); const float dec = DECS[k];
;             f32x4 sn = s * dec;
; #pragma unroll
;             for (int t = 0; t < 4; ++t) { sn += vr[t] * kd[t]; o[t] += s * qv[t]; }
;             *(f32x4*)(SN + (size_t)k * 512 + vc) = sn; } }
	v_mul_f32_e32 v118, v62, v116
	v_mul_f32_e32 v119, v63, v116
	v_mul_f32_e32 v120, v60, v116
	v_mul_f32_e32 v121, v61, v116
	v_fmac_f32_e32 v118, v14, v226
	v_fmac_f32_e32 v119, v15, v226
	v_fmac_f32_e32 v120, v12, v226
	v_fmac_f32_e32 v121, v13, v226
	v_fma_f32 v76, v10, v227, v118
	v_fma_f32 v77, v11, v227, v119
	v_fma_f32 v78, v8, v227, v120
	v_fma_f32 v79, v9, v227, v121
	v_fmac_f32_e32 v76, v6, v228
	v_fmac_f32_e32 v77, v7, v228
	v_fma_f32 v118, v4, v228, v78
	v_fma_f32 v119, v5, v228, v79
	v_mov_b32_e32 v116, v229
	v_fma_f32 v78, v2, v116, v76
	v_fma_f32 v79, v3, v116, v77
	v_fma_f32 v76, v0, v116, v118
	v_fma_f32 v77, v1, v116, v119
	v_mov_b32_e32 v116, v225
	v_fmac_f32_e32 v82, v60, v223
	v_fmac_f32_e32 v83, v61, v223
	v_fmac_f32_e32 v112, v62, v224
	v_fmac_f32_e32 v113, v63, v224
	v_fmac_f32_e32 v114, v60, v224
	v_fmac_f32_e32 v115, v61, v224
	v_fma_f32 v118, v62, v116, v70
	v_fma_f32 v119, v63, v116, v71
	v_fma_f32 v120, v60, v116, v68
	v_fma_f32 v121, v61, v116, v69
	s_mov_b32 s0, 0xb634000
	ds_read_b128 v[60:63], v169
	ds_read_b128 v[68:71], v169 offset:4096
	v_add_co_u32_e32 v222, vcc, s0, v108
	s_mov_b32 s0, 0xb636000
	s_nop 0
	v_addc_co_u32_e32 v223, vcc, 0, v109, vcc
	global_store_dwordx4 v[222:223], v[76:79], off nt
	s_nop 1
	v_mov_b32_e32 v76, v117
	s_waitcnt vmcnt(23)
	v_mul_f32_e32 v78, v54, v76
	v_mul_f32_e32 v79, v55, v76
	v_mul_f32_e32 v77, v53, v76
	v_mul_f32_e32 v76, v52, v76
	s_waitcnt lgkmcnt(0)
	v_fmac_f32_e32 v78, v14, v68
	v_fmac_f32_e32 v79, v15, v68
	v_fmac_f32_e32 v76, v12, v68
	v_fmac_f32_e32 v77, v13, v68
	v_fmac_f32_e32 v78, v10, v69
	v_fmac_f32_e32 v79, v11, v69
	v_fma_f32 v116, v54, v60, v122
	v_fma_f32 v117, v55, v60, v123
	v_fma_f32 v122, v52, v60, v230
	v_fma_f32 v123, v53, v60, v231
	v_fma_f32 v68, v8, v69, v76
	v_fma_f32 v69, v9, v69, v77
	v_fma_f32 v76, v54, v61, v80
	v_fma_f32 v77, v55, v61, v81
	v_fma_f32 v80, v52, v61, v82
	v_fma_f32 v81, v53, v61, v83
	v_fma_f32 v60, v6, v70, v78
	v_fma_f32 v61, v7, v70, v79
	v_fma_f32 v78, v54, v62, v112
	v_fma_f32 v79, v55, v62, v113
	v_fma_f32 v82, v52, v62, v114
	v_fma_f32 v83, v53, v62, v115
	v_mov_b32_e32 v62, v71
	v_fmac_f32_e32 v68, v4, v70
	v_fmac_f32_e32 v69, v5, v70
	v_fma_f32 v70, v2, v62, v60
	v_fma_f32 v71, v3, v62, v61
	v_mov_b32_e32 v60, v63
	v_fmac_f32_e32 v68, v0, v62
	v_fmac_f32_e32 v69, v1, v62
	v_fma_f32 v112, v54, v60, v118
	v_fma_f32 v113, v55, v60, v119
	v_fma_f32 v114, v52, v60, v120
	v_fma_f32 v115, v53, v60, v121
	ds_read_b128 v[52:55], v170
	ds_read_b128 v[60:63], v170 offset:4096
	ds_read2_b32 v[118:119], v107 offset0:112 offset1:116
	v_add_co_u32_e32 v120, vcc, s0, v108
	s_waitcnt vmcnt(22) lgkmcnt(2)
	v_fmac_f32_e32 v116, v46, v52
	v_fmac_f32_e32 v117, v47, v52
	v_addc_co_u32_e32 v121, vcc, 0, v109, vcc
	global_store_dwordx4 v[120:121], v[68:71], off nt
	v_fma_f32 v120, v44, v52, v122
	v_fma_f32 v121, v45, v52, v123
	s_mov_b32 s0, 0xb638000
	s_waitcnt lgkmcnt(0)
	v_mul_f32_e32 v68, v46, v118
	v_mul_f32_e32 v69, v47, v118
	v_mul_f32_e32 v70, v44, v118
	v_mul_f32_e32 v71, v45, v118
	v_fmac_f32_e32 v68, v14, v60
	v_fmac_f32_e32 v69, v15, v60
	v_fmac_f32_e32 v70, v12, v60
	v_fmac_f32_e32 v71, v13, v60
	v_fmac_f32_e32 v68, v10, v61
	v_fmac_f32_e32 v69, v11, v61
	v_fma_f32 v60, v8, v61, v70
	v_fma_f32 v61, v9, v61, v71
	v_fma_f32 v70, v46, v53, v76
	v_fma_f32 v71, v47, v53, v77
	v_fma_f32 v76, v44, v53, v80
	v_fma_f32 v77, v45, v53, v81
	v_fma_f32 v52, v6, v62, v68
	v_fma_f32 v53, v7, v62, v69
	v_fma_f32 v68, v46, v54, v78
	v_fma_f32 v69, v47, v54, v79
	v_fma_f32 v78, v44, v54, v82
	v_fma_f32 v79, v45, v54, v83
	v_mov_b32_e32 v54, v63
	v_fmac_f32_e32 v60, v4, v62
	v_fmac_f32_e32 v61, v5, v62
	v_fma_f32 v62, v2, v54, v52
	v_fma_f32 v63, v3, v54, v53
	v_mov_b32_e32 v52, v55
	v_fmac_f32_e32 v60, v0, v54
	v_fmac_f32_e32 v61, v1, v54
	v_fma_f32 v80, v46, v52, v112
	v_fma_f32 v81, v47, v52, v113
	v_fma_f32 v82, v44, v52, v114
	v_fma_f32 v83, v45, v52, v115
	ds_read_b128 v[44:47], v171
	ds_read_b128 v[52:55], v171 offset:4096
	v_add_co_u32_e32 v112, vcc, s0, v108
	s_mov_b32 s0, 0xb63a000
	s_nop 0
	v_addc_co_u32_e32 v113, vcc, 0, v109, vcc
	global_store_dwordx4 v[112:113], v[60:63], off nt
	s_waitcnt vmcnt(23) lgkmcnt(1)
	v_fma_f32 v112, v38, v44, v116
	v_fma_f32 v113, v39, v44, v117
	v_fma_f32 v114, v36, v44, v120
	v_fma_f32 v115, v37, v44, v121
	v_mov_b32_e32 v60, v119
	v_mul_f32_e32 v62, v38, v60
	v_mul_f32_e32 v63, v39, v60
	v_mul_f32_e32 v61, v37, v60
	v_mul_f32_e32 v60, v36, v60
	s_waitcnt lgkmcnt(0)
	v_fmac_f32_e32 v62, v14, v52
	v_fmac_f32_e32 v63, v15, v52
	v_fmac_f32_e32 v60, v12, v52
	v_fmac_f32_e32 v61, v13, v52
	v_fmac_f32_e32 v62, v10, v53
	v_fmac_f32_e32 v63, v11, v53
	v_fma_f32 v52, v8, v53, v60
	v_fma_f32 v53, v9, v53, v61
	v_fma_f32 v60, v38, v45, v70
	v_fma_f32 v61, v39, v45, v71
	v_fma_f32 v70, v36, v45, v76
	v_fma_f32 v71, v37, v45, v77
	v_fma_f32 v44, v6, v54, v62
	v_fma_f32 v45, v7, v54, v63
	v_fma_f32 v62, v38, v46, v68
	v_fma_f32 v63, v39, v46, v69
	v_fma_f32 v68, v36, v46, v78
	v_fma_f32 v69, v37, v46, v79
	v_mov_b32_e32 v46, v55
	v_fmac_f32_e32 v52, v4, v54
	v_fmac_f32_e32 v53, v5, v54
	v_fma_f32 v54, v2, v46, v44
	v_fma_f32 v55, v3, v46, v45
	v_mov_b32_e32 v44, v47
	v_fmac_f32_e32 v52, v0, v46
	v_fmac_f32_e32 v53, v1, v46
	v_fma_f32 v76, v38, v44, v80
	v_fma_f32 v77, v39, v44, v81
	v_fma_f32 v78, v36, v44, v82
	v_fma_f32 v79, v37, v44, v83
	ds_read_b128 v[36:39], v172
	ds_read_b128 v[44:47], v172 offset:4096
	ds_read2_b32 v[80:81], v107 offset0:120 offset1:124
	v_add_co_u32_e32 v82, vcc, s0, v108
	s_mov_b32 s0, 0xb63c000
	s_nop 0
	v_addc_co_u32_e32 v83, vcc, 0, v109, vcc
	global_store_dwordx4 v[82:83], v[52:55], off nt
	s_waitcnt vmcnt(23) lgkmcnt(2)
; __device__ __forceinline__ void gla_sample_unit(const Args& a, unsigned char* lds, int unit, int tid) {
;     ...
;     for (int g = 0; g < 8; ++g) {
;         if (g + 1 < 8) {
; #pragma unroll
;             for (int i = 0; i < 8; ++i) sb[(g + 1) & 1][i] = *(const f32x4*)(S0 + (size_t)(((g + 1) * 8 + i) * 4 + kq) * 512 + vc); }
; #pragma unroll
;         for (int i = 0; i < 8; ++i) { const int k = (g * 8 + i) * 4 + kq; const f32x4 s = sb[g & 1][i];
;             const f32x4 qv = *(const f32x4*)(Q4 + k * 4), kd = *(const f32x4*)(KD4 + k * 4); const float dec = DECS[k];
;             f32x4 sn = s * dec;
; #pragma unroll
;             for (int t = 0; t < 4; ++t) { sn += vr[t] * kd[t]; o[t] += s * qv[t]; }
;             *(f32x4*)(SN + (size_t)k * 512 + vc) = sn; } }
	v_fma_f32 v82, v30, v36, v112
	v_fma_f32 v83, v31, v36, v113
	v_fma_f32 v112, v28, v36, v114
	v_fma_f32 v113, v29, v36, v115
	s_waitcnt lgkmcnt(0)
	v_mul_f32_e32 v52, v30, v80
	v_mul_f32_e32 v53, v31, v80
	v_mul_f32_e32 v54, v28, v80
	v_mul_f32_e32 v55, v29, v80
	v_fmac_f32_e32 v52, v14, v44
	v_fmac_f32_e32 v53, v15, v44
	v_fmac_f32_e32 v54, v12, v44
	v_fmac_f32_e32 v55, v13, v44
	v_fmac_f32_e32 v52, v10, v45
	v_fmac_f32_e32 v53, v11, v45
	v_fma_f32 v44, v8, v45, v54
	v_fma_f32 v45, v9, v45, v55
	v_fma_f32 v54, v30, v37, v60
	v_fma_f32 v55, v31, v37, v61
	v_fma_f32 v60, v28, v37, v70
	v_fma_f32 v61, v29, v37, v71
	v_fma_f32 v36, v6, v46, v52
	v_fma_f32 v37, v7, v46, v53
	v_fma_f32 v52, v30, v38, v62
	v_fma_f32 v53, v31, v38, v63
	v_fma_f32 v62, v28, v38, v68
	v_fma_f32 v63, v29, v38, v69
	v_mov_b32_e32 v38, v47
	v_fmac_f32_e32 v44, v4, v46
	v_fmac_f32_e32 v45, v5, v46
	v_fma_f32 v46, v2, v38, v36
	v_fma_f32 v47, v3, v38, v37
	v_mov_b32_e32 v36, v39
	v_fmac_f32_e32 v44, v0, v38
	v_fmac_f32_e32 v45, v1, v38
	v_fma_f32 v68, v30, v36, v76
	v_fma_f32 v69, v31, v36, v77
	v_fma_f32 v70, v28, v36, v78
	v_fma_f32 v71, v29, v36, v79
	ds_read_b128 v[28:31], v173
	ds_read_b128 v[36:39], v173 offset:4096
	v_add_co_u32_e32 v76, vcc, s0, v108
	s_mov_b32 s0, 0xb63e000
	s_nop 0
	v_addc_co_u32_e32 v77, vcc, 0, v109, vcc
	global_store_dwordx4 v[76:77], v[44:47], off nt
	s_waitcnt vmcnt(23) lgkmcnt(1)
	v_fma_f32 v114, v20, v29, v60
	v_fma_f32 v115, v21, v29, v61
	v_fma_f32 v116, v22, v30, v52
	v_fma_f32 v117, v23, v30, v53
	v_mov_b32_e32 v44, v81
	v_mul_f32_e32 v46, v22, v44
	v_mul_f32_e32 v47, v23, v44
	v_mul_f32_e32 v45, v21, v44
	v_mul_f32_e32 v44, v20, v44
	s_waitcnt lgkmcnt(0)
	v_fmac_f32_e32 v46, v14, v36
	v_fmac_f32_e32 v47, v15, v36
	v_fmac_f32_e32 v44, v12, v36
	v_fmac_f32_e32 v45, v13, v36
	v_fmac_f32_e32 v46, v10, v37
	v_fmac_f32_e32 v47, v11, v37
	v_fma_f32 v80, v22, v28, v82
	v_fma_f32 v81, v23, v28, v83
	v_fma_f32 v82, v20, v28, v112
	v_fma_f32 v83, v21, v28, v113
	v_fma_f32 v36, v8, v37, v44
	v_fma_f32 v37, v9, v37, v45
	v_fma_f32 v112, v22, v29, v54
	v_fma_f32 v113, v23, v29, v55
	v_fma_f32 v28, v6, v38, v46
	v_fma_f32 v29, v7, v38, v47
	v_fma_f32 v118, v20, v30, v62
	v_fma_f32 v119, v21, v30, v63
	v_mov_b32_e32 v30, v39
	v_fmac_f32_e32 v36, v4, v38
	v_fmac_f32_e32 v37, v5, v38
	v_fma_f32 v38, v2, v30, v28
	v_fma_f32 v39, v3, v30, v29
	v_mov_b32_e32 v28, v31
	v_fma_f32 v122, v20, v28, v70
	v_fma_f32 v123, v21, v28, v71
	v_add_co_u32_e32 v20, vcc, s0, v108
	v_fmac_f32_e32 v36, v0, v30
	v_fmac_f32_e32 v37, v1, v30
	s_nop 0
	v_addc_co_u32_e32 v21, vcc, 0, v109, vcc
	s_mov_b32 s0, 0x50000
	global_store_dwordx4 v[20:21], v[36:39], off nt
	v_add_co_u32_e32 v20, vcc, s0, v110
	s_mov_b32 s0, 0x52000
	s_nop 0
	v_addc_co_u32_e32 v21, vcc, 0, v111, vcc
	v_fma_f32 v120, v22, v28, v68
	v_fma_f32 v121, v23, v28, v69
	v_add_co_u32_e32 v22, vcc, s0, v110
	s_mov_b32 s0, 0x54000
	s_nop 0
	v_addc_co_u32_e32 v23, vcc, 0, v111, vcc
	global_load_dwordx4 v[76:79], v[20:21], off nt
	global_load_dwordx4 v[68:71], v[22:23], off nt
	v_add_co_u32_e32 v20, vcc, s0, v110
	s_mov_b32 s0, 0x56000
	s_nop 0
	v_addc_co_u32_e32 v21, vcc, 0, v111, vcc
	v_add_co_u32_e32 v22, vcc, s0, v110
	s_mov_b32 s0, 0x58000
	s_nop 0
	v_addc_co_u32_e32 v23, vcc, 0, v111, vcc
	global_load_dwordx4 v[60:63], v[20:21], off nt
	global_load_dwordx4 v[52:55], v[22:23], off nt
	v_add_co_u32_e32 v20, vcc, s0, v110
	s_mov_b32 s0, 0x5a000
	s_nop 0
	v_addc_co_u32_e32 v21, vcc, 0, v111, vcc
	v_add_co_u32_e32 v22, vcc, s0, v110
	s_mov_b32 s0, 0x5c000
	s_nop 0
	v_addc_co_u32_e32 v23, vcc, 0, v111, vcc
	global_load_dwordx4 v[44:47], v[20:21], off nt
	global_load_dwordx4 v[36:39], v[22:23], off nt
	ds_read2_b32 v[230:231], v107 offset0:128 offset1:132
	ds_read_b128 v[222:225], v174
	ds_read_b128 v[226:229], v174 offset:4096
	v_add_co_u32_e32 v20, vcc, s0, v110
	s_waitcnt vmcnt(21) lgkmcnt(2)
	v_mul_f32_e32 v232, v74, v230
	v_mul_f32_e32 v233, v75, v230
	v_mul_f32_e32 v234, v72, v230
	v_mul_f32_e32 v235, v73, v230
	s_waitcnt lgkmcnt(0)
	v_fmac_f32_e32 v232, v14, v226
	v_fmac_f32_e32 v233, v15, v226
	v_fmac_f32_e32 v234, v12, v226
	v_fmac_f32_e32 v235, v13, v226
	v_addc_co_u32_e32 v21, vcc, 0, v111, vcc
	s_mov_b32 s0, 0x5e000
	v_fma_f32 v236, v74, v222, v80
	v_fma_f32 v237, v75, v222, v81
	v_fma_f32 v238, v72, v222, v82
	v_fma_f32 v239, v73, v222, v83
	v_fma_f32 v80, v10, v227, v232
	v_fma_f32 v81, v11, v227, v233
	v_fma_f32 v82, v8, v227, v234
	v_fma_f32 v83, v9, v227, v235
	v_add_co_u32_e32 v22, vcc, s0, v110
	v_fmac_f32_e32 v112, v74, v223
	v_fmac_f32_e32 v113, v75, v223
	v_fma_f32 v222, v72, v223, v114
	v_fma_f32 v223, v73, v223, v115
	v_fmac_f32_e32 v80, v6, v228
	v_fmac_f32_e32 v81, v7, v228
	v_fma_f32 v114, v4, v228, v82
	v_fma_f32 v115, v5, v228, v83
	v_fma_f32 v226, v74, v224, v116
	v_fma_f32 v227, v75, v224, v117
	v_mov_b32_e32 v116, v229
	v_addc_co_u32_e32 v23, vcc, 0, v111, vcc
	v_fma_f32 v82, v2, v116, v80
	v_fma_f32 v83, v3, v116, v81
	v_fma_f32 v80, v0, v116, v114
	v_fma_f32 v81, v1, v116, v115
	v_mov_b32_e32 v114, v225
	global_load_dwordx4 v[28:31], v[20:21], off nt
	s_nop 0
	global_load_dwordx4 v[20:23], v[22:23], off nt
	v_fma_f32 v232, v72, v224, v118
	v_fma_f32 v233, v73, v224, v119
	v_fma_f32 v224, v74, v114, v120
	v_fma_f32 v225, v75, v114, v121
	v_fmac_f32_e32 v122, v72, v114
	v_fmac_f32_e32 v123, v73, v114
	s_mov_b32 s0, 0xb640000
	ds_read_b128 v[114:117], v175
	ds_read_b128 v[118:121], v175 offset:4096
	v_add_co_u32_e32 v72, vcc, s0, v108
	s_mov_b32 s0, 0xb642000
	s_nop 0
	v_addc_co_u32_e32 v73, vcc, 0, v109, vcc
	global_store_dwordx4 v[72:73], v[80:83], off nt
	v_mov_b32_e32 v72, v231
	s_waitcnt vmcnt(23)
; __device__ __forceinline__ void gla_sample_unit(const Args& a, unsigned char* lds, int unit, int tid) {
;     ...
;     for (int g = 0; g < 8; ++g) {
;         if (g + 1 < 8) {
; #pragma unroll
;             for (int i = 0; i < 8; ++i) sb[(g + 1) & 1][i] = *(const f32x4*)(S0 + (size_t)(((g + 1) * 8 + i) * 4 + kq) * 512 + vc); }
; #pragma unroll
;         for (int i = 0; i < 8; ++i) { const int k = (g * 8 + i) * 4 + kq; const f32x4 s = sb[g & 1][i];
;             const f32x4 qv = *(const f32x4*)(Q4 + k * 4), kd = *(const f32x4*)(KD4 + k * 4); const float dec = DECS[k];
;             f32x4 sn = s * dec;
; #pragma unroll
;             for (int t = 0; t < 4; ++t) { sn += vr[t] * kd[t]; o[t] += s * qv[t]; }
;             *(f32x4*)(SN + (size_t)k * 512 + vc) = sn; } }
	v_mul_f32_e32 v74, v66, v72
	v_mul_f32_e32 v75, v67, v72
	v_mul_f32_e32 v73, v65, v72
	v_mul_f32_e32 v72, v64, v72
	s_waitcnt lgkmcnt(0)
	v_fma_f32 v80, v14, v118, v74
	v_fma_f32 v81, v15, v118, v75
	v_fma_f32 v82, v12, v118, v72
	v_fma_f32 v83, v13, v118, v73
	v_fma_f32 v228, v10, v119, v80
	v_fma_f32 v229, v11, v119, v81
	v_fma_f32 v118, v8, v119, v82
	v_fma_f32 v119, v9, v119, v83
	v_fma_f32 v72, v66, v114, v236
	v_fma_f32 v73, v67, v114, v237
	v_fma_f32 v74, v64, v114, v238
	v_fma_f32 v75, v65, v114, v239
	v_fma_f32 v80, v66, v115, v112
	v_fma_f32 v81, v67, v115, v113
	v_fma_f32 v82, v64, v115, v222
	v_fma_f32 v83, v65, v115, v223
	v_fma_f32 v222, v6, v120, v228
	v_fma_f32 v223, v7, v120, v229
	v_fmac_f32_e32 v118, v4, v120
	v_fmac_f32_e32 v119, v5, v120
	v_fma_f32 v112, v66, v116, v226
	v_fma_f32 v113, v67, v116, v227
	v_fma_f32 v114, v64, v116, v232
	v_fma_f32 v115, v65, v116, v233
	v_mov_b32_e32 v116, v121
	v_fma_f32 v120, v2, v116, v222
	v_fma_f32 v121, v3, v116, v223
	v_fmac_f32_e32 v118, v0, v116
	v_fmac_f32_e32 v119, v1, v116
	v_mov_b32_e32 v116, v117
	v_fma_f32 v66, v66, v116, v224
	v_fma_f32 v67, v67, v116, v225
	v_fma_f32 v64, v64, v116, v122
	v_fma_f32 v65, v65, v116, v123
	ds_read_b128 v[222:225], v176
	ds_read_b128 v[226:229], v176 offset:4096
	ds_read2_b32 v[116:117], v107 offset0:136 offset1:140
	v_add_co_u32_e32 v122, vcc, s0, v108
	s_waitcnt vmcnt(22) lgkmcnt(2)
	v_fma_f32 v230, v56, v222, v74
	v_fma_f32 v231, v57, v222, v75
	v_addc_co_u32_e32 v123, vcc, 0, v109, vcc
	global_store_dwordx4 v[122:123], v[118:121], off nt
	v_fma_f32 v122, v58, v222, v72
	v_fma_f32 v123, v59, v222, v73
	v_fmac_f32_e32 v80, v58, v223
	v_fmac_f32_e32 v81, v59, v223
	s_waitcnt lgkmcnt(0)
	v_mul_f32_e32 v118, v58, v116
	v_mul_f32_e32 v119, v59, v116
	v_mul_f32_e32 v120, v56, v116
	v_mul_f32_e32 v121, v57, v116
	v_fmac_f32_e32 v118, v14, v226
	v_fmac_f32_e32 v119, v15, v226
	v_fmac_f32_e32 v120, v12, v226
	v_fmac_f32_e32 v121, v13, v226
	v_fma_f32 v72, v10, v227, v118
	v_fma_f32 v73, v11, v227, v119
	v_fma_f32 v74, v8, v227, v120
	v_fma_f32 v75, v9, v227, v121
	v_fmac_f32_e32 v72, v6, v228
	v_fmac_f32_e32 v73, v7, v228
	v_fma_f32 v118, v4, v228, v74
	v_fma_f32 v119, v5, v228, v75
	v_mov_b32_e32 v116, v229
	v_fma_f32 v74, v2, v116, v72
	v_fma_f32 v75, v3, v116, v73
	v_fma_f32 v72, v0, v116, v118
	v_fma_f32 v73, v1, v116, v119
	v_mov_b32_e32 v116, v225
	v_fmac_f32_e32 v82, v56, v223
	v_fmac_f32_e32 v83, v57, v223
	v_fmac_f32_e32 v112, v58, v224
	v_fmac_f32_e32 v113, v59, v224
	v_fmac_f32_e32 v114, v56, v224
	v_fmac_f32_e32 v115, v57, v224
	v_fma_f32 v118, v58, v116, v66
	v_fma_f32 v119, v59, v116, v67
	v_fma_f32 v120, v56, v116, v64
	v_fma_f32 v121, v57, v116, v65
	s_mov_b32 s0, 0xb644000
	ds_read_b128 v[56:59], v177
	ds_read_b128 v[64:67], v177 offset:4096
	v_add_co_u32_e32 v222, vcc, s0, v108
	s_mov_b32 s0, 0xb646000
	s_nop 0
	v_addc_co_u32_e32 v223, vcc, 0, v109, vcc
	global_store_dwordx4 v[222:223], v[72:75], off nt
	s_nop 1
	v_mov_b32_e32 v72, v117
	s_waitcnt vmcnt(23)
	v_mul_f32_e32 v74, v50, v72
	v_mul_f32_e32 v75, v51, v72
	v_mul_f32_e32 v73, v49, v72
	v_mul_f32_e32 v72, v48, v72
	s_waitcnt lgkmcnt(0)
	v_fmac_f32_e32 v74, v14, v64
	v_fmac_f32_e32 v75, v15, v64
	v_fmac_f32_e32 v72, v12, v64
	v_fmac_f32_e32 v73, v13, v64
	v_fmac_f32_e32 v74, v10, v65
	v_fmac_f32_e32 v75, v11, v65
	v_fma_f32 v116, v50, v56, v122
	v_fma_f32 v117, v51, v56, v123
	v_fma_f32 v122, v48, v56, v230
	v_fma_f32 v123, v49, v56, v231
	v_fma_f32 v64, v8, v65, v72
	v_fma_f32 v65, v9, v65, v73
	v_fma_f32 v72, v50, v57, v80
	v_fma_f32 v73, v51, v57, v81
	v_fma_f32 v80, v48, v57, v82
	v_fma_f32 v81, v49, v57, v83
	v_fma_f32 v56, v6, v66, v74
	v_fma_f32 v57, v7, v66, v75
	v_fma_f32 v74, v50, v58, v112
	v_fma_f32 v75, v51, v58, v113
	v_fma_f32 v82, v48, v58, v114
	v_fma_f32 v83, v49, v58, v115
	v_mov_b32_e32 v58, v67
	v_fmac_f32_e32 v64, v4, v66
	v_fmac_f32_e32 v65, v5, v66
	v_fma_f32 v66, v2, v58, v56
	v_fma_f32 v67, v3, v58, v57
	v_mov_b32_e32 v56, v59
	v_fmac_f32_e32 v64, v0, v58
	v_fmac_f32_e32 v65, v1, v58
	v_fma_f32 v112, v50, v56, v118
	v_fma_f32 v113, v51, v56, v119
	v_fma_f32 v114, v48, v56, v120
	v_fma_f32 v115, v49, v56, v121
	ds_read_b128 v[48:51], v178
	ds_read_b128 v[56:59], v178 offset:4096
	ds_read2_b32 v[118:119], v107 offset0:144 offset1:148
	v_add_co_u32_e32 v120, vcc, s0, v108
	s_waitcnt vmcnt(22) lgkmcnt(2)
	v_fmac_f32_e32 v116, v42, v48
	v_fmac_f32_e32 v117, v43, v48
	v_addc_co_u32_e32 v121, vcc, 0, v109, vcc
	global_store_dwordx4 v[120:121], v[64:67], off nt
	v_fma_f32 v120, v40, v48, v122
	v_fma_f32 v121, v41, v48, v123
	s_mov_b32 s0, 0xb648000
	s_waitcnt lgkmcnt(0)
	v_mul_f32_e32 v64, v42, v118
	v_mul_f32_e32 v65, v43, v118
	v_mul_f32_e32 v66, v40, v118
	v_mul_f32_e32 v67, v41, v118
	v_fmac_f32_e32 v64, v14, v56
	v_fmac_f32_e32 v65, v15, v56
	v_fmac_f32_e32 v66, v12, v56
	v_fmac_f32_e32 v67, v13, v56
	v_fmac_f32_e32 v64, v10, v57
	v_fmac_f32_e32 v65, v11, v57
	v_fma_f32 v56, v8, v57, v66
	v_fma_f32 v57, v9, v57, v67
	v_fma_f32 v66, v42, v49, v72
	v_fma_f32 v67, v43, v49, v73
	v_fma_f32 v72, v40, v49, v80
	v_fma_f32 v73, v41, v49, v81
	v_fma_f32 v48, v6, v58, v64
	v_fma_f32 v49, v7, v58, v65
	v_fma_f32 v64, v42, v50, v74
	v_fma_f32 v65, v43, v50, v75
	v_fma_f32 v74, v40, v50, v82
	v_fma_f32 v75, v41, v50, v83
	v_mov_b32_e32 v50, v59
	v_fmac_f32_e32 v56, v4, v58
	v_fmac_f32_e32 v57, v5, v58
	v_fma_f32 v58, v2, v50, v48
	v_fma_f32 v59, v3, v50, v49
	v_mov_b32_e32 v48, v51
	v_fmac_f32_e32 v56, v0, v50
	v_fmac_f32_e32 v57, v1, v50
	v_fma_f32 v80, v42, v48, v112
	v_fma_f32 v81, v43, v48, v113
	v_fma_f32 v82, v40, v48, v114
	v_fma_f32 v83, v41, v48, v115
	ds_read_b128 v[40:43], v179
	ds_read_b128 v[48:51], v179 offset:4096
	v_add_co_u32_e32 v112, vcc, s0, v108
	s_mov_b32 s0, 0xb64a000
	s_nop 0
	v_addc_co_u32_e32 v113, vcc, 0, v109, vcc
	global_store_dwordx4 v[112:113], v[56:59], off nt
	s_waitcnt vmcnt(23) lgkmcnt(1)
; __device__ __forceinline__ void gla_sample_unit(const Args& a, unsigned char* lds, int unit, int tid) {
;     ...
;     for (int g = 0; g < 8; ++g) {
;         if (g + 1 < 8) {
; #pragma unroll
;             for (int i = 0; i < 8; ++i) sb[(g + 1) & 1][i] = *(const f32x4*)(S0 + (size_t)(((g + 1) * 8 + i) * 4 + kq) * 512 + vc); }
; #pragma unroll
;         for (int i = 0; i < 8; ++i) { const int k = (g * 8 + i) * 4 + kq; const f32x4 s = sb[g & 1][i];
;             const f32x4 qv = *(const f32x4*)(Q4 + k * 4), kd = *(const f32x4*)(KD4 + k * 4); const float dec = DECS[k];
;             f32x4 sn = s * dec;
; #pragma unroll
;             for (int t = 0; t < 4; ++t) { sn += vr[t] * kd[t]; o[t] += s * qv[t]; }
;             *(f32x4*)(SN + (size_t)k * 512 + vc) = sn; } }
	v_fma_f32 v112, v34, v40, v116
	v_fma_f32 v113, v35, v40, v117
	v_fma_f32 v114, v32, v40, v120
	v_fma_f32 v115, v33, v40, v121
	v_mov_b32_e32 v56, v119
	v_mul_f32_e32 v58, v34, v56
	v_mul_f32_e32 v59, v35, v56
	v_mul_f32_e32 v57, v33, v56
	v_mul_f32_e32 v56, v32, v56
	s_waitcnt lgkmcnt(0)
	v_fmac_f32_e32 v58, v14, v48
	v_fmac_f32_e32 v59, v15, v48
	v_fmac_f32_e32 v56, v12, v48
	v_fmac_f32_e32 v57, v13, v48
	v_fmac_f32_e32 v58, v10, v49
	v_fmac_f32_e32 v59, v11, v49
	v_fma_f32 v48, v8, v49, v56
	v_fma_f32 v49, v9, v49, v57
	v_fma_f32 v56, v34, v41, v66
	v_fma_f32 v57, v35, v41, v67
	v_fma_f32 v66, v32, v41, v72
	v_fma_f32 v67, v33, v41, v73
	v_fma_f32 v40, v6, v50, v58
	v_fma_f32 v41, v7, v50, v59
	v_fma_f32 v58, v34, v42, v64
	v_fma_f32 v59, v35, v42, v65
	v_fma_f32 v64, v32, v42, v74
	v_fma_f32 v65, v33, v42, v75
	v_mov_b32_e32 v42, v51
	v_fmac_f32_e32 v48, v4, v50
	v_fmac_f32_e32 v49, v5, v50
	v_fma_f32 v50, v2, v42, v40
	v_fma_f32 v51, v3, v42, v41
	v_mov_b32_e32 v40, v43
	v_fmac_f32_e32 v48, v0, v42
	v_fmac_f32_e32 v49, v1, v42
	v_fma_f32 v72, v34, v40, v80
	v_fma_f32 v73, v35, v40, v81
	v_fma_f32 v74, v32, v40, v82
	v_fma_f32 v75, v33, v40, v83
	ds_read_b128 v[32:35], v180
	ds_read_b128 v[40:43], v180 offset:4096
	ds_read2_b32 v[80:81], v107 offset0:152 offset1:156
	v_add_co_u32_e32 v82, vcc, s0, v108
	s_mov_b32 s0, 0xb64c000
	s_nop 0
	v_addc_co_u32_e32 v83, vcc, 0, v109, vcc
	global_store_dwordx4 v[82:83], v[48:51], off nt
	s_waitcnt vmcnt(23) lgkmcnt(2)
	v_fma_f32 v82, v26, v32, v112
	v_fma_f32 v83, v27, v32, v113
	v_fma_f32 v112, v24, v32, v114
	v_fma_f32 v113, v25, v32, v115
	s_waitcnt lgkmcnt(0)
	v_mul_f32_e32 v48, v26, v80
	v_mul_f32_e32 v49, v27, v80
	v_mul_f32_e32 v50, v24, v80
	v_mul_f32_e32 v51, v25, v80
	v_fmac_f32_e32 v48, v14, v40
	v_fmac_f32_e32 v49, v15, v40
	v_fmac_f32_e32 v50, v12, v40
	v_fmac_f32_e32 v51, v13, v40
	v_fmac_f32_e32 v48, v10, v41
	v_fmac_f32_e32 v49, v11, v41
	v_fma_f32 v40, v8, v41, v50
	v_fma_f32 v41, v9, v41, v51
	v_fma_f32 v50, v26, v33, v56
	v_fma_f32 v51, v27, v33, v57
	v_fma_f32 v56, v24, v33, v66
	v_fma_f32 v57, v25, v33, v67
	v_fma_f32 v32, v6, v42, v48
	v_fma_f32 v33, v7, v42, v49
	v_fma_f32 v48, v26, v34, v58
	v_fma_f32 v49, v27, v34, v59
	v_fma_f32 v58, v24, v34, v64
	v_fma_f32 v59, v25, v34, v65
	v_mov_b32_e32 v34, v43
	v_fmac_f32_e32 v40, v4, v42
	v_fmac_f32_e32 v41, v5, v42
	v_fma_f32 v42, v2, v34, v32
	v_fma_f32 v43, v3, v34, v33
	v_mov_b32_e32 v32, v35
	v_fmac_f32_e32 v40, v0, v34
	v_fmac_f32_e32 v41, v1, v34
	v_fma_f32 v64, v26, v32, v72
	v_fma_f32 v65, v27, v32, v73
	v_fma_f32 v66, v24, v32, v74
	v_fma_f32 v67, v25, v32, v75
	ds_read_b128 v[24:27], v181
	ds_read_b128 v[32:35], v181 offset:4096
	v_add_co_u32_e32 v72, vcc, s0, v108
	s_mov_b32 s0, 0xb64e000
	s_nop 0
	v_addc_co_u32_e32 v73, vcc, 0, v109, vcc
	global_store_dwordx4 v[72:73], v[40:43], off nt
	s_waitcnt vmcnt(23) lgkmcnt(1)
	v_fma_f32 v114, v16, v25, v56
	v_fma_f32 v115, v17, v25, v57
	v_fma_f32 v116, v18, v26, v48
	v_fma_f32 v117, v19, v26, v49
	v_mov_b32_e32 v40, v81
	v_mul_f32_e32 v42, v18, v40
	v_mul_f32_e32 v43, v19, v40
	v_mul_f32_e32 v41, v17, v40
	v_mul_f32_e32 v40, v16, v40
	s_waitcnt lgkmcnt(0)
	v_fmac_f32_e32 v42, v14, v32
	v_fmac_f32_e32 v43, v15, v32
	v_fmac_f32_e32 v40, v12, v32
	v_fmac_f32_e32 v41, v13, v32
	v_fmac_f32_e32 v42, v10, v33
	v_fmac_f32_e32 v43, v11, v33
	v_fma_f32 v80, v18, v24, v82
	v_fma_f32 v81, v19, v24, v83
	v_fma_f32 v82, v16, v24, v112
	v_fma_f32 v83, v17, v24, v113
	v_fma_f32 v32, v8, v33, v40
	v_fma_f32 v33, v9, v33, v41
	v_fma_f32 v112, v18, v25, v50
	v_fma_f32 v113, v19, v25, v51
	v_fma_f32 v24, v6, v34, v42
	v_fma_f32 v25, v7, v34, v43
	v_fma_f32 v118, v16, v26, v58
	v_fma_f32 v119, v17, v26, v59
	v_mov_b32_e32 v26, v35
	v_fmac_f32_e32 v32, v4, v34
	v_fmac_f32_e32 v33, v5, v34
	v_fma_f32 v34, v2, v26, v24
	v_fma_f32 v35, v3, v26, v25
	v_mov_b32_e32 v24, v27
	v_fma_f32 v122, v16, v24, v66
	v_fma_f32 v123, v17, v24, v67
	v_add_co_u32_e32 v16, vcc, s0, v108
	v_fmac_f32_e32 v32, v0, v26
	v_fmac_f32_e32 v33, v1, v26
	s_nop 0
	v_addc_co_u32_e32 v17, vcc, 0, v109, vcc
	s_mov_b32 s0, 0x60000
	global_store_dwordx4 v[16:17], v[32:35], off nt
	v_add_co_u32_e32 v16, vcc, s0, v110
	s_mov_b32 s0, 0x62000
	s_nop 0
	v_addc_co_u32_e32 v17, vcc, 0, v111, vcc
	v_fma_f32 v120, v18, v24, v64
	v_fma_f32 v121, v19, v24, v65
	v_add_co_u32_e32 v18, vcc, s0, v110
	s_mov_b32 s0, 0x64000
	s_nop 0
	v_addc_co_u32_e32 v19, vcc, 0, v111, vcc
	global_load_dwordx4 v[72:75], v[16:17], off nt
	global_load_dwordx4 v[64:67], v[18:19], off nt
	v_add_co_u32_e32 v16, vcc, s0, v110
	s_mov_b32 s0, 0x66000
	s_nop 0
	v_addc_co_u32_e32 v17, vcc, 0, v111, vcc
	v_add_co_u32_e32 v18, vcc, s0, v110
	s_mov_b32 s0, 0x68000
	s_nop 0
	v_addc_co_u32_e32 v19, vcc, 0, v111, vcc
	global_load_dwordx4 v[56:59], v[16:17], off nt
	global_load_dwordx4 v[48:51], v[18:19], off nt
	v_add_co_u32_e32 v16, vcc, s0, v110
	s_mov_b32 s0, 0x6a000
	s_nop 0
	v_addc_co_u32_e32 v17, vcc, 0, v111, vcc
	v_add_co_u32_e32 v18, vcc, s0, v110
	s_mov_b32 s0, 0x6c000
	s_nop 0
	v_addc_co_u32_e32 v19, vcc, 0, v111, vcc
	global_load_dwordx4 v[40:43], v[16:17], off nt
	global_load_dwordx4 v[32:35], v[18:19], off nt
	ds_read2_b32 v[230:231], v107 offset0:160 offset1:164
	ds_read_b128 v[222:225], v182
	ds_read_b128 v[226:229], v182 offset:4096
	v_add_co_u32_e32 v16, vcc, s0, v110
	s_waitcnt vmcnt(21) lgkmcnt(2)
	v_mul_f32_e32 v232, v78, v230
	v_mul_f32_e32 v233, v79, v230
	v_mul_f32_e32 v234, v76, v230
	v_mul_f32_e32 v235, v77, v230
	s_waitcnt lgkmcnt(0)
; __device__ __forceinline__ void gla_sample_unit(const Args& a, unsigned char* lds, int unit, int tid) {
;     ...
;     for (int g = 0; g < 8; ++g) {
;         if (g + 1 < 8) {
; #pragma unroll
;             for (int i = 0; i < 8; ++i) sb[(g + 1) & 1][i] = *(const f32x4*)(S0 + (size_t)(((g + 1) * 8 + i) * 4 + kq) * 512 + vc); }
; #pragma unroll
;         for (int i = 0; i < 8; ++i) { const int k = (g * 8 + i) * 4 + kq; const f32x4 s = sb[g & 1][i];
;             const f32x4 qv = *(const f32x4*)(Q4 + k * 4), kd = *(const f32x4*)(KD4 + k * 4); const float dec = DECS[k];
;             f32x4 sn = s * dec;
; #pragma unroll
;             for (int t = 0; t < 4; ++t) { sn += vr[t] * kd[t]; o[t] += s * qv[t]; }
;             *(f32x4*)(SN + (size_t)k * 512 + vc) = sn; } }
	v_fmac_f32_e32 v232, v14, v226
	v_fmac_f32_e32 v233, v15, v226
	v_fmac_f32_e32 v234, v12, v226
	v_fmac_f32_e32 v235, v13, v226
	v_addc_co_u32_e32 v17, vcc, 0, v111, vcc
	s_mov_b32 s0, 0x6e000
	v_fma_f32 v236, v78, v222, v80
	v_fma_f32 v237, v79, v222, v81
	v_fma_f32 v238, v76, v222, v82
	v_fma_f32 v239, v77, v222, v83
	v_fma_f32 v80, v10, v227, v232
	v_fma_f32 v81, v11, v227, v233
	v_fma_f32 v82, v8, v227, v234
	v_fma_f32 v83, v9, v227, v235
	v_add_co_u32_e32 v18, vcc, s0, v110
	v_fmac_f32_e32 v112, v78, v223
	v_fmac_f32_e32 v113, v79, v223
	v_fma_f32 v222, v76, v223, v114
	v_fma_f32 v223, v77, v223, v115
	v_fmac_f32_e32 v80, v6, v228
	v_fmac_f32_e32 v81, v7, v228
	v_fma_f32 v114, v4, v228, v82
	v_fma_f32 v115, v5, v228, v83
	v_fma_f32 v226, v78, v224, v116
	v_fma_f32 v227, v79, v224, v117
	v_mov_b32_e32 v116, v229
	v_addc_co_u32_e32 v19, vcc, 0, v111, vcc
	v_fma_f32 v82, v2, v116, v80
	v_fma_f32 v83, v3, v116, v81
	v_fma_f32 v80, v0, v116, v114
	v_fma_f32 v81, v1, v116, v115
	v_mov_b32_e32 v114, v225
	global_load_dwordx4 v[24:27], v[16:17], off nt
	s_nop 0
	global_load_dwordx4 v[16:19], v[18:19], off nt
	v_fma_f32 v232, v76, v224, v118
	v_fma_f32 v233, v77, v224, v119
	v_fma_f32 v224, v78, v114, v120
	v_fma_f32 v225, v79, v114, v121
	v_fmac_f32_e32 v122, v76, v114
	v_fmac_f32_e32 v123, v77, v114
	s_mov_b32 s0, 0xb650000
	ds_read_b128 v[114:117], v183
	ds_read_b128 v[118:121], v183 offset:4096
	v_add_co_u32_e32 v76, vcc, s0, v108
	s_mov_b32 s0, 0xb652000
	s_nop 0
	v_addc_co_u32_e32 v77, vcc, 0, v109, vcc
	global_store_dwordx4 v[76:77], v[80:83], off nt
	v_mov_b32_e32 v76, v231
	s_waitcnt vmcnt(23)
	v_mul_f32_e32 v78, v70, v76
	v_mul_f32_e32 v79, v71, v76
	v_mul_f32_e32 v77, v69, v76
	v_mul_f32_e32 v76, v68, v76
	s_waitcnt lgkmcnt(0)
	v_fma_f32 v80, v14, v118, v78
	v_fma_f32 v81, v15, v118, v79
	v_fma_f32 v82, v12, v118, v76
	v_fma_f32 v83, v13, v118, v77
	v_fma_f32 v228, v10, v119, v80
	v_fma_f32 v229, v11, v119, v81
	v_fma_f32 v118, v8, v119, v82
	v_fma_f32 v119, v9, v119, v83
	v_fma_f32 v76, v70, v114, v236
	v_fma_f32 v77, v71, v114, v237
	v_fma_f32 v78, v68, v114, v238
	v_fma_f32 v79, v69, v114, v239
	v_fma_f32 v80, v70, v115, v112
	v_fma_f32 v81, v71, v115, v113
	v_fma_f32 v82, v68, v115, v222
	v_fma_f32 v83, v69, v115, v223
	v_fma_f32 v222, v6, v120, v228
	v_fma_f32 v223, v7, v120, v229
	v_fmac_f32_e32 v118, v4, v120
	v_fmac_f32_e32 v119, v5, v120
	v_fma_f32 v112, v70, v116, v226
	v_fma_f32 v113, v71, v116, v227
	v_fma_f32 v114, v68, v116, v232
	v_fma_f32 v115, v69, v116, v233
	v_mov_b32_e32 v116, v121
	v_fma_f32 v120, v2, v116, v222
	v_fma_f32 v121, v3, v116, v223
	v_fmac_f32_e32 v118, v0, v116
	v_fmac_f32_e32 v119, v1, v116
	v_mov_b32_e32 v116, v117
	v_fma_f32 v70, v70, v116, v224
	v_fma_f32 v71, v71, v116, v225
	v_fma_f32 v68, v68, v116, v122
	v_fma_f32 v69, v69, v116, v123
	ds_read_b128 v[222:225], v185
	ds_read_b128 v[226:229], v185 offset:4096
	ds_read2_b32 v[116:117], v107 offset0:168 offset1:172
	v_add_co_u32_e32 v122, vcc, s0, v108
	s_waitcnt vmcnt(22) lgkmcnt(2)
	v_fma_f32 v230, v60, v222, v78
	v_fma_f32 v231, v61, v222, v79
	v_addc_co_u32_e32 v123, vcc, 0, v109, vcc
	global_store_dwordx4 v[122:123], v[118:121], off nt
	v_fma_f32 v122, v62, v222, v76
	v_fma_f32 v123, v63, v222, v77
	v_fmac_f32_e32 v80, v62, v223
	v_fmac_f32_e32 v81, v63, v223
	s_waitcnt lgkmcnt(0)
	v_mul_f32_e32 v118, v62, v116
	v_mul_f32_e32 v119, v63, v116
	v_mul_f32_e32 v120, v60, v116
	v_mul_f32_e32 v121, v61, v116
	v_fmac_f32_e32 v118, v14, v226
	v_fmac_f32_e32 v119, v15, v226
	v_fmac_f32_e32 v120, v12, v226
	v_fmac_f32_e32 v121, v13, v226
	v_fma_f32 v76, v10, v227, v118
	v_fma_f32 v77, v11, v227, v119
	v_fma_f32 v78, v8, v227, v120
	v_fma_f32 v79, v9, v227, v121
	v_fmac_f32_e32 v76, v6, v228
	v_fmac_f32_e32 v77, v7, v228
	v_fma_f32 v118, v4, v228, v78
	v_fma_f32 v119, v5, v228, v79
	v_mov_b32_e32 v116, v229
	v_fma_f32 v78, v2, v116, v76
	v_fma_f32 v79, v3, v116, v77
	v_fma_f32 v76, v0, v116, v118
	v_fma_f32 v77, v1, v116, v119
	v_mov_b32_e32 v116, v225
	v_fmac_f32_e32 v82, v60, v223
	v_fmac_f32_e32 v83, v61, v223
	v_fmac_f32_e32 v112, v62, v224
	v_fmac_f32_e32 v113, v63, v224
	v_fmac_f32_e32 v114, v60, v224
	v_fmac_f32_e32 v115, v61, v224
	v_fma_f32 v118, v62, v116, v70
	v_fma_f32 v119, v63, v116, v71
	v_fma_f32 v120, v60, v116, v68
	v_fma_f32 v121, v61, v116, v69
	s_mov_b32 s0, 0xb654000
	ds_read_b128 v[60:63], v187
	ds_read_b128 v[68:71], v187 offset:4096
	v_add_co_u32_e32 v222, vcc, s0, v108
	s_mov_b32 s0, 0xb656000
	s_nop 0
	v_addc_co_u32_e32 v223, vcc, 0, v109, vcc
	global_store_dwordx4 v[222:223], v[76:79], off nt
	s_nop 1
	v_mov_b32_e32 v76, v117
	s_waitcnt vmcnt(23)
	v_mul_f32_e32 v78, v54, v76
	v_mul_f32_e32 v79, v55, v76
	v_mul_f32_e32 v77, v53, v76
	v_mul_f32_e32 v76, v52, v76
	s_waitcnt lgkmcnt(0)
	v_fmac_f32_e32 v78, v14, v68
	v_fmac_f32_e32 v79, v15, v68
	v_fmac_f32_e32 v76, v12, v68
	v_fmac_f32_e32 v77, v13, v68
	v_fmac_f32_e32 v78, v10, v69
	v_fmac_f32_e32 v79, v11, v69
	v_fma_f32 v116, v54, v60, v122
	v_fma_f32 v117, v55, v60, v123
	v_fma_f32 v122, v52, v60, v230
	v_fma_f32 v123, v53, v60, v231
	v_fma_f32 v68, v8, v69, v76
	v_fma_f32 v69, v9, v69, v77
	v_fma_f32 v76, v54, v61, v80
	v_fma_f32 v77, v55, v61, v81
	v_fma_f32 v80, v52, v61, v82
	v_fma_f32 v81, v53, v61, v83
	v_fma_f32 v60, v6, v70, v78
	v_fma_f32 v61, v7, v70, v79
	v_fma_f32 v78, v54, v62, v112
	v_fma_f32 v79, v55, v62, v113
	v_fma_f32 v82, v52, v62, v114
	v_fma_f32 v83, v53, v62, v115
	v_mov_b32_e32 v62, v71
	v_fmac_f32_e32 v68, v4, v70
	v_fmac_f32_e32 v69, v5, v70
	v_fma_f32 v70, v2, v62, v60
	v_fma_f32 v71, v3, v62, v61
	v_mov_b32_e32 v60, v63
	v_fmac_f32_e32 v68, v0, v62
	v_fmac_f32_e32 v69, v1, v62
	v_fma_f32 v112, v54, v60, v118
	v_fma_f32 v113, v55, v60, v119
	v_fma_f32 v114, v52, v60, v120
	v_fma_f32 v115, v53, v60, v121
	ds_read_b128 v[52:55], v190
	ds_read_b128 v[60:63], v190 offset:4096
	ds_read2_b32 v[118:119], v107 offset0:176 offset1:180
	v_add_co_u32_e32 v120, vcc, s0, v108
	s_waitcnt vmcnt(22) lgkmcnt(2)
; __device__ __forceinline__ void gla_sample_unit(const Args& a, unsigned char* lds, int unit, int tid) {
;     ...
;     for (int g = 0; g < 8; ++g) {
;         if (g + 1 < 8) {
; #pragma unroll
;             for (int i = 0; i < 8; ++i) sb[(g + 1) & 1][i] = *(const f32x4*)(S0 + (size_t)(((g + 1) * 8 + i) * 4 + kq) * 512 + vc); }
; #pragma unroll
;         for (int i = 0; i < 8; ++i) { const int k = (g * 8 + i) * 4 + kq; const f32x4 s = sb[g & 1][i];
;             const f32x4 qv = *(const f32x4*)(Q4 + k * 4), kd = *(const f32x4*)(KD4 + k * 4); const float dec = DECS[k];
;             f32x4 sn = s * dec;
; #pragma unroll
;             for (int t = 0; t < 4; ++t) { sn += vr[t] * kd[t]; o[t] += s * qv[t]; }
;             *(f32x4*)(SN + (size_t)k * 512 + vc) = sn; } }
	v_fmac_f32_e32 v116, v46, v52
	v_fmac_f32_e32 v117, v47, v52
	v_addc_co_u32_e32 v121, vcc, 0, v109, vcc
	global_store_dwordx4 v[120:121], v[68:71], off nt
	v_fma_f32 v120, v44, v52, v122
	v_fma_f32 v121, v45, v52, v123
	s_mov_b32 s0, 0xb658000
	s_waitcnt lgkmcnt(0)
	v_mul_f32_e32 v68, v46, v118
	v_mul_f32_e32 v69, v47, v118
	v_mul_f32_e32 v70, v44, v118
	v_mul_f32_e32 v71, v45, v118
	v_fmac_f32_e32 v68, v14, v60
	v_fmac_f32_e32 v69, v15, v60
	v_fmac_f32_e32 v70, v12, v60
	v_fmac_f32_e32 v71, v13, v60
	v_fmac_f32_e32 v68, v10, v61
	v_fmac_f32_e32 v69, v11, v61
	v_fma_f32 v60, v8, v61, v70
	v_fma_f32 v61, v9, v61, v71
	v_fma_f32 v70, v46, v53, v76
	v_fma_f32 v71, v47, v53, v77
	v_fma_f32 v76, v44, v53, v80
	v_fma_f32 v77, v45, v53, v81
	v_fma_f32 v52, v6, v62, v68
	v_fma_f32 v53, v7, v62, v69
	v_fma_f32 v68, v46, v54, v78
	v_fma_f32 v69, v47, v54, v79
	v_fma_f32 v78, v44, v54, v82
	v_fma_f32 v79, v45, v54, v83
	v_mov_b32_e32 v54, v63
	v_fmac_f32_e32 v60, v4, v62
	v_fmac_f32_e32 v61, v5, v62
	v_fma_f32 v62, v2, v54, v52
	v_fma_f32 v63, v3, v54, v53
	v_mov_b32_e32 v52, v55
	v_fmac_f32_e32 v60, v0, v54
	v_fmac_f32_e32 v61, v1, v54
	v_fma_f32 v80, v46, v52, v112
	v_fma_f32 v81, v47, v52, v113
	v_fma_f32 v82, v44, v52, v114
	v_fma_f32 v83, v45, v52, v115
	ds_read_b128 v[44:47], v191
	ds_read_b128 v[52:55], v191 offset:4096
	v_add_co_u32_e32 v112, vcc, s0, v108
	s_mov_b32 s0, 0xb65a000
	s_nop 0
	v_addc_co_u32_e32 v113, vcc, 0, v109, vcc
	global_store_dwordx4 v[112:113], v[60:63], off nt
	s_waitcnt vmcnt(23) lgkmcnt(1)
	v_fma_f32 v112, v38, v44, v116
	v_fma_f32 v113, v39, v44, v117
	v_fma_f32 v114, v36, v44, v120
	v_fma_f32 v115, v37, v44, v121
	v_mov_b32_e32 v60, v119
	v_mul_f32_e32 v62, v38, v60
	v_mul_f32_e32 v63, v39, v60
	v_mul_f32_e32 v61, v37, v60
	v_mul_f32_e32 v60, v36, v60
	s_waitcnt lgkmcnt(0)
	v_fmac_f32_e32 v62, v14, v52
	v_fmac_f32_e32 v63, v15, v52
	v_fmac_f32_e32 v60, v12, v52
	v_fmac_f32_e32 v61, v13, v52
	v_fmac_f32_e32 v62, v10, v53
	v_fmac_f32_e32 v63, v11, v53
	v_fma_f32 v52, v8, v53, v60
	v_fma_f32 v53, v9, v53, v61
	v_fma_f32 v60, v38, v45, v70
	v_fma_f32 v61, v39, v45, v71
	v_fma_f32 v70, v36, v45, v76
	v_fma_f32 v71, v37, v45, v77
	v_fma_f32 v44, v6, v54, v62
	v_fma_f32 v45, v7, v54, v63
	v_fma_f32 v62, v38, v46, v68
	v_fma_f32 v63, v39, v46, v69
	v_fma_f32 v68, v36, v46, v78
	v_fma_f32 v69, v37, v46, v79
	v_mov_b32_e32 v46, v55
	v_fmac_f32_e32 v52, v4, v54
	v_fmac_f32_e32 v53, v5, v54
	v_fma_f32 v54, v2, v46, v44
	v_fma_f32 v55, v3, v46, v45
	v_mov_b32_e32 v44, v47
	v_fmac_f32_e32 v52, v0, v46
	v_fmac_f32_e32 v53, v1, v46
	v_fma_f32 v76, v38, v44, v80
	v_fma_f32 v77, v39, v44, v81
	v_fma_f32 v78, v36, v44, v82
	v_fma_f32 v79, v37, v44, v83
	ds_read_b128 v[36:39], v192
	ds_read_b128 v[44:47], v192 offset:4096
	ds_read2_b32 v[80:81], v107 offset0:184 offset1:188
	v_add_co_u32_e32 v82, vcc, s0, v108
	s_mov_b32 s0, 0xb65c000
	s_nop 0
	v_addc_co_u32_e32 v83, vcc, 0, v109, vcc
	global_store_dwordx4 v[82:83], v[52:55], off nt
	s_waitcnt vmcnt(23) lgkmcnt(2)
	v_fma_f32 v82, v30, v36, v112
	v_fma_f32 v83, v31, v36, v113
	v_fma_f32 v112, v28, v36, v114
	v_fma_f32 v113, v29, v36, v115
	s_waitcnt lgkmcnt(0)
	v_mul_f32_e32 v52, v30, v80
	v_mul_f32_e32 v53, v31, v80
	v_mul_f32_e32 v54, v28, v80
	v_mul_f32_e32 v55, v29, v80
	v_fmac_f32_e32 v52, v14, v44
	v_fmac_f32_e32 v53, v15, v44
	v_fmac_f32_e32 v54, v12, v44
	v_fmac_f32_e32 v55, v13, v44
	v_fmac_f32_e32 v52, v10, v45
	v_fmac_f32_e32 v53, v11, v45
	v_fma_f32 v44, v8, v45, v54
	v_fma_f32 v45, v9, v45, v55
	v_fma_f32 v54, v30, v37, v60
	v_fma_f32 v55, v31, v37, v61
	v_fma_f32 v60, v28, v37, v70
	v_fma_f32 v61, v29, v37, v71
	v_fma_f32 v36, v6, v46, v52
	v_fma_f32 v37, v7, v46, v53
	v_fma_f32 v52, v30, v38, v62
	v_fma_f32 v53, v31, v38, v63
	v_fma_f32 v62, v28, v38, v68
	v_fma_f32 v63, v29, v38, v69
	v_mov_b32_e32 v38, v47
	v_fmac_f32_e32 v44, v4, v46
	v_fmac_f32_e32 v45, v5, v46
	v_fma_f32 v46, v2, v38, v36
	v_fma_f32 v47, v3, v38, v37
	v_mov_b32_e32 v36, v39
	v_fmac_f32_e32 v44, v0, v38
	v_fmac_f32_e32 v45, v1, v38
	v_fma_f32 v68, v30, v36, v76
	v_fma_f32 v69, v31, v36, v77
	v_fma_f32 v70, v28, v36, v78
	v_fma_f32 v71, v29, v36, v79
	ds_read_b128 v[28:31], v193
	ds_read_b128 v[36:39], v193 offset:4096
	v_add_co_u32_e32 v76, vcc, s0, v108
	s_mov_b32 s0, 0xb65e000
	s_nop 0
	v_addc_co_u32_e32 v77, vcc, 0, v109, vcc
	global_store_dwordx4 v[76:77], v[44:47], off nt
	s_waitcnt vmcnt(23) lgkmcnt(1)
	v_fma_f32 v114, v20, v29, v60
	v_fma_f32 v115, v21, v29, v61
	v_fma_f32 v116, v22, v30, v52
	v_fma_f32 v117, v23, v30, v53
	v_mov_b32_e32 v44, v81
	v_mul_f32_e32 v46, v22, v44
	v_mul_f32_e32 v47, v23, v44
	v_mul_f32_e32 v45, v21, v44
	v_mul_f32_e32 v44, v20, v44
	s_waitcnt lgkmcnt(0)
; __device__ __forceinline__ void gla_sample_unit(const Args& a, unsigned char* lds, int unit, int tid) {
;     ...
;     for (int g = 0; g < 8; ++g) {
;         if (g + 1 < 8) {
; #pragma unroll
;             for (int i = 0; i < 8; ++i) sb[(g + 1) & 1][i] = *(const f32x4*)(S0 + (size_t)(((g + 1) * 8 + i) * 4 + kq) * 512 + vc); }
; #pragma unroll
;         for (int i = 0; i < 8; ++i) { const int k = (g * 8 + i) * 4 + kq; const f32x4 s = sb[g & 1][i];
;             const f32x4 qv = *(const f32x4*)(Q4 + k * 4), kd = *(const f32x4*)(KD4 + k * 4); const float dec = DECS[k];
;             f32x4 sn = s * dec;
; #pragma unroll
;             for (int t = 0; t < 4; ++t) { sn += vr[t] * kd[t]; o[t] += s * qv[t]; }
;             *(f32x4*)(SN + (size_t)k * 512 + vc) = sn; } }
	v_fmac_f32_e32 v46, v14, v36
	v_fmac_f32_e32 v47, v15, v36
	v_fmac_f32_e32 v44, v12, v36
	v_fmac_f32_e32 v45, v13, v36
	v_fmac_f32_e32 v46, v10, v37
	v_fmac_f32_e32 v47, v11, v37
	v_fma_f32 v80, v22, v28, v82
	v_fma_f32 v81, v23, v28, v83
	v_fma_f32 v82, v20, v28, v112
	v_fma_f32 v83, v21, v28, v113
	v_fma_f32 v36, v8, v37, v44
	v_fma_f32 v37, v9, v37, v45
	v_fma_f32 v112, v22, v29, v54
	v_fma_f32 v113, v23, v29, v55
	v_fma_f32 v28, v6, v38, v46
	v_fma_f32 v29, v7, v38, v47
	v_fma_f32 v118, v20, v30, v62
	v_fma_f32 v119, v21, v30, v63
	v_mov_b32_e32 v30, v39
	v_fmac_f32_e32 v36, v4, v38
	v_fmac_f32_e32 v37, v5, v38
	v_fma_f32 v38, v2, v30, v28
	v_fma_f32 v39, v3, v30, v29
	v_mov_b32_e32 v28, v31
	v_fma_f32 v122, v20, v28, v70
	v_fma_f32 v123, v21, v28, v71
	v_add_co_u32_e32 v20, vcc, s0, v108
	v_fmac_f32_e32 v36, v0, v30
	v_fmac_f32_e32 v37, v1, v30
	s_nop 0
	v_addc_co_u32_e32 v21, vcc, 0, v109, vcc
	s_mov_b32 s0, 0x70000
	global_store_dwordx4 v[20:21], v[36:39], off nt
	v_add_co_u32_e32 v20, vcc, s0, v110
	s_mov_b32 s0, 0x72000
	s_nop 0
	v_addc_co_u32_e32 v21, vcc, 0, v111, vcc
	v_fma_f32 v120, v22, v28, v68
	v_fma_f32 v121, v23, v28, v69
	v_add_co_u32_e32 v22, vcc, s0, v110
	s_mov_b32 s0, 0x74000
	s_nop 0
	v_addc_co_u32_e32 v23, vcc, 0, v111, vcc
	global_load_dwordx4 v[76:79], v[20:21], off nt
	global_load_dwordx4 v[68:71], v[22:23], off nt
	v_add_co_u32_e32 v20, vcc, s0, v110
	s_mov_b32 s0, 0x76000
	s_nop 0
	v_addc_co_u32_e32 v21, vcc, 0, v111, vcc
	v_add_co_u32_e32 v22, vcc, s0, v110
	s_mov_b32 s0, 0x78000
	s_nop 0
	v_addc_co_u32_e32 v23, vcc, 0, v111, vcc
	global_load_dwordx4 v[60:63], v[20:21], off nt
	global_load_dwordx4 v[52:55], v[22:23], off nt
	v_add_co_u32_e32 v20, vcc, s0, v110
	s_mov_b32 s0, 0x7a000
	s_nop 0
	v_addc_co_u32_e32 v21, vcc, 0, v111, vcc
	v_add_co_u32_e32 v22, vcc, s0, v110
	s_mov_b32 s0, 0x7c000
	s_nop 0
	v_addc_co_u32_e32 v23, vcc, 0, v111, vcc
	global_load_dwordx4 v[44:47], v[20:21], off nt
	global_load_dwordx4 v[36:39], v[22:23], off nt
	ds_read2_b32 v[230:231], v107 offset0:192 offset1:196
	ds_read_b128 v[222:225], v194
	ds_read_b128 v[226:229], v194 offset:4096
	v_add_co_u32_e32 v20, vcc, s0, v110
	s_mov_b32 s0, 0x7e000
	s_nop 0
	v_addc_co_u32_e32 v21, vcc, 0, v111, vcc
	v_add_co_u32_e32 v22, vcc, s0, v110
	s_waitcnt vmcnt(21) lgkmcnt(2)
	v_mul_f32_e32 v232, v72, v230
	v_mul_f32_e32 v233, v73, v230
	v_addc_co_u32_e32 v23, vcc, 0, v111, vcc
	v_mul_f32_e32 v110, v74, v230
	v_mul_f32_e32 v111, v75, v230
	s_waitcnt lgkmcnt(0)
	v_fmac_f32_e32 v232, v12, v226
	v_fmac_f32_e32 v233, v13, v226
	v_fmac_f32_e32 v110, v14, v226
	v_fmac_f32_e32 v111, v15, v226
	v_fma_f32 v234, v74, v222, v80
	v_fma_f32 v235, v75, v222, v81
	v_fma_f32 v236, v72, v222, v82
	v_fma_f32 v237, v73, v222, v83
	v_fma_f32 v80, v10, v227, v110
	v_fma_f32 v81, v11, v227, v111
	v_fma_f32 v82, v8, v227, v232
	v_fma_f32 v83, v9, v227, v233
	v_fma_f32 v226, v74, v223, v112
	v_fma_f32 v227, v75, v223, v113
	v_fmac_f32_e32 v80, v6, v228
	v_fmac_f32_e32 v81, v7, v228
	v_fma_f32 v110, v4, v228, v82
	v_fma_f32 v111, v5, v228, v83
	v_mov_b32_e32 v112, v229
	v_fma_f32 v82, v2, v112, v80
	v_fma_f32 v83, v3, v112, v81
	v_fma_f32 v80, v0, v112, v110
	v_fma_f32 v81, v1, v112, v111
	v_mov_b32_e32 v110, v225
	global_load_dwordx4 v[28:31], v[20:21], off nt
	s_nop 0
	global_load_dwordx4 v[20:23], v[22:23], off nt
	v_fmac_f32_e32 v114, v72, v223
	v_fmac_f32_e32 v115, v73, v223
	v_fmac_f32_e32 v116, v74, v224
	v_fmac_f32_e32 v117, v75, v224
	v_fmac_f32_e32 v118, v72, v224
	v_fmac_f32_e32 v119, v73, v224
	v_fmac_f32_e32 v120, v74, v110
	v_fmac_f32_e32 v121, v75, v110
	v_fmac_f32_e32 v122, v72, v110
	v_fmac_f32_e32 v123, v73, v110
	s_mov_b32 s0, 0xb660000
	ds_read_b128 v[72:75], v195
	ds_read_b128 v[110:113], v195 offset:4096
	v_add_co_u32_e32 v222, vcc, s0, v108
	s_mov_b32 s0, 0xb662000
	s_nop 0
	v_addc_co_u32_e32 v223, vcc, 0, v109, vcc
	global_store_dwordx4 v[222:223], v[80:83], off nt
	s_waitcnt vmcnt(23) lgkmcnt(1)
	v_fma_f32 v222, v66, v72, v234
	v_fma_f32 v223, v67, v72, v235
	v_fma_f32 v224, v64, v72, v236
	v_fma_f32 v225, v65, v72, v237
	v_mov_b32_e32 v80, v231
	v_mul_f32_e32 v82, v66, v80
	v_mul_f32_e32 v83, v67, v80
	v_mul_f32_e32 v81, v65, v80
	v_mul_f32_e32 v80, v64, v80
	s_waitcnt lgkmcnt(0)
	v_fmac_f32_e32 v82, v14, v110
	v_fmac_f32_e32 v83, v15, v110
	v_fmac_f32_e32 v80, v12, v110
	v_fmac_f32_e32 v81, v13, v110
	v_fmac_f32_e32 v82, v10, v111
	v_fmac_f32_e32 v83, v11, v111
	v_fmac_f32_e32 v226, v66, v73
	v_fmac_f32_e32 v227, v67, v73
	v_fma_f32 v228, v64, v73, v114
	v_fma_f32 v229, v65, v73, v115
	v_fma_f32 v72, v6, v112, v82
	v_fma_f32 v73, v7, v112, v83
	v_fma_f32 v230, v66, v74, v116
	v_fma_f32 v231, v67, v74, v117
	v_fmac_f32_e32 v118, v64, v74
	v_fmac_f32_e32 v119, v65, v74
	v_mov_b32_e32 v74, v113
	v_fmac_f32_e32 v80, v8, v111
	v_fmac_f32_e32 v81, v9, v111
	v_fma_f32 v82, v2, v74, v72
	v_fma_f32 v83, v3, v74, v73
	v_mov_b32_e32 v72, v75
	v_fmac_f32_e32 v80, v4, v112
	v_fmac_f32_e32 v81, v5, v112
	v_fmac_f32_e32 v122, v64, v72
	v_fmac_f32_e32 v123, v65, v72
	ds_read_b128 v[110:113], v196
	ds_read_b128 v[114:117], v196 offset:4096
	ds_read2_b32 v[64:65], v107 offset0:200 offset1:204
	v_fmac_f32_e32 v120, v66, v72
	v_fmac_f32_e32 v121, v67, v72
	v_add_co_u32_e32 v66, vcc, s0, v108
	v_fmac_f32_e32 v80, v0, v74
	v_fmac_f32_e32 v81, v1, v74
	s_nop 0
	v_addc_co_u32_e32 v67, vcc, 0, v109, vcc
	global_store_dwordx4 v[66:67], v[80:83], off nt
	s_waitcnt vmcnt(23) lgkmcnt(0)
; __device__ __forceinline__ void gla_sample_unit(const Args& a, unsigned char* lds, int unit, int tid) {
;     ...
;     for (int g = 0; g < 8; ++g) {
;         if (g + 1 < 8) {
; #pragma unroll
;             for (int i = 0; i < 8; ++i) sb[(g + 1) & 1][i] = *(const f32x4*)(S0 + (size_t)(((g + 1) * 8 + i) * 4 + kq) * 512 + vc); }
; #pragma unroll
;         for (int i = 0; i < 8; ++i) { const int k = (g * 8 + i) * 4 + kq; const f32x4 s = sb[g & 1][i];
;             const f32x4 qv = *(const f32x4*)(Q4 + k * 4), kd = *(const f32x4*)(KD4 + k * 4); const float dec = DECS[k];
;             f32x4 sn = s * dec;
; #pragma unroll
;             for (int t = 0; t < 4; ++t) { sn += vr[t] * kd[t]; o[t] += s * qv[t]; }
;             *(f32x4*)(SN + (size_t)k * 512 + vc) = sn; } }
	v_mul_f32_e32 v66, v58, v64
	v_mul_f32_e32 v67, v59, v64
	v_mul_f32_e32 v72, v56, v64
	v_mul_f32_e32 v73, v57, v64
	v_fma_f32 v74, v14, v114, v66
	v_fma_f32 v75, v15, v114, v67
	v_fma_f32 v80, v12, v114, v72
	v_fma_f32 v81, v13, v114, v73
	v_fma_f32 v82, v10, v115, v74
	v_fma_f32 v83, v11, v115, v75
	v_fma_f32 v114, v8, v115, v80
	v_fma_f32 v115, v9, v115, v81
	v_fma_f32 v66, v58, v110, v222
	v_fma_f32 v67, v59, v110, v223
	v_fma_f32 v222, v6, v116, v82
	v_fma_f32 v223, v7, v116, v83
	v_fmac_f32_e32 v114, v4, v116
	v_fmac_f32_e32 v115, v5, v116
	v_mov_b32_e32 v64, v117
	v_fma_f32 v116, v2, v64, v222
	v_fma_f32 v117, v3, v64, v223
	v_fmac_f32_e32 v114, v0, v64
	v_fmac_f32_e32 v115, v1, v64
	v_mov_b32_e32 v64, v113
	v_fma_f32 v72, v56, v110, v224
	v_fma_f32 v73, v57, v110, v225
	v_fma_f32 v74, v58, v111, v226
	v_fma_f32 v75, v59, v111, v227
	v_fma_f32 v80, v56, v111, v228
	v_fma_f32 v81, v57, v111, v229
	v_fma_f32 v82, v58, v112, v230
	v_fma_f32 v83, v59, v112, v231
	v_fma_f32 v110, v56, v112, v118
	v_fma_f32 v111, v57, v112, v119
	v_fma_f32 v58, v58, v64, v120
	v_fma_f32 v59, v59, v64, v121
	ds_read_b128 v[118:121], v197
	ds_read_b128 v[222:225], v197 offset:4096
	s_mov_b32 s0, 0xb664000
	v_add_co_u32_e32 v112, vcc, s0, v108
	v_fma_f32 v56, v56, v64, v122
	v_fma_f32 v57, v57, v64, v123
	s_nop 0
	v_addc_co_u32_e32 v113, vcc, 0, v109, vcc
	v_mov_b32_e32 v64, v65
	global_store_dwordx4 v[112:113], v[114:117], off nt
	s_waitcnt vmcnt(23)
	v_mul_f32_e32 v112, v50, v64
	v_mul_f32_e32 v113, v51, v64
	v_mul_f32_e32 v65, v49, v64
	v_mul_f32_e32 v64, v48, v64
	s_waitcnt lgkmcnt(0)
	v_fmac_f32_e32 v112, v14, v222
	v_fmac_f32_e32 v113, v15, v222
	v_fmac_f32_e32 v64, v12, v222
	v_fmac_f32_e32 v65, v13, v222
	v_fma_f32 v114, v50, v118, v66
	v_fma_f32 v115, v51, v118, v67
	v_fma_f32 v66, v10, v223, v112
	v_fma_f32 v67, v11, v223, v113
	v_fmac_f32_e32 v64, v8, v223
	v_fmac_f32_e32 v65, v9, v223
	v_fmac_f32_e32 v66, v6, v224
	v_fmac_f32_e32 v67, v7, v224
	v_fmac_f32_e32 v64, v4, v224
	v_fmac_f32_e32 v65, v5, v224
	v_mov_b32_e32 v112, v225
	v_fmac_f32_e32 v66, v2, v112
	v_fmac_f32_e32 v67, v3, v112
	v_fmac_f32_e32 v64, v0, v112
	v_fmac_f32_e32 v65, v1, v112
	v_mov_b32_e32 v112, v121
	v_fmac_f32_e32 v72, v48, v118
	v_fmac_f32_e32 v73, v49, v118
	v_fmac_f32_e32 v74, v50, v119
	v_fmac_f32_e32 v75, v51, v119
	v_fmac_f32_e32 v80, v48, v119
	v_fmac_f32_e32 v81, v49, v119
	v_fmac_f32_e32 v82, v50, v120
	v_fmac_f32_e32 v83, v51, v120
	v_fmac_f32_e32 v110, v48, v120
	v_fmac_f32_e32 v111, v49, v120
	v_fma_f32 v116, v50, v112, v58
	v_fma_f32 v117, v51, v112, v59
	v_fma_f32 v113, v49, v112, v57
	v_fma_f32 v112, v48, v112, v56
	ds_read_b128 v[48:51], v198
	ds_read_b128 v[56:59], v198 offset:4096
	ds_read2_b32 v[118:119], v107 offset0:208 offset1:212
	s_mov_b32 s0, 0xb666000
	v_add_co_u32_e32 v120, vcc, s0, v108
	s_waitcnt vmcnt(22) lgkmcnt(2)
	v_fmac_f32_e32 v114, v42, v48
	v_fmac_f32_e32 v115, v43, v48
	v_addc_co_u32_e32 v121, vcc, 0, v109, vcc
	global_store_dwordx4 v[120:121], v[64:67], off nt
	v_fmac_f32_e32 v72, v40, v48
	v_fmac_f32_e32 v73, v41, v48
	s_waitcnt lgkmcnt(0)
	v_mul_f32_e32 v64, v42, v118
	v_mul_f32_e32 v65, v43, v118
	v_mul_f32_e32 v66, v40, v118
	v_mul_f32_e32 v67, v41, v118
	v_fmac_f32_e32 v64, v14, v56
	v_fmac_f32_e32 v65, v15, v56
	v_fmac_f32_e32 v66, v12, v56
	v_fmac_f32_e32 v67, v13, v56
	v_fmac_f32_e32 v64, v10, v57
	v_fmac_f32_e32 v65, v11, v57
	v_fma_f32 v56, v8, v57, v66
	v_fma_f32 v57, v9, v57, v67
	v_fma_f32 v66, v42, v49, v74
	v_fma_f32 v67, v43, v49, v75
	v_fma_f32 v74, v40, v49, v80
	v_fma_f32 v75, v41, v49, v81
	v_fma_f32 v48, v6, v58, v64
	v_fma_f32 v49, v7, v58, v65
	v_fma_f32 v64, v42, v50, v82
	v_fma_f32 v65, v43, v50, v83
	v_fma_f32 v80, v40, v50, v110
	v_fma_f32 v81, v41, v50, v111
	v_mov_b32_e32 v50, v59
	v_fmac_f32_e32 v56, v4, v58
	v_fmac_f32_e32 v57, v5, v58
	v_fma_f32 v58, v2, v50, v48
	v_fma_f32 v59, v3, v50, v49
	v_mov_b32_e32 v48, v51
	v_fmac_f32_e32 v56, v0, v50
	v_fmac_f32_e32 v57, v1, v50
	v_fma_f32 v82, v42, v48, v116
	v_fma_f32 v83, v43, v48, v117
	v_fma_f32 v110, v40, v48, v112
	v_fma_f32 v111, v41, v48, v113
	ds_read_b128 v[40:43], v199
	ds_read_b128 v[48:51], v199 offset:4096
	v_add_co_u32_e32 v112, vcc, s34, v108
	s_waitcnt vmcnt(22) lgkmcnt(1)
	v_fmac_f32_e32 v72, v32, v40
	v_fmac_f32_e32 v73, v33, v40
	v_addc_co_u32_e32 v113, vcc, 0, v109, vcc
	global_store_dwordx4 v[112:113], v[56:59], off nt
	v_fma_f32 v112, v34, v40, v114
	v_fma_f32 v113, v35, v40, v115
	s_nop 0
	v_mov_b32_e32 v56, v119
	v_mul_f32_e32 v58, v34, v56
	v_mul_f32_e32 v59, v35, v56
	v_mul_f32_e32 v57, v33, v56
	v_mul_f32_e32 v56, v32, v56
	s_waitcnt lgkmcnt(0)
	v_fmac_f32_e32 v58, v14, v48
	v_fmac_f32_e32 v59, v15, v48
	v_fmac_f32_e32 v56, v12, v48
	v_fmac_f32_e32 v57, v13, v48
	v_fmac_f32_e32 v58, v10, v49
	v_fmac_f32_e32 v59, v11, v49
	v_fma_f32 v48, v8, v49, v56
	v_fma_f32 v49, v9, v49, v57
	v_fma_f32 v56, v34, v41, v66
	v_fma_f32 v57, v35, v41, v67
	v_fma_f32 v66, v32, v41, v74
	v_fma_f32 v67, v33, v41, v75
	v_fma_f32 v40, v6, v50, v58
	v_fma_f32 v41, v7, v50, v59
	v_fma_f32 v58, v34, v42, v64
	v_fma_f32 v59, v35, v42, v65
	v_fma_f32 v64, v32, v42, v80
	v_fma_f32 v65, v33, v42, v81
	v_mov_b32_e32 v42, v51
	v_fmac_f32_e32 v48, v4, v50
	v_fmac_f32_e32 v49, v5, v50
	v_fma_f32 v50, v2, v42, v40
	v_fma_f32 v51, v3, v42, v41
	v_mov_b32_e32 v40, v43
	v_fmac_f32_e32 v48, v0, v42
	v_fmac_f32_e32 v49, v1, v42
	v_fma_f32 v74, v34, v40, v82
	v_fma_f32 v75, v35, v40, v83
	v_fma_f32 v80, v32, v40, v110
	v_fma_f32 v81, v33, v40, v111
	ds_read_b128 v[32:35], v200
	ds_read_b128 v[40:43], v200 offset:4096
	ds_read2_b32 v[82:83], v107 offset0:216 offset1:220
	v_add_co_u32_e32 v110, vcc, s35, v108
	s_waitcnt vmcnt(22) lgkmcnt(2)
; __device__ __forceinline__ void gla_sample_unit(const Args& a, unsigned char* lds, int unit, int tid) {
;     ...
;     for (int g = 0; g < 8; ++g) {
;         if (g + 1 < 8) {
; #pragma unroll
;             for (int i = 0; i < 8; ++i) sb[(g + 1) & 1][i] = *(const f32x4*)(S0 + (size_t)(((g + 1) * 8 + i) * 4 + kq) * 512 + vc); }
; #pragma unroll
;         for (int i = 0; i < 8; ++i) { const int k = (g * 8 + i) * 4 + kq; const f32x4 s = sb[g & 1][i];
;             const f32x4 qv = *(const f32x4*)(Q4 + k * 4), kd = *(const f32x4*)(KD4 + k * 4); const float dec = DECS[k];
;             f32x4 sn = s * dec;
; #pragma unroll
;             for (int t = 0; t < 4; ++t) { sn += vr[t] * kd[t]; o[t] += s * qv[t]; }
;             *(f32x4*)(SN + (size_t)k * 512 + vc) = sn; } }
	v_fmac_f32_e32 v72, v24, v32
	v_fmac_f32_e32 v73, v25, v32
	v_addc_co_u32_e32 v111, vcc, 0, v109, vcc
	global_store_dwordx4 v[110:111], v[48:51], off nt
	v_fma_f32 v110, v26, v32, v112
	v_fma_f32 v111, v27, v32, v113
	s_waitcnt lgkmcnt(0)
	v_mul_f32_e32 v48, v26, v82
	v_mul_f32_e32 v49, v27, v82
	v_mul_f32_e32 v50, v24, v82
	v_mul_f32_e32 v51, v25, v82
	v_fmac_f32_e32 v48, v14, v40
	v_fmac_f32_e32 v49, v15, v40
	v_fmac_f32_e32 v50, v12, v40
	v_fmac_f32_e32 v51, v13, v40
	v_fmac_f32_e32 v48, v10, v41
	v_fmac_f32_e32 v49, v11, v41
	v_fma_f32 v40, v8, v41, v50
	v_fma_f32 v41, v9, v41, v51
	v_fma_f32 v50, v26, v33, v56
	v_fma_f32 v51, v27, v33, v57
	v_fma_f32 v56, v24, v33, v66
	v_fma_f32 v57, v25, v33, v67
	v_fma_f32 v32, v6, v42, v48
	v_fma_f32 v33, v7, v42, v49
	v_fma_f32 v48, v26, v34, v58
	v_fma_f32 v49, v27, v34, v59
	v_fma_f32 v58, v24, v34, v64
	v_fma_f32 v59, v25, v34, v65
	v_mov_b32_e32 v34, v43
	v_fmac_f32_e32 v40, v4, v42
	v_fmac_f32_e32 v41, v5, v42
	v_fma_f32 v42, v2, v34, v32
	v_fma_f32 v43, v3, v34, v33
	v_mov_b32_e32 v32, v35
	v_fmac_f32_e32 v40, v0, v34
	v_fmac_f32_e32 v41, v1, v34
	v_fma_f32 v64, v26, v32, v74
	v_fma_f32 v65, v27, v32, v75
	v_fma_f32 v66, v24, v32, v80
	v_fma_f32 v67, v25, v32, v81
	ds_read_b128 v[24:27], v201
	ds_read_b128 v[32:35], v201 offset:4096
	v_add_co_u32_e32 v74, vcc, s36, v108
	s_waitcnt vmcnt(22) lgkmcnt(1)
	v_fmac_f32_e32 v72, v16, v24
	v_fmac_f32_e32 v73, v17, v24
	v_addc_co_u32_e32 v75, vcc, 0, v109, vcc
	global_store_dwordx4 v[74:75], v[40:43], off nt
	v_fma_f32 v74, v18, v24, v110
	v_fma_f32 v75, v19, v24, v111
	s_nop 0
	v_mov_b32_e32 v40, v83
	v_mul_f32_e32 v42, v18, v40
	v_mul_f32_e32 v43, v19, v40
	v_mul_f32_e32 v41, v17, v40
	v_mul_f32_e32 v40, v16, v40
	s_waitcnt lgkmcnt(0)
	v_fmac_f32_e32 v42, v14, v32
	v_fmac_f32_e32 v43, v15, v32
	v_fmac_f32_e32 v40, v12, v32
	v_fmac_f32_e32 v41, v13, v32
	v_fmac_f32_e32 v42, v10, v33
	v_fmac_f32_e32 v43, v11, v33
	v_fma_f32 v32, v8, v33, v40
	v_fma_f32 v33, v9, v33, v41
	v_fma_f32 v40, v18, v25, v50
	v_fma_f32 v41, v19, v25, v51
	v_fma_f32 v50, v16, v25, v56
	v_fma_f32 v51, v17, v25, v57
	v_fma_f32 v24, v6, v34, v42
	v_fma_f32 v25, v7, v34, v43
	v_fma_f32 v42, v18, v26, v48
	v_fma_f32 v43, v19, v26, v49
	v_fma_f32 v48, v16, v26, v58
	v_fma_f32 v49, v17, v26, v59
	v_mov_b32_e32 v26, v35
	v_fmac_f32_e32 v32, v4, v34
	v_fmac_f32_e32 v33, v5, v34
	v_fma_f32 v34, v2, v26, v24
	v_fma_f32 v35, v3, v26, v25
	v_mov_b32_e32 v24, v27
	v_fmac_f32_e32 v32, v0, v26
	v_fmac_f32_e32 v33, v1, v26
	v_fma_f32 v56, v18, v24, v64
	v_fma_f32 v57, v19, v24, v65
	v_fma_f32 v58, v16, v24, v66
	v_fma_f32 v59, v17, v24, v67
	ds_read_b128 v[16:19], v202
	ds_read_b128 v[24:27], v202 offset:4096
	ds_read2_b32 v[64:65], v107 offset0:224 offset1:228
	v_add_co_u32_e32 v66, vcc, s37, v108
	s_waitcnt vmcnt(14) lgkmcnt(2)
	v_fmac_f32_e32 v72, v76, v16
	v_fmac_f32_e32 v73, v77, v16
	v_addc_co_u32_e32 v67, vcc, 0, v109, vcc
	global_store_dwordx4 v[66:67], v[32:35], off nt
	v_fma_f32 v66, v78, v16, v74
	v_fma_f32 v67, v79, v16, v75
	v_fmac_f32_e32 v40, v78, v17
	v_fmac_f32_e32 v41, v79, v17
	s_waitcnt lgkmcnt(0)
	v_mul_f32_e32 v32, v78, v64
	v_mul_f32_e32 v33, v79, v64
	v_mul_f32_e32 v34, v76, v64
	v_mul_f32_e32 v35, v77, v64
	v_fmac_f32_e32 v32, v14, v24
	v_fmac_f32_e32 v33, v15, v24
	v_fmac_f32_e32 v34, v12, v24
	v_fmac_f32_e32 v35, v13, v24
	v_fmac_f32_e32 v32, v10, v25
	v_fmac_f32_e32 v33, v11, v25
	v_fma_f32 v24, v8, v25, v34
	v_fma_f32 v25, v9, v25, v35
	v_fmac_f32_e32 v50, v76, v17
	v_fmac_f32_e32 v51, v77, v17
	v_fma_f32 v16, v6, v26, v32
	v_fma_f32 v17, v7, v26, v33
	v_fmac_f32_e32 v42, v78, v18
	v_fmac_f32_e32 v43, v79, v18
	v_fmac_f32_e32 v48, v76, v18
	v_fmac_f32_e32 v49, v77, v18
	v_mov_b32_e32 v18, v27
	v_fmac_f32_e32 v24, v4, v26
	v_fmac_f32_e32 v25, v5, v26
	v_fma_f32 v26, v2, v18, v16
	v_fma_f32 v27, v3, v18, v17
	v_mov_b32_e32 v16, v19
	v_fmac_f32_e32 v24, v0, v18
	v_fmac_f32_e32 v25, v1, v18
	v_fmac_f32_e32 v56, v78, v16
	v_fmac_f32_e32 v57, v79, v16
	v_fmac_f32_e32 v58, v76, v16
	v_fmac_f32_e32 v59, v77, v16
	ds_read_b128 v[16:19], v203
	ds_read_b128 v[32:35], v203 offset:4096
	v_add_co_u32_e32 v74, vcc, s38, v108
	s_waitcnt vmcnt(14) lgkmcnt(1)
	v_fmac_f32_e32 v40, v70, v17
	v_fmac_f32_e32 v41, v71, v17
	v_addc_co_u32_e32 v75, vcc, 0, v109, vcc
	global_store_dwordx4 v[74:75], v[24:27], off nt
	v_fmac_f32_e32 v50, v68, v17
	v_fmac_f32_e32 v51, v69, v17
	v_fmac_f32_e32 v42, v70, v18
	v_fmac_f32_e32 v43, v71, v18
	v_mov_b32_e32 v24, v65
	v_mul_f32_e32 v26, v70, v24
	v_mul_f32_e32 v27, v71, v24
	v_mul_f32_e32 v25, v69, v24
	v_mul_f32_e32 v24, v68, v24
	s_waitcnt lgkmcnt(0)
	v_fmac_f32_e32 v26, v14, v32
	v_fmac_f32_e32 v27, v15, v32
	v_fmac_f32_e32 v24, v12, v32
	v_fmac_f32_e32 v25, v13, v32
	v_fmac_f32_e32 v26, v10, v33
	v_fmac_f32_e32 v27, v11, v33
	v_fma_f32 v64, v70, v16, v66
	v_fma_f32 v65, v71, v16, v67
	v_fma_f32 v66, v68, v16, v72
	v_fma_f32 v67, v69, v16, v73
	v_fmac_f32_e32 v24, v8, v33
	v_fmac_f32_e32 v25, v9, v33
	v_fma_f32 v16, v6, v34, v26
	v_fma_f32 v17, v7, v34, v27
	v_fmac_f32_e32 v48, v68, v18
	v_fmac_f32_e32 v49, v69, v18
	v_mov_b32_e32 v18, v35
	v_fmac_f32_e32 v24, v4, v34
	v_fmac_f32_e32 v25, v5, v34
	v_fma_f32 v26, v2, v18, v16
	v_fma_f32 v27, v3, v18, v17
	v_mov_b32_e32 v16, v19
	v_fmac_f32_e32 v24, v0, v18
	v_fmac_f32_e32 v25, v1, v18
	v_fmac_f32_e32 v56, v70, v16
	v_fmac_f32_e32 v57, v71, v16
	v_fmac_f32_e32 v58, v68, v16
	v_fmac_f32_e32 v59, v69, v16
	ds_read_b128 v[16:19], v204
	ds_read_b128 v[32:35], v204 offset:4096
	ds_read2_b32 v[68:69], v107 offset0:232 offset1:236
	v_add_co_u32_e32 v70, vcc, s39, v108
	s_waitcnt vmcnt(14) lgkmcnt(2)
; __device__ __forceinline__ void gla_sample_unit(const Args& a, unsigned char* lds, int unit, int tid) {
;     ...
;     for (int g = 0; g < 8; ++g) {
;         if (g + 1 < 8) {
; #pragma unroll
;             for (int i = 0; i < 8; ++i) sb[(g + 1) & 1][i] = *(const f32x4*)(S0 + (size_t)(((g + 1) * 8 + i) * 4 + kq) * 512 + vc); }
; #pragma unroll
;         for (int i = 0; i < 8; ++i) { const int k = (g * 8 + i) * 4 + kq; const f32x4 s = sb[g & 1][i];
;             const f32x4 qv = *(const f32x4*)(Q4 + k * 4), kd = *(const f32x4*)(KD4 + k * 4); const float dec = DECS[k];
;             f32x4 sn = s * dec;
; #pragma unroll
;             for (int t = 0; t < 4; ++t) { sn += vr[t] * kd[t]; o[t] += s * qv[t]; }
;             *(f32x4*)(SN + (size_t)k * 512 + vc) = sn; } }
	v_fmac_f32_e32 v64, v62, v16
	v_fmac_f32_e32 v65, v63, v16
	v_addc_co_u32_e32 v71, vcc, 0, v109, vcc
	global_store_dwordx4 v[70:71], v[24:27], off nt
	v_fmac_f32_e32 v66, v60, v16
	v_fmac_f32_e32 v67, v61, v16
	v_fmac_f32_e32 v40, v62, v17
	v_fmac_f32_e32 v41, v63, v17
	s_waitcnt lgkmcnt(0)
	v_mul_f32_e32 v24, v62, v68
	v_mul_f32_e32 v25, v63, v68
	v_mul_f32_e32 v26, v60, v68
	v_mul_f32_e32 v27, v61, v68
	v_fmac_f32_e32 v24, v14, v32
	v_fmac_f32_e32 v25, v15, v32
	v_fmac_f32_e32 v26, v12, v32
	v_fmac_f32_e32 v27, v13, v32
	v_fmac_f32_e32 v24, v10, v33
	v_fmac_f32_e32 v25, v11, v33
	v_fmac_f32_e32 v26, v8, v33
	v_fmac_f32_e32 v27, v9, v33
	v_fmac_f32_e32 v50, v60, v17
	v_fmac_f32_e32 v51, v61, v17
	v_fma_f32 v16, v6, v34, v24
	v_fma_f32 v17, v7, v34, v25
	v_fmac_f32_e32 v42, v62, v18
	v_fmac_f32_e32 v43, v63, v18
	v_fmac_f32_e32 v48, v60, v18
	v_fmac_f32_e32 v49, v61, v18
	v_mov_b32_e32 v18, v35
	v_fma_f32 v24, v4, v34, v26
	v_fma_f32 v25, v5, v34, v27
	v_fma_f32 v26, v2, v18, v16
	v_fma_f32 v27, v3, v18, v17
	v_mov_b32_e32 v16, v19
	v_fmac_f32_e32 v24, v0, v18
	v_fmac_f32_e32 v25, v1, v18
	v_fmac_f32_e32 v56, v62, v16
	v_fmac_f32_e32 v57, v63, v16
	v_fmac_f32_e32 v58, v60, v16
	v_fmac_f32_e32 v59, v61, v16
	ds_read_b128 v[16:19], v205
	ds_read_b128 v[32:35], v205 offset:4096
	v_add_co_u32_e32 v60, vcc, s40, v108
	s_waitcnt vmcnt(14) lgkmcnt(1)
	v_fma_f32 v62, v52, v16, v66
	v_fma_f32 v63, v53, v16, v67
	v_addc_co_u32_e32 v61, vcc, 0, v109, vcc
	global_store_dwordx4 v[60:61], v[24:27], off nt
	v_fma_f32 v60, v54, v16, v64
	v_fma_f32 v61, v55, v16, v65
	v_fmac_f32_e32 v40, v54, v17
	v_fmac_f32_e32 v41, v55, v17
	v_mov_b32_e32 v24, v69
	v_mul_f32_e32 v26, v54, v24
	v_mul_f32_e32 v27, v55, v24
	v_mul_f32_e32 v25, v53, v24
	v_mul_f32_e32 v24, v52, v24
	s_waitcnt lgkmcnt(0)
	v_fmac_f32_e32 v26, v14, v32
	v_fmac_f32_e32 v27, v15, v32
	v_fmac_f32_e32 v24, v12, v32
	v_fmac_f32_e32 v25, v13, v32
	v_fmac_f32_e32 v26, v10, v33
	v_fmac_f32_e32 v27, v11, v33
	v_fmac_f32_e32 v24, v8, v33
	v_fmac_f32_e32 v25, v9, v33
	v_fmac_f32_e32 v50, v52, v17
	v_fmac_f32_e32 v51, v53, v17
	v_fma_f32 v16, v6, v34, v26
	v_fma_f32 v17, v7, v34, v27
	v_fmac_f32_e32 v42, v54, v18
	v_fmac_f32_e32 v43, v55, v18
	v_fmac_f32_e32 v48, v52, v18
	v_fmac_f32_e32 v49, v53, v18
	v_mov_b32_e32 v18, v35
	v_fmac_f32_e32 v24, v4, v34
	v_fmac_f32_e32 v25, v5, v34
	v_fma_f32 v26, v2, v18, v16
	v_fma_f32 v27, v3, v18, v17
	v_mov_b32_e32 v16, v19
	v_fmac_f32_e32 v24, v0, v18
	v_fmac_f32_e32 v25, v1, v18
	v_fma_f32 v54, v54, v16, v56
	v_fma_f32 v55, v55, v16, v57
	v_fma_f32 v52, v52, v16, v58
	v_fma_f32 v53, v53, v16, v59
	ds_read_b128 v[16:19], v206
	ds_read_b128 v[32:35], v206 offset:4096
	ds_read2_b32 v[56:57], v107 offset0:240 offset1:244
	v_add_co_u32_e32 v58, vcc, s41, v108
	s_waitcnt vmcnt(14) lgkmcnt(2)
	v_fmac_f32_e32 v40, v46, v17
	v_fmac_f32_e32 v41, v47, v17
	v_addc_co_u32_e32 v59, vcc, 0, v109, vcc
	global_store_dwordx4 v[58:59], v[24:27], off nt
	v_fma_f32 v58, v46, v16, v60
	v_fma_f32 v59, v47, v16, v61
	v_fma_f32 v60, v44, v16, v62
	v_fma_f32 v61, v45, v16, v63
	s_waitcnt lgkmcnt(0)
	v_mul_f32_e32 v24, v46, v56
	v_mul_f32_e32 v25, v47, v56
	v_mul_f32_e32 v26, v44, v56
	v_mul_f32_e32 v27, v45, v56
	v_fmac_f32_e32 v24, v14, v32
	v_fmac_f32_e32 v25, v15, v32
	v_fmac_f32_e32 v26, v12, v32
	v_fmac_f32_e32 v27, v13, v32
	v_fmac_f32_e32 v24, v10, v33
	v_fmac_f32_e32 v25, v11, v33
	v_fmac_f32_e32 v26, v8, v33
	v_fmac_f32_e32 v27, v9, v33
	v_fmac_f32_e32 v50, v44, v17
	v_fmac_f32_e32 v51, v45, v17
	v_fma_f32 v16, v6, v34, v24
	v_fma_f32 v17, v7, v34, v25
	v_fmac_f32_e32 v42, v46, v18
	v_fmac_f32_e32 v43, v47, v18
	v_fmac_f32_e32 v48, v44, v18
	v_fmac_f32_e32 v49, v45, v18
	v_mov_b32_e32 v18, v35
	v_fma_f32 v24, v4, v34, v26
	v_fma_f32 v25, v5, v34, v27
	v_fma_f32 v26, v2, v18, v16
	v_fma_f32 v27, v3, v18, v17
	v_mov_b32_e32 v16, v19
	v_fmac_f32_e32 v24, v0, v18
	v_fmac_f32_e32 v25, v1, v18
	v_fma_f32 v46, v46, v16, v54
	v_fma_f32 v47, v47, v16, v55
	v_fma_f32 v44, v44, v16, v52
	v_fma_f32 v45, v45, v16, v53
	ds_read_b128 v[16:19], v207
	ds_read_b128 v[32:35], v207 offset:4096
	v_add_co_u32_e32 v52, vcc, s42, v108
	s_waitcnt vmcnt(14) lgkmcnt(1)
	v_fma_f32 v54, v36, v16, v60
	v_fma_f32 v55, v37, v16, v61
	v_addc_co_u32_e32 v53, vcc, 0, v109, vcc
	global_store_dwordx4 v[52:53], v[24:27], off nt
	v_fma_f32 v52, v38, v16, v58
	v_fma_f32 v53, v39, v16, v59
	v_fmac_f32_e32 v40, v38, v17
	v_fmac_f32_e32 v41, v39, v17
	v_mov_b32_e32 v24, v57
	v_mul_f32_e32 v26, v38, v24
	v_mul_f32_e32 v27, v39, v24
	v_mul_f32_e32 v25, v37, v24
	v_mul_f32_e32 v24, v36, v24
	s_waitcnt lgkmcnt(0)
	v_fmac_f32_e32 v26, v14, v32
	v_fmac_f32_e32 v27, v15, v32
	v_fmac_f32_e32 v24, v12, v32
	v_fmac_f32_e32 v25, v13, v32
	v_fmac_f32_e32 v26, v10, v33
	v_fmac_f32_e32 v27, v11, v33
	v_fmac_f32_e32 v24, v8, v33
	v_fmac_f32_e32 v25, v9, v33
	v_fmac_f32_e32 v50, v36, v17
	v_fmac_f32_e32 v51, v37, v17
	v_fma_f32 v16, v6, v34, v26
	v_fma_f32 v17, v7, v34, v27
	v_fmac_f32_e32 v42, v38, v18
	v_fmac_f32_e32 v43, v39, v18
	v_fmac_f32_e32 v48, v36, v18
	v_fmac_f32_e32 v49, v37, v18
	v_mov_b32_e32 v18, v35
	v_fmac_f32_e32 v24, v4, v34
	v_fmac_f32_e32 v25, v5, v34
	v_fma_f32 v26, v2, v18, v16
	v_fma_f32 v27, v3, v18, v17
	v_mov_b32_e32 v16, v19
	v_fmac_f32_e32 v24, v0, v18
	v_fmac_f32_e32 v25, v1, v18
	v_fma_f32 v38, v38, v16, v46
	v_fma_f32 v39, v39, v16, v47
	v_fma_f32 v36, v36, v16, v44
	v_fma_f32 v37, v37, v16, v45
	ds_read_b128 v[16:19], v208
	ds_read_b128 v[32:35], v208 offset:4096
	ds_read2_b32 v[44:45], v107 offset0:248 offset1:252
	v_add_co_u32_e32 v46, vcc, s43, v108
	s_waitcnt vmcnt(14) lgkmcnt(2)
; __device__ __forceinline__ void gla_sample_unit(const Args& a, unsigned char* lds, int unit, int tid) {
;     ...
;         for (int i = 0; i < 8; ++i) { const int k = (g * 8 + i) * 4 + kq; const f32x4 s = sb[g & 1][i];
;             const f32x4 qv = *(const f32x4*)(Q4 + k * 4), kd = *(const f32x4*)(KD4 + k * 4); const float dec = DECS[k];
;             f32x4 sn = s * dec;
; #pragma unroll
;             for (int t = 0; t < 4; ++t) { sn += vr[t] * kd[t]; o[t] += s * qv[t]; }
;             *(f32x4*)(SN + (size_t)k * 512 + vc) = sn; } }
; #pragma unroll
;     for (int t = 0; t < 4; ++t) *(f32x4*)(ORED + (kq * 4 + t) * 512 + vc) = o[t];
;     __syncthreads();
;     { const int t = tid >> 7, v4 = (tid & 127) * 4; f32x4 ov = (f32x4){0.f, 0.f, 0.f, 0.f};
; #pragma unroll
;       for (int q = 0; q < 4; ++q) ov += *(const f32x4*)(ORED + (q * 4 + t) * 512 + v4);
; #pragma unroll
;       for (int m = 0; m < 4; ++m) ov += *(const f32x4*)(VS + m * 512 + v4) * AS[t * 4 + m];
;       float ss = (ov[0] * ov[0] + ov[1] * ov[1]) + (ov[2] * ov[2] + ov[3] * ov[3]); ss = wave_sum(ss);
;       if (lane == 0) RED[wave] = ss;
	v_fmac_f32_e32 v42, v30, v18
	v_fmac_f32_e32 v43, v31, v18
	v_addc_co_u32_e32 v47, vcc, 0, v109, vcc
	global_store_dwordx4 v[46:47], v[24:27], off nt
	v_fma_f32 v46, v30, v16, v52
	v_fma_f32 v47, v31, v16, v53
	v_fma_f32 v52, v28, v16, v54
	v_fma_f32 v53, v29, v16, v55
	s_waitcnt lgkmcnt(0)
	v_mul_f32_e32 v24, v30, v44
	v_mul_f32_e32 v25, v31, v44
	v_mul_f32_e32 v26, v28, v44
	v_mul_f32_e32 v27, v29, v44
	v_fmac_f32_e32 v24, v14, v32
	v_fmac_f32_e32 v25, v15, v32
	v_fmac_f32_e32 v26, v12, v32
	v_fmac_f32_e32 v27, v13, v32
	v_fmac_f32_e32 v24, v10, v33
	v_fmac_f32_e32 v25, v11, v33
	v_fmac_f32_e32 v26, v8, v33
	v_fmac_f32_e32 v27, v9, v33
	v_fma_f32 v32, v30, v17, v40
	v_fma_f32 v33, v31, v17, v41
	v_fma_f32 v40, v28, v17, v50
	v_fma_f32 v41, v29, v17, v51
	v_fma_f32 v16, v6, v34, v24
	v_fma_f32 v17, v7, v34, v25
	v_fmac_f32_e32 v48, v28, v18
	v_fmac_f32_e32 v49, v29, v18
	v_mov_b32_e32 v18, v35
	v_fma_f32 v24, v4, v34, v26
	v_fma_f32 v25, v5, v34, v27
	v_fma_f32 v26, v2, v18, v16
	v_fma_f32 v27, v3, v18, v17
	v_mov_b32_e32 v16, v19
	v_fmac_f32_e32 v24, v0, v18
	v_fmac_f32_e32 v25, v1, v18
	v_fma_f32 v34, v30, v16, v38
	v_fma_f32 v35, v31, v16, v39
	v_fmac_f32_e32 v36, v28, v16
	v_fmac_f32_e32 v37, v29, v16
	ds_read_b128 v[28:31], v209
	ds_read_b128 v[16:19], v209 offset:4096
	v_add_co_u32_e32 v38, vcc, s44, v108
	s_nop 1
	v_addc_co_u32_e32 v39, vcc, 0, v109, vcc
	global_store_dwordx4 v[38:39], v[24:27], off nt
	s_nop 1
	v_mov_b32_e32 v24, v45
	s_waitcnt vmcnt(15)
	v_mul_f32_e32 v26, v22, v24
	v_mul_f32_e32 v27, v23, v24
	v_mul_f32_e32 v25, v21, v24
	v_mul_f32_e32 v24, v20, v24
	s_waitcnt lgkmcnt(0)
	v_fmac_f32_e32 v26, v14, v16
	v_fmac_f32_e32 v27, v15, v16
	v_fmac_f32_e32 v24, v12, v16
	v_fmac_f32_e32 v25, v13, v16
	v_fmac_f32_e32 v26, v10, v17
	v_fmac_f32_e32 v27, v11, v17
	v_fma_f32 v16, v8, v17, v24
	v_fma_f32 v17, v9, v17, v25
	v_fma_f32 v24, v6, v18, v26
	v_fma_f32 v25, v7, v18, v27
	v_fmac_f32_e32 v16, v4, v18
	v_fmac_f32_e32 v17, v5, v18
	v_mov_b32_e32 v26, v19
	v_fmac_f32_e32 v16, v0, v26
	v_fmac_f32_e32 v17, v1, v26
	v_mov_b32_e32 v0, v31
	v_fma_f32 v12, v20, v28, v52
	v_fma_f32 v13, v21, v28, v53
	v_fma_f32 v8, v20, v29, v40
	v_fma_f32 v9, v21, v29, v41
	v_fma_f32 v4, v20, v30, v48
	v_fma_f32 v5, v21, v30, v49
	v_fma_f32 v18, v2, v26, v24
	v_fma_f32 v19, v3, v26, v25
	v_fma_f32 v2, v22, v0, v34
	v_fma_f32 v3, v23, v0, v35
	v_fma_f32 v1, v21, v0, v37
	v_fma_f32 v0, v20, v0, v36
	v_add_co_u32_e32 v20, vcc, s45, v108
	v_fma_f32 v14, v22, v28, v46
	v_fma_f32 v15, v23, v28, v47
	v_fma_f32 v10, v22, v29, v32
	v_fma_f32 v11, v23, v29, v33
	v_fma_f32 v6, v22, v30, v42
	v_fma_f32 v7, v23, v30, v43
	v_addc_co_u32_e32 v21, vcc, 0, v109, vcc
	global_store_dwordx4 v[20:21], v[16:19], off nt
	ds_write_b128 v210, v[12:15] offset:21632
	ds_write_b128 v210, v[8:11] offset:23680
	ds_write_b128 v210, v[4:7] offset:25728
	ds_write_b128 v210, v[0:3] offset:27776
	s_waitcnt lgkmcnt(0)
	s_barrier
	ds_read_b128 v[0:3], v211 offset:21632
	ds_read_b128 v[4:7], v211 offset:29824
	ds_read_b128 v[8:11], v211 offset:46208
	ds_read_b128 v[12:15], v211 offset:38016
	s_waitcnt lgkmcnt(3)
	v_add_f32_e32 v2, 0, v2
	v_add_f32_e32 v3, 0, v3
	v_add_f32_e32 v0, 0, v0
	v_add_f32_e32 v1, 0, v1
	s_waitcnt lgkmcnt(2)
	v_add_f32_e32 v6, v2, v6
	v_add_f32_e32 v7, v3, v7
	v_add_f32_e32 v4, v0, v4
	v_add_f32_e32 v5, v1, v5
	ds_read_b128 v[0:3], v140 offset:19584
	s_waitcnt lgkmcnt(1)
	v_add_f32_e32 v16, v6, v14
	v_add_f32_e32 v17, v7, v15
	v_add_f32_e32 v20, v4, v12
	v_add_f32_e32 v21, v5, v13
	ds_read_b128 v[4:7], v140 offset:13440
	ds_read_b128 v[12:15], v138 offset:13312
	v_add_f32_e32 v22, v16, v10
	v_add_f32_e32 v23, v17, v11
	ds_read_b128 v[16:19], v140 offset:15488
	v_add_f32_e32 v20, v20, v8
	v_add_f32_e32 v21, v21, v9
	ds_read_b128 v[8:11], v140 offset:17536
	s_waitcnt lgkmcnt(2)
	v_fma_f32 v6, v6, v12, v22
	v_fma_f32 v7, v7, v12, v23
	v_fma_f32 v4, v4, v12, v20
	v_fma_f32 v5, v5, v12, v21
	s_waitcnt lgkmcnt(1)
	v_fmac_f32_e32 v6, v18, v13
	v_fmac_f32_e32 v7, v19, v13
	v_fmac_f32_e32 v4, v16, v13
	v_fmac_f32_e32 v5, v17, v13
	s_waitcnt lgkmcnt(0)
	v_fmac_f32_e32 v6, v10, v14
	v_fmac_f32_e32 v7, v11, v14
	v_fmac_f32_e32 v4, v8, v14
	v_fmac_f32_e32 v5, v9, v14
	v_mov_b32_e32 v8, v15
	v_fmac_f32_e32 v6, v2, v8
	v_fmac_f32_e32 v7, v3, v8
	v_fma_f32 v9, v1, v8, v5
	v_fma_f32 v8, v0, v8, v4
	v_mul_f32_e32 v1, v7, v7
	v_mul_f32_e32 v0, v9, v9
	v_fmac_f32_e32 v0, v8, v8
	v_fmac_f32_e32 v1, v6, v6
	v_add_f32_e32 v0, v0, v1
	ds_bpermute_b32 v1, v129, v0
	s_waitcnt lgkmcnt(0)
	v_add_f32_e32 v0, v0, v1
	ds_bpermute_b32 v1, v130, v0
	s_waitcnt lgkmcnt(0)
	v_add_f32_e32 v0, v0, v1
	ds_bpermute_b32 v1, v131, v0
	s_waitcnt lgkmcnt(0)
	v_add_f32_e32 v0, v0, v1
	ds_bpermute_b32 v1, v132, v0
	s_waitcnt lgkmcnt(0)
	v_add_f32_e32 v0, v0, v1
	ds_bpermute_b32 v1, v85, v0
	s_waitcnt lgkmcnt(0)
	v_add_f32_e32 v0, v0, v1
	ds_bpermute_b32 v1, v128, v0
	s_and_saveexec_b64 s[0:1], s[12:13]
	s_cbranch_execz .LBB0_383
	s_waitcnt lgkmcnt(0)
	v_add_f32_e32 v0, v0, v1
	ds_write_b32 v212, v0 offset:13376
	s_branch .LBB0_383

; __device__ __forceinline__ float bflo(unsigned w) { return __uint_as_float(w << 16); }
; __device__ __forceinline__ float bfhi(unsigned w) { return __uint_as_float(w & 0xffff0000u); }
; __device__ __forceinline__ void swa_sample_unit(const Args& a, unsigned char* lds, int unit, int tid) {
;     ...
;     for (int e = tid; e < 132 * 16; e += 512) { const int j = e >> 4, c = e & 15; f32x4 kv, vv;
;         if (j < 128) { const size_t o = ((size_t)(b * 128 + j) * 4 + kvh) * 64 + c * 4; kv = *(const f32x4*)(a.ck + o); vv = *(const f32x4*)(a.cv + o); }
;         else { const int i = j - 128; const bf16_t* kp = Z + (row0 + i) * DINP + ZKS + kvh * 64; const u32x2 kw = *(const u32x2*)(kp + c * 4); const u32x2 vw = *(const u32x2*)(Z + (row0 + i) * DINP + ZVS + kvh * 64 + c * 4);
;             kv = (f32x4){bflo(kw.x), bfhi(kw.x), bflo(kw.y), bfhi(kw.y)}; vv = (f32x4){bflo(vw.x), bfhi(vw.x), bflo(vw.y), bfhi(vw.y)};
;             if (c < 4) { const u32x2 pw = *(const u32x2*)(kp + (c ^ 2) * 4); const f32x4 pv = (f32x4){bflo(pw.x), bfhi(pw.x), bflo(pw.y), bfhi(pw.y)}; const float sg = c < 2 ? -1.f : 1.f;
;                 const f32x2* rp = ROPE + (2048 + i) * 8 + (c & 1) * 4;
; #pragma unroll
;                 for (int d = 0; d < 4; ++d) { const f32x2 cs = rp[d]; kv[d] = kv[d] * cs.x + sg * pv[d] * cs.y; }
;             } }
.LBB0_395:
	v_cmp_lt_u32_e32 vcc, s36, v37
	s_and_saveexec_b64 s[30:31], vcc
	s_xor_b64 s[30:31], exec, s[30:31]
	s_cbranch_execz .LBB0_399
	v_lshl_add_u64 v[0:1], s[22:23], 0, v[8:9]
	v_mov_b64_e32 v[2:3], s[24:25]
	v_mad_u64_u32 v[4:5], s[34:35], v0, s37, v[2:3]
	v_mad_i32_i24 v5, v1, s37, v5
	v_lshlrev_b32_e32 v0, 1, v88
	v_mov_b32_e32 v1, v9
	v_lshl_add_u64 v[0:1], v[4:5], 0, v[0:1]
	global_load_dwordx2 v[2:3], v[0:1], off offset:2048
	global_load_dwordx2 v[6:7], v[0:1], off offset:2560
	s_waitcnt vmcnt(1)
	v_lshlrev_b32_e32 v0, 16, v2
	v_and_b32_e32 v1, 0xffff0000, v2
	v_lshlrev_b32_e32 v2, 16, v3
	v_and_b32_e32 v3, 0xffff0000, v3
	s_and_saveexec_b64 s[34:35], s[6:7]
	s_cbranch_execz .LBB0_398
	v_lshlrev_b32_e32 v38, 1, v10
	v_mov_b32_e32 v39, v9
	v_lshl_add_u64 v[4:5], v[4:5], 0, v[38:39]
	v_lshl_add_u64 v[42:43], v[18:19], 0, s[28:29]
	global_load_dwordx2 v[4:5], v[4:5], off offset:2048
	v_lshl_add_u64 v[38:39], v[42:43], 0, s[18:19]
	v_add_co_u32_e32 v42, vcc, 0xbe000, v42
	global_load_dwordx4 v[38:41], v[38:39], off offset:16 nt
	s_nop 0
	v_addc_co_u32_e32 v43, vcc, 0, v43, vcc
	global_load_dwordx4 v[42:45], v[42:43], off nt
	v_mov_b32_e32 v46, v1
	v_mov_b32_e32 v48, v3
	s_waitcnt vmcnt(2)
	v_lshlrev_b32_e32 v1, 16, v4
	v_and_b32_e32 v3, 0xffff0000, v4
	v_lshlrev_b32_e32 v4, 16, v5
	v_and_b32_e32 v5, 0xffff0000, v5
	v_cndmask_b32_e64 v1, v1, -v1, s[8:9]
	v_cndmask_b32_e64 v47, v3, -v3, s[8:9]
	v_cndmask_b32_e64 v49, v5, -v5, s[8:9]
	v_cndmask_b32_e64 v3, v4, -v4, s[8:9]
	s_waitcnt vmcnt(0)
	v_mul_f32_e32 v0, v42, v0
	v_mul_f32_e32 v1, v43, v1
	v_mul_f32_e32 v4, v44, v46
	v_mul_f32_e32 v5, v45, v47
	v_mul_f32_e32 v40, v40, v48
	v_mul_f32_e32 v41, v41, v49
	v_mul_f32_e32 v2, v38, v2
	v_mul_f32_e32 v38, v3, v39
	v_mov_b32_e32 v42, v1
	v_mov_b32_e32 v43, v5
	v_mov_b32_e32 v1, v4
	v_mov_b32_e32 v3, v40
	v_mov_b32_e32 v39, v41
	v_add_f32_e32 v0, v0, v42
	v_add_f32_e32 v1, v1, v43
	v_add_f32_e32 v2, v2, v38
	v_add_f32_e32 v3, v3, v39

; __device__ __forceinline__ float bflo(unsigned w) { return __uint_as_float(w << 16); }
; __device__ __forceinline__ float bfhi(unsigned w) { return __uint_as_float(w & 0xffff0000u); }
; __device__ __forceinline__ void swa_sample_unit(const Args& a, unsigned char* lds, int unit, int tid) {
;     ...
;     if (tid < 256) { const int pr = tid >> 4, c = tid & 15, g = pr >> 2, i = pr & 3; const bf16_t* qp = Z + (row0 + i) * DINP + ZQS + (kvh * 4 + g) * 64; const u32x2 qw = *(const u32x2*)(qp + c * 4);
;         f32x4 qv = (f32x4){bflo(qw.x), bfhi(qw.x), bflo(qw.y), bfhi(qw.y)};
;         if (c < 4) { const u32x2 pw = *(const u32x2*)(qp + (c ^ 2) * 4); const f32x4 pv = (f32x4){bflo(pw.x), bfhi(pw.x), bflo(pw.y), bfhi(pw.y)}; const float sg = c < 2 ? -1.f : 1.f;
;             const f32x2* rp = ROPE + (2048 + i) * 8 + (c & 1) * 4;
; #pragma unroll
;             for (int d = 0; d < 4; ++d) { const f32x2 cs = rp[d]; qv[d] = qv[d] * cs.x + sg * pv[d] * cs.y; } }
;         *(f32x4*)(QS + pr * 64 + c * 4) = qv * 0.125f; }
.LBB0_403:
	s_or_b64 exec, exec, s[26:27]
	s_and_saveexec_b64 s[24:25], s[4:5]
	s_cbranch_execz .LBB0_407
	v_or_b32_e32 v2, s22, v86
	v_mov_b64_e32 v[0:1], s[74:75]
	v_mad_u64_u32 v[0:1], s[26:27], v2, s37, v[0:1]
	v_mad_i32_i24 v1, s23, v32, v1
	v_lshl_or_b32 v8, s41, 9, v31
	v_lshl_add_u64 v[4:5], v[0:1], 0, v[8:9]
	v_lshlrev_b32_e32 v8, 1, v88
	v_lshl_add_u64 v[0:1], v[4:5], 0, v[8:9]
	global_load_dwordx2 v[0:1], v[0:1], off
	s_waitcnt vmcnt(0)
	v_lshlrev_b32_e32 v2, 16, v0
	v_and_b32_e32 v3, 0xffff0000, v0
	v_lshlrev_b32_e32 v0, 16, v1
	v_and_b32_e32 v1, 0xffff0000, v1
	s_and_saveexec_b64 s[26:27], s[6:7]
	s_cbranch_execz .LBB0_406
	v_lshlrev_b32_e32 v8, 1, v10
	v_lshl_add_u64 v[36:37], v[4:5], 0, v[8:9]
	global_load_dwordx4 v[4:7], v[12:13], off offset:16 nt
	global_load_dwordx2 v[40:41], v[36:37], off
	s_nop 0
	global_load_dwordx4 v[36:39], v[12:13], off nt
	v_mov_b32_e32 v44, v1
	v_mov_b32_e32 v42, v3
	s_waitcnt vmcnt(2)
	v_mul_f32_e32 v0, v4, v0
	s_waitcnt vmcnt(1)
	v_lshlrev_b32_e32 v1, 16, v40
	v_and_b32_e32 v4, 0xffff0000, v40
	v_and_b32_e32 v20, 0xffff0000, v41
	v_lshlrev_b32_e32 v8, 16, v41
	v_cndmask_b32_e64 v3, v1, -v1, s[8:9]
	v_cndmask_b32_e64 v43, v4, -v4, s[8:9]
	v_cndmask_b32_e64 v45, v20, -v20, s[8:9]
	v_cndmask_b32_e64 v1, v8, -v8, s[8:9]
	s_waitcnt vmcnt(0)
	v_mul_f32_e32 v2, v36, v2
	v_mul_f32_e32 v3, v37, v3
	v_mul_f32_e32 v36, v38, v42
	v_mul_f32_e32 v37, v39, v43
	v_mul_f32_e32 v6, v6, v44
	v_mul_f32_e32 v7, v7, v45
	v_mul_f32_e32 v4, v1, v5
	v_mov_b32_e32 v38, v3
	v_mov_b32_e32 v39, v37
	v_mov_b32_e32 v3, v36
	v_mov_b32_e32 v1, v6
	v_mov_b32_e32 v5, v7
	v_add_f32_e32 v2, v2, v38
	v_add_f32_e32 v3, v3, v39
	v_add_f32_e32 v0, v0, v4
	v_add_f32_e32 v1, v1, v5
.LBB0_406:
	s_or_b64 exec, exec, s[26:27]
	v_mul_f32_e32 v4, s20, v0
	v_mul_f32_e32 v5, s20, v1
	v_mul_f32_e32 v2, s20, v2
	v_mul_f32_e32 v3, s20, v3
	ds_write_b128 v11, v[2:5]

; __device__ __forceinline__ unsigned cvt_pk_bf16(float lo, float hi) { unsigned r; asm volatile("v_cvt_pk_bf16_f32 %0, %1, %2" : "=v"(r) : "v"(lo), "v"(hi)); return r; }
; #define MFMA_SETTLE1(a) asm volatile("s_nop 15\n\ts_nop 15" : "+v"(a))
; #define LBAR() asm volatile("s_waitcnt lgkmcnt(0)\n\ts_barrier" ::: "memory")
; __device__ __forceinline__ void gla_prompt_unit(const Args& a, unsigned char* lds, int unit, int tid) {
;     ...
; #pragma unroll
;         for (int kk = 0; kk < 8; ++kk) { const bf16x8 af = *(const bf16x8*)(ST + (vt * 16 + r16) * 528 + kk * 64 + q4 * 16); const bf16x8 bfg = *(const bf16x8*)(QI + (lt * 16 + r16) * 528 + kk * 64 + q4 * 16);
;             oacc = __builtin_amdgcn_mfma_f32_16x16x32_bf16(af, bfg, oacc, 0, 0, 0); }
;         { const bf16x8 af = *(const bf16x8*)(VT + (vt * 16 + r16) * 80 + q4 * 16); const bf16x8 bfg = *(const bf16x8*)(AM + (lt * 16 + r16) * 80 + q4 * 16);
;           oacc = __builtin_amdgcn_mfma_f32_16x16x32_bf16(af, bfg, oacc, 0, 0, 0);
;           MFMA_SETTLE1(oacc);
;           const size_t row = row0 + lt * 16 + r16;
;           *(u32x2*)(OCAT + row * OC + 1024 + h * 512 + vs * 64 + vt * 16 + q4 * 4) = (u32x2){cvt_pk_bf16(oacc[0], oacc[1]), cvt_pk_bf16(oacc[2], oacc[3])};
;           float ss = (oacc[0] * oacc[0] + oacc[1] * oacc[1]) + (oacc[2] * oacc[2] + oacc[3] * oacc[3]); ss += __shfl_xor(ss, 16); ss += __shfl_xor(ss, 32);
;           if (lane < 16) GSS[(row * 4 + h) * 32 + vs * 4 + vt] = ss; }
;         LBAR();
; #pragma unroll
;         for (int k2 = 0; k2 < 2; ++k2) { const int kt = wave * 2 + k2; const f32x4 dec4 = *(const f32x4*)(DEC + kt * 16 + q4 * 4); const bf16x8 af = *(const bf16x8*)(KDT + (kt * 16 + r16) * 80 + q4 * 16);
; #pragma unroll
;             for (int v2 = 0; v2 < 4; ++v2) { const bf16x8 bfg = *(const bf16x8*)(VT + (v2 * 16 + r16) * 80 + q4 * 16);
;                 sacc[k2][v2] = __builtin_amdgcn_mfma_f32_16x16x32_bf16(af, bfg, sacc[k2][v2] * dec4, 0, 0, 0); } }
.Lgn_a507:
	s_or_b64 exec, exec, s[30:31]
	s_waitcnt lgkmcnt(0)
	s_barrier
	s_cmp_gt_u32 s96, 3
	s_cbranch_scc1 .Lgn_store
	ds_read_b128 v[178:181], v224
	ds_read_b128 v[162:165], v222
	ds_read_b128 v[166:169], v222 offset:8448
	ds_read_b128 v[170:173], v222 offset:64
	ds_read_b128 v[174:177], v222 offset:8512
	ds_read_b128 v[236:239], v222 offset:128
	ds_read_b128 v[240:243], v222 offset:8576
	ds_read_b128 v[244:247], v222 offset:192
	ds_read_b128 v[250:253], v222 offset:8640
	v_cvt_pk_bf16_f32 v150, v8, v9
	v_cvt_pk_bf16_f32 v151, v10, v11
	v_cvt_pk_bf16_f32 v152, v12, v13
	v_cvt_pk_bf16_f32 v153, v14, v15
	s_waitcnt lgkmcnt(6)
	s_nop 0
	v_mfma_f32_16x16x32_bf16 v[142:145], v[150:153], v[162:165], 0
	v_mfma_f32_16x16x32_bf16 v[158:161], v[150:153], v[166:169], 0
	ds_read_b128 v[162:165], v222 offset:256
	ds_read_b128 v[166:169], v222 offset:8704
	v_cvt_pk_bf16_f32 v154, v16, v17
	v_cvt_pk_bf16_f32 v155, v18, v19
	v_cvt_pk_bf16_f32 v156, v20, v21
	v_cvt_pk_bf16_f32 v157, v22, v23
	s_waitcnt lgkmcnt(6)
	s_nop 0
	v_mfma_f32_16x16x32_bf16 v[142:145], v[154:157], v[170:173], v[142:145]
	v_mfma_f32_16x16x32_bf16 v[158:161], v[154:157], v[174:177], v[158:161]
	ds_read_b128 v[170:173], v222 offset:320
	ds_read_b128 v[174:177], v222 offset:8768
	v_cvt_pk_bf16_f32 v150, v24, v25
	v_cvt_pk_bf16_f32 v151, v26, v27
	v_cvt_pk_bf16_f32 v152, v28, v29
	v_cvt_pk_bf16_f32 v153, v30, v31
	s_waitcnt lgkmcnt(6)
	s_nop 0
	v_mfma_f32_16x16x32_bf16 v[142:145], v[150:153], v[236:239], v[142:145]
	v_mfma_f32_16x16x32_bf16 v[158:161], v[150:153], v[240:243], v[158:161]
	ds_read_b128 v[236:239], v222 offset:384
	ds_read_b128 v[240:243], v222 offset:8832
	v_cvt_pk_bf16_f32 v154, v32, v33
	v_cvt_pk_bf16_f32 v155, v34, v35
	v_cvt_pk_bf16_f32 v156, v36, v37
	v_cvt_pk_bf16_f32 v157, v38, v39
	s_waitcnt lgkmcnt(6)
	s_nop 0
	v_mfma_f32_16x16x32_bf16 v[142:145], v[154:157], v[244:247], v[142:145]
	v_mfma_f32_16x16x32_bf16 v[158:161], v[154:157], v[250:253], v[158:161]
	ds_read_b128 v[244:247], v222 offset:448
	ds_read_b128 v[250:253], v222 offset:8896
	v_cvt_pk_bf16_f32 v150, v190, v191
	v_cvt_pk_bf16_f32 v151, v192, v193
	v_cvt_pk_bf16_f32 v152, v194, v195
	v_cvt_pk_bf16_f32 v153, v196, v197
	s_waitcnt lgkmcnt(6)
	s_nop 0
	v_mfma_f32_16x16x32_bf16 v[142:145], v[150:153], v[162:165], v[142:145]
	v_mfma_f32_16x16x32_bf16 v[158:161], v[150:153], v[166:169], v[158:161]
	ds_read_b128 v[162:165], v223
	ds_read_b128 v[166:169], v223 offset:1280
	v_cvt_pk_bf16_f32 v154, v198, v199
	v_cvt_pk_bf16_f32 v155, v200, v201
	v_cvt_pk_bf16_f32 v156, v202, v203
	v_cvt_pk_bf16_f32 v157, v204, v205
	s_waitcnt lgkmcnt(6)
	s_nop 0
	v_mfma_f32_16x16x32_bf16 v[142:145], v[154:157], v[170:173], v[142:145]
	v_mfma_f32_16x16x32_bf16 v[158:161], v[154:157], v[174:177], v[158:161]
	v_cvt_pk_bf16_f32 v150, v206, v207
	v_cvt_pk_bf16_f32 v151, v208, v209
	v_cvt_pk_bf16_f32 v152, v210, v211
	v_cvt_pk_bf16_f32 v153, v212, v213
	s_waitcnt lgkmcnt(4)
	s_nop 0
	v_mfma_f32_16x16x32_bf16 v[142:145], v[150:153], v[236:239], v[142:145]
	v_mfma_f32_16x16x32_bf16 v[158:161], v[150:153], v[240:243], v[158:161]
	v_cvt_pk_bf16_f32 v154, v214, v215
	v_cvt_pk_bf16_f32 v155, v216, v217
	v_cvt_pk_bf16_f32 v156, v218, v219
	v_cvt_pk_bf16_f32 v157, v220, v221
	s_waitcnt lgkmcnt(2)
	s_nop 0
	v_mfma_f32_16x16x32_bf16 v[142:145], v[154:157], v[244:247], v[142:145]
	v_mfma_f32_16x16x32_bf16 v[158:161], v[154:157], v[250:253], v[158:161]
	s_waitcnt lgkmcnt(0)
	v_mfma_f32_16x16x32_bf16 v[142:145], v[178:181], v[162:165], v[142:145]
	v_mfma_f32_16x16x32_bf16 v[158:161], v[178:181], v[166:169], v[158:161]
	ds_read_b128 v[170:173], v225
	ds_read_b128 v[174:177], v226
	ds_read_b128 v[236:239], v225 offset:1280
	ds_read_b128 v[240:243], v226 offset:64
	ds_read_b128 v[244:247], v225 offset:2560
	ds_read_b128 v[250:253], v226 offset:128
	ds_read_b128 v[162:165], v225 offset:3840
	ds_read_b128 v[166:169], v226 offset:192
	s_waitcnt lgkmcnt(6)
	v_mul_f32_e32 v8, v8, v174
	v_mul_f32_e32 v9, v9, v175
	v_mul_f32_e32 v10, v10, v176
	v_mul_f32_e32 v11, v11, v177
	s_nop 1
	v_mfma_f32_16x16x32_bf16 v[8:11], v[170:173], v[178:181], v[8:11]
	ds_read_b128 v[170:173], v225 offset:5120
	ds_read_b128 v[174:177], v226 offset:256
	s_waitcnt lgkmcnt(6)
	v_mul_f32_e32 v12, v12, v240
	v_mul_f32_e32 v13, v13, v241
	v_mul_f32_e32 v14, v14, v242
	v_mul_f32_e32 v15, v15, v243
	s_nop 1
	v_mfma_f32_16x16x32_bf16 v[12:15], v[236:239], v[178:181], v[12:15]
	ds_read_b128 v[236:239], v225 offset:6400
	ds_read_b128 v[240:243], v226 offset:320
	v_mul_f32_e32 v150, v143, v143
	v_mul_f32_e32 v151, v145, v145
	v_fmac_f32_e32 v150, v142, v142
	v_fmac_f32_e32 v151, v144, v144
	v_add_f32_e32 v150, v150, v151
	ds_bpermute_b32 v151, v227, v150
	v_mul_f32_e32 v152, v159, v159
	v_mul_f32_e32 v153, v161, v161
	v_fmac_f32_e32 v152, v158, v158
	v_fmac_f32_e32 v153, v160, v160
	v_add_f32_e32 v152, v152, v153
	ds_bpermute_b32 v153, v227, v152
	s_waitcnt lgkmcnt(8)
; __device__ __forceinline__ unsigned cvt_pk_bf16(float lo, float hi) { unsigned r; asm volatile("v_cvt_pk_bf16_f32 %0, %1, %2" : "=v"(r) : "v"(lo), "v"(hi)); return r; }
; #define MFMA_SETTLE8(a, b, c, d, e, f, g, h) asm volatile("s_nop 15\n\ts_nop 15" : "+v"(a), "+v"(b), "+v"(c), "+v"(d), "+v"(e), "+v"(f), "+v"(g), "+v"(h))
; #define LBAR() asm volatile("s_waitcnt lgkmcnt(0)\n\ts_barrier" ::: "memory")
; __device__ __forceinline__ void gla_prompt_unit(const Args& a, unsigned char* lds, int unit, int tid) {
;     ...
;           const size_t row = row0 + lt * 16 + r16;
;           *(u32x2*)(OCAT + row * OC + 1024 + h * 512 + vs * 64 + vt * 16 + q4 * 4) = (u32x2){cvt_pk_bf16(oacc[0], oacc[1]), cvt_pk_bf16(oacc[2], oacc[3])};
;           float ss = (oacc[0] * oacc[0] + oacc[1] * oacc[1]) + (oacc[2] * oacc[2] + oacc[3] * oacc[3]); ss += __shfl_xor(ss, 16); ss += __shfl_xor(ss, 32);
;           if (lane < 16) GSS[(row * 4 + h) * 32 + vs * 4 + vt] = ss; }
;         LBAR();
; #pragma unroll
;         for (int k2 = 0; k2 < 2; ++k2) { const int kt = wave * 2 + k2; const f32x4 dec4 = *(const f32x4*)(DEC + kt * 16 + q4 * 4); const bf16x8 af = *(const bf16x8*)(KDT + (kt * 16 + r16) * 80 + q4 * 16);
; #pragma unroll
;             for (int v2 = 0; v2 < 4; ++v2) { const bf16x8 bfg = *(const bf16x8*)(VT + (v2 * 16 + r16) * 80 + q4 * 16);
;                 sacc[k2][v2] = __builtin_amdgcn_mfma_f32_16x16x32_bf16(af, bfg, sacc[k2][v2] * dec4, 0, 0, 0); } }
;         MFMA_SETTLE8(sacc[0][0], sacc[0][1], sacc[0][2], sacc[0][3], sacc[1][0], sacc[1][1], sacc[1][2], sacc[1][3]);
; #pragma unroll
;         for (int k2 = 0; k2 < 2; ++k2) { const int kt = wave * 2 + k2;
; #pragma unroll
;             for (int v2 = 0; v2 < 4; ++v2)
;                 *(u32x2*)(ST + (v2 * 16 + r16) * 528 + (kt * 16 + q4 * 4) * 2) = (u32x2){cvt_pk_bf16(sacc[k2][v2][0], sacc[k2][v2][1]), cvt_pk_bf16(sacc[k2][v2][2], sacc[k2][v2][3])}; }
	v_mul_f32_e32 v16, v16, v250
	v_mul_f32_e32 v17, v17, v251
	v_mul_f32_e32 v18, v18, v252
	v_mul_f32_e32 v19, v19, v253
	s_nop 1
	v_mfma_f32_16x16x32_bf16 v[16:19], v[244:247], v[178:181], v[16:19]
	ds_read_b128 v[244:247], v225 offset:7680
	ds_read_b128 v[250:253], v226 offset:384
	s_waitcnt lgkmcnt(8)
	v_mul_f32_e32 v20, v20, v166
	v_mul_f32_e32 v21, v21, v167
	v_mul_f32_e32 v22, v22, v168
	v_mul_f32_e32 v23, v23, v169
	s_nop 1
	v_mfma_f32_16x16x32_bf16 v[20:23], v[162:165], v[178:181], v[20:23]
	ds_read_b128 v[162:165], v225 offset:8960
	ds_read_b128 v[166:169], v226 offset:448
	v_cvt_pk_bf16_f32 v154, v142, v143
	v_cvt_pk_bf16_f32 v155, v144, v145
	v_cvt_pk_bf16_f32 v156, v158, v159
	v_cvt_pk_bf16_f32 v157, v160, v161
	s_and_b32 s97, s0, 1
	s_xor_b32 s97, s97, 1
	s_lshl_b32 s97, s97, 13
	v_add_u32_e32 v229, s97, v231
	ds_write_b64 v229, v[154:155]
	ds_write_b64 v229, v[156:157] offset:2304
	s_waitcnt lgkmcnt(10)
	v_mul_f32_e32 v24, v24, v174
	v_mul_f32_e32 v25, v25, v175
	v_mul_f32_e32 v26, v26, v176
	v_mul_f32_e32 v27, v27, v177
	s_nop 1
	v_mfma_f32_16x16x32_bf16 v[24:27], v[170:173], v[178:181], v[24:27]
	ds_read_b128 v[170:173], v225 offset:10240
	ds_read_b128 v[174:177], v226 offset:512
	s_waitcnt lgkmcnt(10)
	v_mul_f32_e32 v28, v28, v240
	v_mul_f32_e32 v29, v29, v241
	v_mul_f32_e32 v30, v30, v242
	v_mul_f32_e32 v31, v31, v243
	s_nop 1
	v_mfma_f32_16x16x32_bf16 v[28:31], v[236:239], v[178:181], v[28:31]
	ds_read_b128 v[236:239], v225 offset:11520
	ds_read_b128 v[240:243], v226 offset:576
	s_waitcnt lgkmcnt(8)
	v_mul_f32_e32 v32, v32, v250
	v_mul_f32_e32 v33, v33, v251
	v_mul_f32_e32 v34, v34, v252
	v_mul_f32_e32 v35, v35, v253
	s_nop 1
	v_mfma_f32_16x16x32_bf16 v[32:35], v[244:247], v[178:181], v[32:35]
	ds_read_b128 v[244:247], v225 offset:12800
	ds_read_b128 v[250:253], v226 offset:640
	v_add_f32_e32 v150, v150, v151
	v_add_f32_e32 v152, v152, v153
	ds_bpermute_b32 v151, v228, v150
	ds_bpermute_b32 v153, v228, v152
	s_waitcnt lgkmcnt(10)
	v_mul_f32_e32 v36, v36, v166
	v_mul_f32_e32 v37, v37, v167
	v_mul_f32_e32 v38, v38, v168
	v_mul_f32_e32 v39, v39, v169
	s_nop 1
	v_mfma_f32_16x16x32_bf16 v[36:39], v[162:165], v[178:181], v[36:39]
	ds_read_b128 v[162:165], v225 offset:14080
	ds_read_b128 v[166:169], v226 offset:704
	s_waitcnt lgkmcnt(8)
	v_mul_f32_e32 v190, v190, v174
	v_mul_f32_e32 v191, v191, v175
	v_mul_f32_e32 v192, v192, v176
	v_mul_f32_e32 v193, v193, v177
	s_nop 1
	v_mfma_f32_16x16x32_bf16 v[190:193], v[170:173], v[178:181], v[190:193]
	ds_read_b128 v[170:173], v225 offset:15360
	ds_read_b128 v[174:177], v226 offset:768
	s_waitcnt lgkmcnt(8)
	v_mul_f32_e32 v194, v194, v240
	v_mul_f32_e32 v195, v195, v241
	v_mul_f32_e32 v196, v196, v242
	v_mul_f32_e32 v197, v197, v243
	s_nop 1
	v_mfma_f32_16x16x32_bf16 v[194:197], v[236:239], v[178:181], v[194:197]
	ds_read_b128 v[236:239], v225 offset:16640
	ds_read_b128 v[240:243], v226 offset:832
	s_waitcnt lgkmcnt(8)
	v_mul_f32_e32 v198, v198, v250
	v_mul_f32_e32 v199, v199, v251
	v_mul_f32_e32 v200, v200, v252
	v_mul_f32_e32 v201, v201, v253
	s_nop 1
	v_mfma_f32_16x16x32_bf16 v[198:201], v[244:247], v[178:181], v[198:201]
	ds_read_b128 v[244:247], v225 offset:17920
	ds_read_b128 v[250:253], v226 offset:896
	s_waitcnt lgkmcnt(6)
	v_mul_f32_e32 v202, v202, v166
	v_mul_f32_e32 v203, v203, v167
	v_mul_f32_e32 v204, v204, v168
	v_mul_f32_e32 v205, v205, v169
	s_nop 1
	v_mfma_f32_16x16x32_bf16 v[202:205], v[162:165], v[178:181], v[202:205]
	ds_read_b128 v[162:165], v225 offset:19200
	ds_read_b128 v[166:169], v226 offset:960
	v_add_f32_e32 v150, v150, v151
	v_add_f32_e32 v152, v152, v153
	s_lshr_b32 s97, s97, 4
	v_add_u32_e32 v229, s97, v235
	s_and_saveexec_b64 s[30:31], s[12:13]
	ds_write_b32 v229, v150
	ds_write_b32 v229, v152 offset:256
	s_or_b64 exec, exec, s[30:31]
	s_waitcnt lgkmcnt(8)
	v_mul_f32_e32 v206, v206, v174
	v_mul_f32_e32 v207, v207, v175
	v_mul_f32_e32 v208, v208, v176
	v_mul_f32_e32 v209, v209, v177
	s_nop 1
	v_mfma_f32_16x16x32_bf16 v[206:209], v[170:173], v[178:181], v[206:209]
	s_waitcnt lgkmcnt(6)
	v_mul_f32_e32 v210, v210, v240
	v_mul_f32_e32 v211, v211, v241
	v_mul_f32_e32 v212, v212, v242
	v_mul_f32_e32 v213, v213, v243
	s_nop 1
	v_mfma_f32_16x16x32_bf16 v[210:213], v[236:239], v[178:181], v[210:213]
	s_waitcnt lgkmcnt(4)
	v_mul_f32_e32 v214, v214, v250
	v_mul_f32_e32 v215, v215, v251
	v_mul_f32_e32 v216, v216, v252
	v_mul_f32_e32 v217, v217, v253
	s_nop 1
	v_mfma_f32_16x16x32_bf16 v[214:217], v[244:247], v[178:181], v[214:217]
	s_waitcnt lgkmcnt(2)
	v_mul_f32_e32 v218, v218, v166
	v_mul_f32_e32 v219, v219, v167
	v_mul_f32_e32 v220, v220, v168
	v_mul_f32_e32 v221, v221, v169
	s_nop 1
	v_mfma_f32_16x16x32_bf16 v[218:221], v[162:165], v[178:181], v[218:221]
	s_branch .Lgn_skip
